# plus: opening s_setprio 1 of MMA segments dropped
# baseline (speedup 1.0000x reference)
.LBB0_120:
	ds_read_b128 v[128:131], v178
	ds_read_b128 v[132:135], v178 offset:1024
	ds_read_b128 v[154:157], v178 offset:2048
	ds_read_b128 v[158:161], v178 offset:3072
	ds_read_b128 v[162:165], v179
	ds_read_b128 v[166:169], v179 offset:1024
	ds_read_b128 v[182:185], v179 offset:2048
	ds_read_b128 v[186:189], v179 offset:3072
	s_add_u32 s67, s88, 0xfffc0080
	s_addc_u32 s68, s89, -1
	s_cmp_eq_u32 s66, 12
	s_cselect_b32 s93, s52, s68
	s_cselect_b32 s92, s53, s67
	s_cselect_b32 s91, s56, s59
	s_cselect_b32 s90, s57, s58
	v_lshl_add_u64 v[170:171], s[88:89], 0, v[144:145]
	s_add_i32 m0, s17, 0xc000
	ds_read_b128 v[190:193], v180
	ds_read_b128 v[194:197], v180 offset:1024
	ds_read_b128 v[198:201], v180 offset:2048
	ds_read_b128 v[202:205], v180 offset:3072
	ds_read_b128 v[206:209], v180 offset:4096
	ds_read_b128 v[210:213], v180 offset:5120
	ds_read_b128 v[214:217], v180 offset:6144
	ds_read_b128 v[218:221], v180 offset:7168
	global_load_lds_dwordx4 v[170:171], off
	s_add_i32 m0, s17, 0xe000
	v_lshl_add_u64 v[170:171], s[88:89], 0, v[148:149]
	global_load_lds_dwordx4 v[170:171], off
	s_cmp_eq_u32 s66, -2
	s_waitcnt vmcnt(8) lgkmcnt(0)
	s_barrier
	s_cbranch_scc1 .Lzv_0_0
	v_mfma_f32_16x16x32_bf16 v[124:127], v[128:131], v[190:193], v[124:127]
	v_mfma_f32_16x16x32_bf16 v[124:127], v[132:135], v[194:197], v[124:127]
	v_mfma_f32_16x16x32_bf16 v[116:119], v[154:157], v[190:193], v[116:119]
	v_mfma_f32_16x16x32_bf16 v[116:119], v[158:161], v[194:197], v[116:119]
	v_mfma_f32_16x16x32_bf16 v[108:111], v[128:131], v[198:201], v[108:111]
	v_mfma_f32_16x16x32_bf16 v[108:111], v[132:135], v[202:205], v[108:111]
	v_mfma_f32_16x16x32_bf16 v[100:103], v[154:157], v[198:201], v[100:103]
	v_mfma_f32_16x16x32_bf16 v[100:103], v[158:161], v[202:205], v[100:103]
	v_mfma_f32_16x16x32_bf16 v[92:95], v[128:131], v[206:209], v[92:95]
	v_mfma_f32_16x16x32_bf16 v[92:95], v[132:135], v[210:213], v[92:95]
	v_mfma_f32_16x16x32_bf16 v[84:87], v[154:157], v[206:209], v[84:87]
	v_mfma_f32_16x16x32_bf16 v[84:87], v[158:161], v[210:213], v[84:87]
	v_mfma_f32_16x16x32_bf16 v[76:79], v[128:131], v[214:217], v[76:79]
	v_mfma_f32_16x16x32_bf16 v[76:79], v[132:135], v[218:221], v[76:79]
	v_mfma_f32_16x16x32_bf16 v[68:71], v[154:157], v[214:217], v[68:71]
	v_mfma_f32_16x16x32_bf16 v[68:71], v[158:161], v[218:221], v[68:71]
	v_mfma_f32_16x16x32_bf16 v[120:123], v[162:165], v[190:193], v[120:123]
	v_mfma_f32_16x16x32_bf16 v[120:123], v[166:169], v[194:197], v[120:123]
	v_mfma_f32_16x16x32_bf16 v[112:115], v[182:185], v[190:193], v[112:115]
	v_mfma_f32_16x16x32_bf16 v[112:115], v[186:189], v[194:197], v[112:115]
	v_mfma_f32_16x16x32_bf16 v[104:107], v[162:165], v[198:201], v[104:107]
	v_mfma_f32_16x16x32_bf16 v[104:107], v[166:169], v[202:205], v[104:107]
	v_mfma_f32_16x16x32_bf16 v[96:99], v[182:185], v[198:201], v[96:99]
	v_mfma_f32_16x16x32_bf16 v[96:99], v[186:189], v[202:205], v[96:99]
	v_mfma_f32_16x16x32_bf16 v[88:91], v[162:165], v[206:209], v[88:91]
	v_mfma_f32_16x16x32_bf16 v[88:91], v[166:169], v[210:213], v[88:91]
	v_mfma_f32_16x16x32_bf16 v[80:83], v[182:185], v[206:209], v[80:83]
	v_mfma_f32_16x16x32_bf16 v[80:83], v[186:189], v[210:213], v[80:83]
	v_mfma_f32_16x16x32_bf16 v[72:75], v[162:165], v[214:217], v[72:75]
	v_mfma_f32_16x16x32_bf16 v[72:75], v[166:169], v[218:221], v[72:75]
	s_setprio 3
	s_barrier
	v_mfma_f32_16x16x32_bf16 v[64:67], v[182:185], v[214:217], v[64:67]
	v_mfma_f32_16x16x32_bf16 v[64:67], v[186:189], v[218:221], v[64:67]
	s_setprio 0
.Lzj_0_0:
	s_add_i32 s67, s25, s16
	v_lshl_add_u64 v[170:171], s[90:91], 0, v[140:141]
	s_mov_b32 m0, s67
	ds_read_b128 v[190:193], v180 offset:16384
	ds_read_b128 v[194:197], v180 offset:17408
	ds_read_b128 v[198:201], v180 offset:18432
	ds_read_b128 v[202:205], v180 offset:19456
	ds_read_b128 v[206:209], v180 offset:20480
	ds_read_b128 v[210:213], v180 offset:21504
	ds_read_b128 v[214:217], v180 offset:22528
	ds_read_b128 v[218:221], v180 offset:23552
	global_load_lds_dwordx4 v[170:171], off
	s_add_i32 m0, s67, 0x2000
	s_add_u32 s68, s90, 0x40000
	v_lshl_add_u64 v[222:223], s[90:91], 0, v[136:137]
	s_addc_u32 s69, s91, 0
	s_add_i32 s67, s26, s16
	global_load_lds_dwordx4 v[222:223], off
	v_lshl_add_u64 v[224:225], s[68:69], 0, v[140:141]
	s_mov_b32 m0, s67
	global_load_lds_dwordx4 v[224:225], off
	s_add_i32 m0, s67, 0x2000
	v_lshl_add_u64 v[224:225], s[68:69], 0, v[136:137]
	global_load_lds_dwordx4 v[224:225], off
	s_mov_b32 m0, s17
	v_lshl_add_u64 v[224:225], s[92:93], 0, v[142:143]
	global_load_lds_dwordx4 v[224:225], off
	s_mov_b32 m0, s18
	v_lshl_add_u64 v[226:227], s[92:93], 0, v[138:139]
	global_load_lds_dwordx4 v[226:227], off
	s_cmp_eq_u32 s66, -2
	s_waitcnt vmcnt(8) lgkmcnt(0)
	s_barrier
	s_cbranch_scc1 .Lzv_0_1
	v_mfma_f32_16x16x32_bf16 v[60:63], v[128:131], v[190:193], v[60:63]
	v_mfma_f32_16x16x32_bf16 v[60:63], v[132:135], v[194:197], v[60:63]
	v_mfma_f32_16x16x32_bf16 v[52:55], v[154:157], v[190:193], v[52:55]
	v_mfma_f32_16x16x32_bf16 v[52:55], v[158:161], v[194:197], v[52:55]
	v_mfma_f32_16x16x32_bf16 v[44:47], v[128:131], v[198:201], v[44:47]
	v_mfma_f32_16x16x32_bf16 v[44:47], v[132:135], v[202:205], v[44:47]
	v_mfma_f32_16x16x32_bf16 v[36:39], v[154:157], v[198:201], v[36:39]
	v_mfma_f32_16x16x32_bf16 v[36:39], v[158:161], v[202:205], v[36:39]
	v_mfma_f32_16x16x32_bf16 v[28:31], v[128:131], v[206:209], v[28:31]
	v_mfma_f32_16x16x32_bf16 v[28:31], v[132:135], v[210:213], v[28:31]
	v_mfma_f32_16x16x32_bf16 v[20:23], v[154:157], v[206:209], v[20:23]
	v_mfma_f32_16x16x32_bf16 v[20:23], v[158:161], v[210:213], v[20:23]
	v_mfma_f32_16x16x32_bf16 v[12:15], v[128:131], v[214:217], v[12:15]
	v_mfma_f32_16x16x32_bf16 v[12:15], v[132:135], v[218:221], v[12:15]
	v_mfma_f32_16x16x32_bf16 v[4:7], v[154:157], v[214:217], v[4:7]
	v_mfma_f32_16x16x32_bf16 v[4:7], v[158:161], v[218:221], v[4:7]
	v_mfma_f32_16x16x32_bf16 v[56:59], v[162:165], v[190:193], v[56:59]
	v_mfma_f32_16x16x32_bf16 v[56:59], v[166:169], v[194:197], v[56:59]
	v_mfma_f32_16x16x32_bf16 v[48:51], v[182:185], v[190:193], v[48:51]
	v_mfma_f32_16x16x32_bf16 v[48:51], v[186:189], v[194:197], v[48:51]
	v_mfma_f32_16x16x32_bf16 v[40:43], v[162:165], v[198:201], v[40:43]
	v_mfma_f32_16x16x32_bf16 v[40:43], v[166:169], v[202:205], v[40:43]
	v_mfma_f32_16x16x32_bf16 v[32:35], v[182:185], v[198:201], v[32:35]
	v_mfma_f32_16x16x32_bf16 v[32:35], v[186:189], v[202:205], v[32:35]
	v_mfma_f32_16x16x32_bf16 v[24:27], v[162:165], v[206:209], v[24:27]
	v_mfma_f32_16x16x32_bf16 v[24:27], v[166:169], v[210:213], v[24:27]
	v_mfma_f32_16x16x32_bf16 v[16:19], v[182:185], v[206:209], v[16:19]
	v_mfma_f32_16x16x32_bf16 v[16:19], v[186:189], v[210:213], v[16:19]
	v_mfma_f32_16x16x32_bf16 v[8:11], v[162:165], v[214:217], v[8:11]
	v_mfma_f32_16x16x32_bf16 v[8:11], v[166:169], v[218:221], v[8:11]
	s_setprio 3
	s_barrier
	v_mfma_f32_16x16x32_bf16 v[0:3], v[182:185], v[214:217], v[0:3]
	v_mfma_f32_16x16x32_bf16 v[0:3], v[186:189], v[218:221], v[0:3]
	s_setprio 0
.Lzj_0_1:
	s_add_i32 s67, 0, 0x18000
	s_add_i32 s73, 0, 0x1c000
	v_add_u32_e32 v158, s67, v175
	v_add_u32_e32 v186, s73, v175
	ds_read_b128 v[128:131], v158
	ds_read_b128 v[132:135], v158 offset:1024
	ds_read_b128 v[154:157], v158 offset:2048
	ds_read_b128 v[158:161], v158 offset:3072
	ds_read_b128 v[162:165], v186
	ds_read_b128 v[166:169], v186 offset:1024
	ds_read_b128 v[182:185], v186 offset:2048
	ds_read_b128 v[186:189], v186 offset:3072
	s_add_u32 s68, s92, 0x40000
	s_addc_u32 s69, s93, 0
	s_mov_b32 m0, s19
	v_lshl_add_u64 v[228:229], s[68:69], 0, v[142:143]
	ds_read_b128 v[190:193], v180 offset:32768
	ds_read_b128 v[194:197], v180 offset:33792
	ds_read_b128 v[198:201], v180 offset:34816
	ds_read_b128 v[202:205], v180 offset:35840
	ds_read_b128 v[206:209], v180 offset:36864
	ds_read_b128 v[210:213], v180 offset:37888
	ds_read_b128 v[214:217], v180 offset:38912
	ds_read_b128 v[218:221], v180 offset:39936
	global_load_lds_dwordx4 v[228:229], off
	s_mov_b32 m0, s20
	v_lshl_add_u64 v[228:229], s[68:69], 0, v[138:139]
	global_load_lds_dwordx4 v[228:229], off
	s_waitcnt vmcnt(8) lgkmcnt(0)
	s_barrier
	v_mfma_f32_16x16x32_bf16 v[124:127], v[128:131], v[190:193], v[124:127]
	v_mfma_f32_16x16x32_bf16 v[124:127], v[132:135], v[194:197], v[124:127]
	v_mfma_f32_16x16x32_bf16 v[116:119], v[154:157], v[190:193], v[116:119]
	v_mfma_f32_16x16x32_bf16 v[116:119], v[158:161], v[194:197], v[116:119]
	v_mfma_f32_16x16x32_bf16 v[108:111], v[128:131], v[198:201], v[108:111]
	v_mfma_f32_16x16x32_bf16 v[108:111], v[132:135], v[202:205], v[108:111]
	v_mfma_f32_16x16x32_bf16 v[100:103], v[154:157], v[198:201], v[100:103]
	v_mfma_f32_16x16x32_bf16 v[100:103], v[158:161], v[202:205], v[100:103]
	v_mfma_f32_16x16x32_bf16 v[92:95], v[128:131], v[206:209], v[92:95]
	v_mfma_f32_16x16x32_bf16 v[92:95], v[132:135], v[210:213], v[92:95]
	v_mfma_f32_16x16x32_bf16 v[84:87], v[154:157], v[206:209], v[84:87]
	v_mfma_f32_16x16x32_bf16 v[84:87], v[158:161], v[210:213], v[84:87]
	v_mfma_f32_16x16x32_bf16 v[76:79], v[128:131], v[214:217], v[76:79]
	v_mfma_f32_16x16x32_bf16 v[76:79], v[132:135], v[218:221], v[76:79]
	v_mfma_f32_16x16x32_bf16 v[68:71], v[154:157], v[214:217], v[68:71]
	v_mfma_f32_16x16x32_bf16 v[68:71], v[158:161], v[218:221], v[68:71]
	v_mfma_f32_16x16x32_bf16 v[120:123], v[162:165], v[190:193], v[120:123]
	v_mfma_f32_16x16x32_bf16 v[120:123], v[166:169], v[194:197], v[120:123]
	v_mfma_f32_16x16x32_bf16 v[112:115], v[182:185], v[190:193], v[112:115]
	v_mfma_f32_16x16x32_bf16 v[112:115], v[186:189], v[194:197], v[112:115]
	v_mfma_f32_16x16x32_bf16 v[104:107], v[162:165], v[198:201], v[104:107]
	v_mfma_f32_16x16x32_bf16 v[104:107], v[166:169], v[202:205], v[104:107]
	v_mfma_f32_16x16x32_bf16 v[96:99], v[182:185], v[198:201], v[96:99]
	v_mfma_f32_16x16x32_bf16 v[96:99], v[186:189], v[202:205], v[96:99]
	v_mfma_f32_16x16x32_bf16 v[88:91], v[162:165], v[206:209], v[88:91]
	v_mfma_f32_16x16x32_bf16 v[88:91], v[166:169], v[210:213], v[88:91]
	v_mfma_f32_16x16x32_bf16 v[80:83], v[182:185], v[206:209], v[80:83]
	v_mfma_f32_16x16x32_bf16 v[80:83], v[186:189], v[210:213], v[80:83]
	v_mfma_f32_16x16x32_bf16 v[72:75], v[162:165], v[214:217], v[72:75]
	v_mfma_f32_16x16x32_bf16 v[72:75], v[166:169], v[218:221], v[72:75]
	s_setprio 3
	s_barrier
	v_mfma_f32_16x16x32_bf16 v[64:67], v[182:185], v[214:217], v[64:67]
	v_mfma_f32_16x16x32_bf16 v[64:67], v[186:189], v[218:221], v[64:67]
	s_setprio 0
	s_add_i32 s67, s67, s16
	v_lshl_add_u64 v[170:171], v[170:171], 0, s[74:75]
	s_mov_b32 m0, s67
	ds_read_b128 v[190:193], v180 offset:49152
	ds_read_b128 v[194:197], v180 offset:50176
	ds_read_b128 v[198:201], v180 offset:51200
	ds_read_b128 v[202:205], v180 offset:52224
	ds_read_b128 v[206:209], v180 offset:53248
	ds_read_b128 v[210:213], v180 offset:54272
	ds_read_b128 v[214:217], v180 offset:55296
	ds_read_b128 v[218:221], v180 offset:56320
	global_load_lds_dwordx4 v[170:171], off
	s_add_i32 m0, s67, 0x2000
	s_add_u32 s68, s90, 0x40080
	v_lshl_add_u64 v[170:171], v[222:223], 0, s[74:75]
	s_addc_u32 s69, s91, 0
	s_add_i32 s67, s73, s16
	global_load_lds_dwordx4 v[170:171], off
	s_mov_b32 m0, s67
	v_lshl_add_u64 v[170:171], s[68:69], 0, v[140:141]
	global_load_lds_dwordx4 v[170:171], off
	s_add_i32 m0, s67, 0x2000
	v_lshl_add_u64 v[170:171], s[68:69], 0, v[136:137]
	global_load_lds_dwordx4 v[170:171], off
	s_mov_b32 m0, s23
	v_lshl_add_u64 v[170:171], v[224:225], 0, s[74:75]
	global_load_lds_dwordx4 v[170:171], off
	s_mov_b32 m0, s24
	v_lshl_add_u64 v[170:171], v[226:227], 0, s[74:75]
	global_load_lds_dwordx4 v[170:171], off
	s_waitcnt vmcnt(8) lgkmcnt(0)
	s_barrier
	v_mfma_f32_16x16x32_bf16 v[60:63], v[128:131], v[190:193], v[60:63]
	v_mfma_f32_16x16x32_bf16 v[60:63], v[132:135], v[194:197], v[60:63]
	v_mfma_f32_16x16x32_bf16 v[52:55], v[154:157], v[190:193], v[52:55]
	v_mfma_f32_16x16x32_bf16 v[52:55], v[158:161], v[194:197], v[52:55]
	v_mfma_f32_16x16x32_bf16 v[44:47], v[128:131], v[198:201], v[44:47]
	v_mfma_f32_16x16x32_bf16 v[44:47], v[132:135], v[202:205], v[44:47]
	v_mfma_f32_16x16x32_bf16 v[36:39], v[154:157], v[198:201], v[36:39]
	v_mfma_f32_16x16x32_bf16 v[36:39], v[158:161], v[202:205], v[36:39]
	v_mfma_f32_16x16x32_bf16 v[28:31], v[128:131], v[206:209], v[28:31]
	v_mfma_f32_16x16x32_bf16 v[28:31], v[132:135], v[210:213], v[28:31]
	v_mfma_f32_16x16x32_bf16 v[20:23], v[154:157], v[206:209], v[20:23]
	v_mfma_f32_16x16x32_bf16 v[20:23], v[158:161], v[210:213], v[20:23]
	v_mfma_f32_16x16x32_bf16 v[12:15], v[128:131], v[214:217], v[12:15]
	v_mfma_f32_16x16x32_bf16 v[12:15], v[132:135], v[218:221], v[12:15]
	v_mfma_f32_16x16x32_bf16 v[4:7], v[154:157], v[214:217], v[4:7]
	v_mfma_f32_16x16x32_bf16 v[4:7], v[158:161], v[218:221], v[4:7]
	v_mfma_f32_16x16x32_bf16 v[56:59], v[162:165], v[190:193], v[56:59]
	v_mfma_f32_16x16x32_bf16 v[56:59], v[166:169], v[194:197], v[56:59]
	v_mfma_f32_16x16x32_bf16 v[48:51], v[182:185], v[190:193], v[48:51]
	v_mfma_f32_16x16x32_bf16 v[48:51], v[186:189], v[194:197], v[48:51]
	v_mfma_f32_16x16x32_bf16 v[40:43], v[162:165], v[198:201], v[40:43]
	v_mfma_f32_16x16x32_bf16 v[40:43], v[166:169], v[202:205], v[40:43]
	v_mfma_f32_16x16x32_bf16 v[32:35], v[182:185], v[198:201], v[32:35]
	v_mfma_f32_16x16x32_bf16 v[32:35], v[186:189], v[202:205], v[32:35]
	v_mfma_f32_16x16x32_bf16 v[24:27], v[162:165], v[206:209], v[24:27]
	v_mfma_f32_16x16x32_bf16 v[24:27], v[166:169], v[210:213], v[24:27]
	v_mfma_f32_16x16x32_bf16 v[16:19], v[182:185], v[206:209], v[16:19]
	v_mfma_f32_16x16x32_bf16 v[16:19], v[186:189], v[210:213], v[16:19]
	v_mfma_f32_16x16x32_bf16 v[8:11], v[162:165], v[214:217], v[8:11]
	v_mfma_f32_16x16x32_bf16 v[8:11], v[166:169], v[218:221], v[8:11]
	s_setprio 3
	s_barrier
	v_mfma_f32_16x16x32_bf16 v[0:3], v[182:185], v[214:217], v[0:3]
	v_mfma_f32_16x16x32_bf16 v[0:3], v[186:189], v[218:221], v[0:3]
	s_setprio 0
	s_add_i32 s66, s66, 2
	s_add_u32 s88, s88, 0x100
	s_addc_u32 s89, s89, 0
	s_add_u32 s58, s58, 0x100
	s_addc_u32 s59, s59, 0
	s_cmp_gt_u32 s66, 13
	s_cbranch_scc0 .LBB0_120
	s_branch .Lzskip_0

.LBB0_272:
	ds_read_b128 v[120:123], v245
	ds_read_b128 v[124:127], v245 offset:1024
	ds_read_b128 v[128:131], v245 offset:2048
	ds_read_b128 v[132:135], v245 offset:3072
	ds_read_b128 v[144:147], v246
	ds_read_b128 v[148:151], v246 offset:1024
	ds_read_b128 v[152:155], v246 offset:2048
	ds_read_b128 v[156:159], v246 offset:3072
	s_add_u32 s59, s86, 0xfff50080
	s_addc_u32 s66, s87, -1
	s_cmp_eq_u32 s58, 40
	s_cselect_b32 s91, s11, s66
	s_cselect_b32 s90, s10, s59
	s_cselect_b32 s89, s85, s57
	s_cselect_b32 s88, s84, s56
	v_lshl_add_u64 v[204:205], s[86:87], 0, v[200:201]
	s_add_i32 m0, s16, 0xc000
	ds_read_b128 v[160:163], v247
	ds_read_b128 v[164:167], v247 offset:1024
	ds_read_b128 v[168:171], v247 offset:2048
	ds_read_b128 v[172:175], v247 offset:3072
	ds_read_b128 v[176:179], v247 offset:4096
	ds_read_b128 v[180:183], v247 offset:5120
	ds_read_b128 v[184:187], v247 offset:6144
	ds_read_b128 v[188:191], v247 offset:7168
	global_load_lds_dwordx4 v[204:205], off
	s_add_i32 m0, s16, 0xe000
	v_lshl_add_u64 v[204:205], s[86:87], 0, v[202:203]
	global_load_lds_dwordx4 v[204:205], off
	s_cmp_eq_u32 s58, -2
	s_waitcnt vmcnt(8) lgkmcnt(0)
	s_barrier
	s_cbranch_scc1 .Lzv_1_0
	v_mfma_f32_16x16x32_bf16 v[140:143], v[120:123], v[160:163], v[140:143]
	v_mfma_f32_16x16x32_bf16 v[140:143], v[124:127], v[164:167], v[140:143]
	v_mfma_f32_16x16x32_bf16 v[136:139], v[128:131], v[160:163], v[136:139]
	v_mfma_f32_16x16x32_bf16 v[136:139], v[132:135], v[164:167], v[136:139]
	v_mfma_f32_16x16x32_bf16 v[108:111], v[120:123], v[168:171], v[108:111]
	v_mfma_f32_16x16x32_bf16 v[108:111], v[124:127], v[172:175], v[108:111]
	v_mfma_f32_16x16x32_bf16 v[104:107], v[128:131], v[168:171], v[104:107]
	v_mfma_f32_16x16x32_bf16 v[104:107], v[132:135], v[172:175], v[104:107]
	v_mfma_f32_16x16x32_bf16 v[92:95], v[120:123], v[176:179], v[92:95]
	v_mfma_f32_16x16x32_bf16 v[92:95], v[124:127], v[180:183], v[92:95]
	v_mfma_f32_16x16x32_bf16 v[88:91], v[128:131], v[176:179], v[88:91]
	v_mfma_f32_16x16x32_bf16 v[88:91], v[132:135], v[180:183], v[88:91]
	v_mfma_f32_16x16x32_bf16 v[76:79], v[120:123], v[184:187], v[76:79]
	v_mfma_f32_16x16x32_bf16 v[76:79], v[124:127], v[188:191], v[76:79]
	v_mfma_f32_16x16x32_bf16 v[72:75], v[128:131], v[184:187], v[72:75]
	v_mfma_f32_16x16x32_bf16 v[72:75], v[132:135], v[188:191], v[72:75]
	v_mfma_f32_16x16x32_bf16 v[116:119], v[144:147], v[160:163], v[116:119]
	v_mfma_f32_16x16x32_bf16 v[116:119], v[148:151], v[164:167], v[116:119]
	v_mfma_f32_16x16x32_bf16 v[112:115], v[152:155], v[160:163], v[112:115]
	v_mfma_f32_16x16x32_bf16 v[112:115], v[156:159], v[164:167], v[112:115]
	v_mfma_f32_16x16x32_bf16 v[100:103], v[144:147], v[168:171], v[100:103]
	v_mfma_f32_16x16x32_bf16 v[100:103], v[148:151], v[172:175], v[100:103]
	v_mfma_f32_16x16x32_bf16 v[96:99], v[152:155], v[168:171], v[96:99]
	v_mfma_f32_16x16x32_bf16 v[96:99], v[156:159], v[172:175], v[96:99]
	v_mfma_f32_16x16x32_bf16 v[84:87], v[144:147], v[176:179], v[84:87]
	v_mfma_f32_16x16x32_bf16 v[84:87], v[148:151], v[180:183], v[84:87]
	v_mfma_f32_16x16x32_bf16 v[80:83], v[152:155], v[176:179], v[80:83]
	v_mfma_f32_16x16x32_bf16 v[80:83], v[156:159], v[180:183], v[80:83]
	v_mfma_f32_16x16x32_bf16 v[68:71], v[144:147], v[184:187], v[68:71]
	v_mfma_f32_16x16x32_bf16 v[68:71], v[148:151], v[188:191], v[68:71]
	s_setprio 3
	s_barrier
	v_mfma_f32_16x16x32_bf16 v[64:67], v[152:155], v[184:187], v[64:67]
	v_mfma_f32_16x16x32_bf16 v[64:67], v[156:159], v[188:191], v[64:67]
	s_setprio 0
.Lzj_1_0:
	s_add_i32 s59, s26, s15
	v_lshl_add_u64 v[204:205], s[88:89], 0, v[194:195]
	s_mov_b32 m0, s59
	ds_read_b128 v[160:163], v247 offset:16384
	ds_read_b128 v[164:167], v247 offset:17408
	ds_read_b128 v[168:171], v247 offset:18432
	ds_read_b128 v[172:175], v247 offset:19456
	ds_read_b128 v[176:179], v247 offset:20480
	ds_read_b128 v[180:183], v247 offset:21504
	ds_read_b128 v[184:187], v247 offset:22528
	ds_read_b128 v[188:191], v247 offset:23552
	global_load_lds_dwordx4 v[204:205], off
	s_add_i32 m0, s59, 0x2000
	s_add_u32 s66, s88, 0xb0000
	v_lshl_add_u64 v[206:207], s[88:89], 0, v[198:199]
	s_addc_u32 s67, s89, 0
	s_add_i32 s59, s27, s15
	global_load_lds_dwordx4 v[206:207], off
	v_lshl_add_u64 v[208:209], s[66:67], 0, v[194:195]
	s_mov_b32 m0, s59
	global_load_lds_dwordx4 v[208:209], off
	s_add_i32 m0, s59, 0x2000
	v_lshl_add_u64 v[208:209], s[66:67], 0, v[198:199]
	global_load_lds_dwordx4 v[208:209], off
	s_mov_b32 m0, s16
	v_lshl_add_u64 v[208:209], s[90:91], 0, v[192:193]
	global_load_lds_dwordx4 v[208:209], off
	s_mov_b32 m0, s17
	v_lshl_add_u64 v[210:211], s[90:91], 0, v[196:197]
	global_load_lds_dwordx4 v[210:211], off
	s_cmp_eq_u32 s58, -2
	s_waitcnt vmcnt(8) lgkmcnt(0)
	s_barrier
	s_cbranch_scc1 .Lzv_1_1
	v_mfma_f32_16x16x32_bf16 v[60:63], v[120:123], v[160:163], v[60:63]
	v_mfma_f32_16x16x32_bf16 v[60:63], v[124:127], v[164:167], v[60:63]
	v_mfma_f32_16x16x32_bf16 v[56:59], v[128:131], v[160:163], v[56:59]
	v_mfma_f32_16x16x32_bf16 v[56:59], v[132:135], v[164:167], v[56:59]
	v_mfma_f32_16x16x32_bf16 v[44:47], v[120:123], v[168:171], v[44:47]
	v_mfma_f32_16x16x32_bf16 v[44:47], v[124:127], v[172:175], v[44:47]
	v_mfma_f32_16x16x32_bf16 v[40:43], v[128:131], v[168:171], v[40:43]
	v_mfma_f32_16x16x32_bf16 v[40:43], v[132:135], v[172:175], v[40:43]
	v_mfma_f32_16x16x32_bf16 v[28:31], v[120:123], v[176:179], v[28:31]
	v_mfma_f32_16x16x32_bf16 v[28:31], v[124:127], v[180:183], v[28:31]
	v_mfma_f32_16x16x32_bf16 v[24:27], v[128:131], v[176:179], v[24:27]
	v_mfma_f32_16x16x32_bf16 v[24:27], v[132:135], v[180:183], v[24:27]
	v_mfma_f32_16x16x32_bf16 v[12:15], v[120:123], v[184:187], v[12:15]
	v_mfma_f32_16x16x32_bf16 v[12:15], v[124:127], v[188:191], v[12:15]
	v_mfma_f32_16x16x32_bf16 v[8:11], v[128:131], v[184:187], v[8:11]
	v_mfma_f32_16x16x32_bf16 v[8:11], v[132:135], v[188:191], v[8:11]
	v_mfma_f32_16x16x32_bf16 v[52:55], v[144:147], v[160:163], v[52:55]
	v_mfma_f32_16x16x32_bf16 v[52:55], v[148:151], v[164:167], v[52:55]
	v_mfma_f32_16x16x32_bf16 v[48:51], v[152:155], v[160:163], v[48:51]
	v_mfma_f32_16x16x32_bf16 v[48:51], v[156:159], v[164:167], v[48:51]
	v_mfma_f32_16x16x32_bf16 v[36:39], v[144:147], v[168:171], v[36:39]
	v_mfma_f32_16x16x32_bf16 v[36:39], v[148:151], v[172:175], v[36:39]
	v_mfma_f32_16x16x32_bf16 v[32:35], v[152:155], v[168:171], v[32:35]
	v_mfma_f32_16x16x32_bf16 v[32:35], v[156:159], v[172:175], v[32:35]
	v_mfma_f32_16x16x32_bf16 v[20:23], v[144:147], v[176:179], v[20:23]
	v_mfma_f32_16x16x32_bf16 v[20:23], v[148:151], v[180:183], v[20:23]
	v_mfma_f32_16x16x32_bf16 v[16:19], v[152:155], v[176:179], v[16:19]
	v_mfma_f32_16x16x32_bf16 v[16:19], v[156:159], v[180:183], v[16:19]
	v_mfma_f32_16x16x32_bf16 v[4:7], v[144:147], v[184:187], v[4:7]
	v_mfma_f32_16x16x32_bf16 v[4:7], v[148:151], v[188:191], v[4:7]
	s_setprio 3
	s_barrier
	v_mfma_f32_16x16x32_bf16 v[0:3], v[152:155], v[184:187], v[0:3]
	v_mfma_f32_16x16x32_bf16 v[0:3], v[156:159], v[188:191], v[0:3]
	s_setprio 0
.Lzj_1_1:
	s_add_i32 s59, 0, 0x18000
	s_add_i32 s68, 0, 0x1c000
	v_add_u32_e32 v132, s59, v243
	v_add_u32_e32 v156, s68, v243
	ds_read_b128 v[120:123], v132
	ds_read_b128 v[124:127], v132 offset:1024
	ds_read_b128 v[128:131], v132 offset:2048
	ds_read_b128 v[132:135], v132 offset:3072
	ds_read_b128 v[144:147], v156
	ds_read_b128 v[148:151], v156 offset:1024
	ds_read_b128 v[152:155], v156 offset:2048
	ds_read_b128 v[156:159], v156 offset:3072
	s_add_u32 s66, s90, 0xb0000
	s_addc_u32 s67, s91, 0
	s_mov_b32 m0, s18
	v_lshl_add_u64 v[212:213], s[66:67], 0, v[192:193]
	ds_read_b128 v[160:163], v247 offset:32768
	ds_read_b128 v[164:167], v247 offset:33792
	ds_read_b128 v[168:171], v247 offset:34816
	ds_read_b128 v[172:175], v247 offset:35840
	ds_read_b128 v[176:179], v247 offset:36864
	ds_read_b128 v[180:183], v247 offset:37888
	ds_read_b128 v[184:187], v247 offset:38912
	ds_read_b128 v[188:191], v247 offset:39936
	global_load_lds_dwordx4 v[212:213], off
	s_mov_b32 m0, s19
	v_lshl_add_u64 v[212:213], s[66:67], 0, v[196:197]
	global_load_lds_dwordx4 v[212:213], off
	s_waitcnt vmcnt(8) lgkmcnt(0)
	s_barrier
	v_mfma_f32_16x16x32_bf16 v[140:143], v[120:123], v[160:163], v[140:143]
	v_mfma_f32_16x16x32_bf16 v[140:143], v[124:127], v[164:167], v[140:143]
	v_mfma_f32_16x16x32_bf16 v[136:139], v[128:131], v[160:163], v[136:139]
	v_mfma_f32_16x16x32_bf16 v[136:139], v[132:135], v[164:167], v[136:139]
	v_mfma_f32_16x16x32_bf16 v[108:111], v[120:123], v[168:171], v[108:111]
	v_mfma_f32_16x16x32_bf16 v[108:111], v[124:127], v[172:175], v[108:111]
	v_mfma_f32_16x16x32_bf16 v[104:107], v[128:131], v[168:171], v[104:107]
	v_mfma_f32_16x16x32_bf16 v[104:107], v[132:135], v[172:175], v[104:107]
	v_mfma_f32_16x16x32_bf16 v[92:95], v[120:123], v[176:179], v[92:95]
	v_mfma_f32_16x16x32_bf16 v[92:95], v[124:127], v[180:183], v[92:95]
	v_mfma_f32_16x16x32_bf16 v[88:91], v[128:131], v[176:179], v[88:91]
	v_mfma_f32_16x16x32_bf16 v[88:91], v[132:135], v[180:183], v[88:91]
	v_mfma_f32_16x16x32_bf16 v[76:79], v[120:123], v[184:187], v[76:79]
	v_mfma_f32_16x16x32_bf16 v[76:79], v[124:127], v[188:191], v[76:79]
	v_mfma_f32_16x16x32_bf16 v[72:75], v[128:131], v[184:187], v[72:75]
	v_mfma_f32_16x16x32_bf16 v[72:75], v[132:135], v[188:191], v[72:75]
	v_mfma_f32_16x16x32_bf16 v[116:119], v[144:147], v[160:163], v[116:119]
	v_mfma_f32_16x16x32_bf16 v[116:119], v[148:151], v[164:167], v[116:119]
	v_mfma_f32_16x16x32_bf16 v[112:115], v[152:155], v[160:163], v[112:115]
	v_mfma_f32_16x16x32_bf16 v[112:115], v[156:159], v[164:167], v[112:115]
	v_mfma_f32_16x16x32_bf16 v[100:103], v[144:147], v[168:171], v[100:103]
	v_mfma_f32_16x16x32_bf16 v[100:103], v[148:151], v[172:175], v[100:103]
	v_mfma_f32_16x16x32_bf16 v[96:99], v[152:155], v[168:171], v[96:99]
	v_mfma_f32_16x16x32_bf16 v[96:99], v[156:159], v[172:175], v[96:99]
	v_mfma_f32_16x16x32_bf16 v[84:87], v[144:147], v[176:179], v[84:87]
	v_mfma_f32_16x16x32_bf16 v[84:87], v[148:151], v[180:183], v[84:87]
	v_mfma_f32_16x16x32_bf16 v[80:83], v[152:155], v[176:179], v[80:83]
	v_mfma_f32_16x16x32_bf16 v[80:83], v[156:159], v[180:183], v[80:83]
	v_mfma_f32_16x16x32_bf16 v[68:71], v[144:147], v[184:187], v[68:71]
	v_mfma_f32_16x16x32_bf16 v[68:71], v[148:151], v[188:191], v[68:71]
	s_setprio 3
	s_barrier
	v_mfma_f32_16x16x32_bf16 v[64:67], v[152:155], v[184:187], v[64:67]
	v_mfma_f32_16x16x32_bf16 v[64:67], v[156:159], v[188:191], v[64:67]
	s_setprio 0
	s_add_i32 s59, s59, s15
	v_lshl_add_u64 v[204:205], v[204:205], 0, s[80:81]
	s_mov_b32 m0, s59
	ds_read_b128 v[160:163], v247 offset:49152
	ds_read_b128 v[164:167], v247 offset:50176
	ds_read_b128 v[168:171], v247 offset:51200
	ds_read_b128 v[172:175], v247 offset:52224
	ds_read_b128 v[176:179], v247 offset:53248
	ds_read_b128 v[180:183], v247 offset:54272
	ds_read_b128 v[184:187], v247 offset:55296
	ds_read_b128 v[188:191], v247 offset:56320
	global_load_lds_dwordx4 v[204:205], off
	s_add_i32 m0, s59, 0x2000
	s_add_u32 s66, s88, 0xb0080
	v_lshl_add_u64 v[204:205], v[206:207], 0, s[80:81]
	s_addc_u32 s67, s89, 0
	s_add_i32 s59, s68, s15
	global_load_lds_dwordx4 v[204:205], off
	s_mov_b32 m0, s59
	v_lshl_add_u64 v[204:205], s[66:67], 0, v[194:195]
	global_load_lds_dwordx4 v[204:205], off
	s_add_i32 m0, s59, 0x2000
	v_lshl_add_u64 v[204:205], s[66:67], 0, v[198:199]
	global_load_lds_dwordx4 v[204:205], off
	s_mov_b32 m0, s21
	v_lshl_add_u64 v[204:205], v[208:209], 0, s[80:81]
	global_load_lds_dwordx4 v[204:205], off
	s_mov_b32 m0, s22
	v_lshl_add_u64 v[204:205], v[210:211], 0, s[80:81]
	global_load_lds_dwordx4 v[204:205], off
	s_waitcnt vmcnt(8) lgkmcnt(0)
	s_barrier
	v_mfma_f32_16x16x32_bf16 v[60:63], v[120:123], v[160:163], v[60:63]
	v_mfma_f32_16x16x32_bf16 v[60:63], v[124:127], v[164:167], v[60:63]
	v_mfma_f32_16x16x32_bf16 v[56:59], v[128:131], v[160:163], v[56:59]
	v_mfma_f32_16x16x32_bf16 v[56:59], v[132:135], v[164:167], v[56:59]
	v_mfma_f32_16x16x32_bf16 v[44:47], v[120:123], v[168:171], v[44:47]
	v_mfma_f32_16x16x32_bf16 v[44:47], v[124:127], v[172:175], v[44:47]
	v_mfma_f32_16x16x32_bf16 v[40:43], v[128:131], v[168:171], v[40:43]
	v_mfma_f32_16x16x32_bf16 v[40:43], v[132:135], v[172:175], v[40:43]
	v_mfma_f32_16x16x32_bf16 v[28:31], v[120:123], v[176:179], v[28:31]
	v_mfma_f32_16x16x32_bf16 v[28:31], v[124:127], v[180:183], v[28:31]
	v_mfma_f32_16x16x32_bf16 v[24:27], v[128:131], v[176:179], v[24:27]
	v_mfma_f32_16x16x32_bf16 v[24:27], v[132:135], v[180:183], v[24:27]
	v_mfma_f32_16x16x32_bf16 v[12:15], v[120:123], v[184:187], v[12:15]
	v_mfma_f32_16x16x32_bf16 v[12:15], v[124:127], v[188:191], v[12:15]
	v_mfma_f32_16x16x32_bf16 v[8:11], v[128:131], v[184:187], v[8:11]
	v_mfma_f32_16x16x32_bf16 v[8:11], v[132:135], v[188:191], v[8:11]
	v_mfma_f32_16x16x32_bf16 v[52:55], v[144:147], v[160:163], v[52:55]
	v_mfma_f32_16x16x32_bf16 v[52:55], v[148:151], v[164:167], v[52:55]
	v_mfma_f32_16x16x32_bf16 v[48:51], v[152:155], v[160:163], v[48:51]
	v_mfma_f32_16x16x32_bf16 v[48:51], v[156:159], v[164:167], v[48:51]
	v_mfma_f32_16x16x32_bf16 v[36:39], v[144:147], v[168:171], v[36:39]
	v_mfma_f32_16x16x32_bf16 v[36:39], v[148:151], v[172:175], v[36:39]
	v_mfma_f32_16x16x32_bf16 v[32:35], v[152:155], v[168:171], v[32:35]
	v_mfma_f32_16x16x32_bf16 v[32:35], v[156:159], v[172:175], v[32:35]
	v_mfma_f32_16x16x32_bf16 v[20:23], v[144:147], v[176:179], v[20:23]
	v_mfma_f32_16x16x32_bf16 v[20:23], v[148:151], v[180:183], v[20:23]
	v_mfma_f32_16x16x32_bf16 v[16:19], v[152:155], v[176:179], v[16:19]
	v_mfma_f32_16x16x32_bf16 v[16:19], v[156:159], v[180:183], v[16:19]
	v_mfma_f32_16x16x32_bf16 v[4:7], v[144:147], v[184:187], v[4:7]
	v_mfma_f32_16x16x32_bf16 v[4:7], v[148:151], v[188:191], v[4:7]
	s_setprio 3
	s_barrier
	v_mfma_f32_16x16x32_bf16 v[0:3], v[152:155], v[184:187], v[0:3]
	v_mfma_f32_16x16x32_bf16 v[0:3], v[156:159], v[188:191], v[0:3]
	s_setprio 0
	s_add_i32 s58, s58, 2
	s_add_u32 s86, s86, 0x100
	s_addc_u32 s87, s87, 0
	s_add_u32 s56, s56, 0x100
	s_addc_u32 s57, s57, 0
	s_cmp_gt_u32 s58, 41
	s_cbranch_scc0 .LBB0_272
	s_branch .Lzskip_1

.LBB0_429:
	ds_read_b128 v[128:131], v203
	ds_read_b128 v[132:135], v203 offset:1024
	ds_read_b128 v[136:139], v203 offset:2048
	ds_read_b128 v[164:167], v203 offset:3072
	ds_read_b128 v[168:171], v204
	ds_read_b128 v[172:175], v204 offset:1024
	ds_read_b128 v[176:179], v204 offset:2048
	ds_read_b128 v[180:183], v204 offset:3072
	s_add_u32 s6, s88, 0xfffc0080
	s_addc_u32 s7, s89, -1
	s_cmp_eq_u32 s21, 12
	s_cselect_b32 vcc_hi, s15, s7
	s_cselect_b32 vcc_lo, s16, s6
	s_cselect_b32 s7, s17, s20
	s_cselect_b32 s6, s18, s19
	v_lshl_add_u64 v[196:197], s[88:89], 0, v[156:157]
	s_add_i32 m0, s58, 0xc000
	ds_read_b128 v[184:187], v205
	ds_read_b128 v[188:191], v205 offset:1024
	ds_read_b128 v[192:195], v205 offset:2048
	ds_read_b128 v[212:215], v205 offset:3072
	ds_read_b128 v[216:219], v205 offset:4096
	ds_read_b128 v[220:223], v205 offset:5120
	ds_read_b128 v[224:227], v205 offset:6144
	ds_read_b128 v[228:231], v205 offset:7168
	global_load_lds_dwordx4 v[196:197], off
	s_add_i32 m0, s58, 0xe000
	v_lshl_add_u64 v[196:197], s[88:89], 0, v[158:159]
	global_load_lds_dwordx4 v[196:197], off
	s_cmp_eq_u32 s21, -2
	s_waitcnt vmcnt(8) lgkmcnt(0)
	s_barrier
	s_cbranch_scc1 .Lzv_2_0
	v_mfma_f32_16x16x32_bf16 v[124:127], v[128:131], v[184:187], v[124:127]
	v_mfma_f32_16x16x32_bf16 v[124:127], v[132:135], v[188:191], v[124:127]
	v_mfma_f32_16x16x32_bf16 v[116:119], v[136:139], v[184:187], v[116:119]
	v_mfma_f32_16x16x32_bf16 v[116:119], v[164:167], v[188:191], v[116:119]
	v_mfma_f32_16x16x32_bf16 v[108:111], v[128:131], v[192:195], v[108:111]
	v_mfma_f32_16x16x32_bf16 v[108:111], v[132:135], v[212:215], v[108:111]
	v_mfma_f32_16x16x32_bf16 v[100:103], v[136:139], v[192:195], v[100:103]
	v_mfma_f32_16x16x32_bf16 v[100:103], v[164:167], v[212:215], v[100:103]
	v_mfma_f32_16x16x32_bf16 v[92:95], v[128:131], v[216:219], v[92:95]
	v_mfma_f32_16x16x32_bf16 v[92:95], v[132:135], v[220:223], v[92:95]
	v_mfma_f32_16x16x32_bf16 v[84:87], v[136:139], v[216:219], v[84:87]
	v_mfma_f32_16x16x32_bf16 v[84:87], v[164:167], v[220:223], v[84:87]
	v_mfma_f32_16x16x32_bf16 v[76:79], v[128:131], v[224:227], v[76:79]
	v_mfma_f32_16x16x32_bf16 v[76:79], v[132:135], v[228:231], v[76:79]
	v_mfma_f32_16x16x32_bf16 v[68:71], v[136:139], v[224:227], v[68:71]
	v_mfma_f32_16x16x32_bf16 v[68:71], v[164:167], v[228:231], v[68:71]
	v_mfma_f32_16x16x32_bf16 v[120:123], v[168:171], v[184:187], v[120:123]
	v_mfma_f32_16x16x32_bf16 v[120:123], v[172:175], v[188:191], v[120:123]
	v_mfma_f32_16x16x32_bf16 v[112:115], v[176:179], v[184:187], v[112:115]
	v_mfma_f32_16x16x32_bf16 v[112:115], v[180:183], v[188:191], v[112:115]
	v_mfma_f32_16x16x32_bf16 v[104:107], v[168:171], v[192:195], v[104:107]
	v_mfma_f32_16x16x32_bf16 v[104:107], v[172:175], v[212:215], v[104:107]
	v_mfma_f32_16x16x32_bf16 v[96:99], v[176:179], v[192:195], v[96:99]
	v_mfma_f32_16x16x32_bf16 v[96:99], v[180:183], v[212:215], v[96:99]
	v_mfma_f32_16x16x32_bf16 v[88:91], v[168:171], v[216:219], v[88:91]
	v_mfma_f32_16x16x32_bf16 v[88:91], v[172:175], v[220:223], v[88:91]
	v_mfma_f32_16x16x32_bf16 v[80:83], v[176:179], v[216:219], v[80:83]
	v_mfma_f32_16x16x32_bf16 v[80:83], v[180:183], v[220:223], v[80:83]
	v_mfma_f32_16x16x32_bf16 v[72:75], v[168:171], v[224:227], v[72:75]
	v_mfma_f32_16x16x32_bf16 v[72:75], v[172:175], v[228:231], v[72:75]
	s_setprio 3
	s_barrier
	v_mfma_f32_16x16x32_bf16 v[64:67], v[176:179], v[224:227], v[64:67]
	v_mfma_f32_16x16x32_bf16 v[64:67], v[180:183], v[228:231], v[64:67]
	s_setprio 0
.Lzj_2_0:
	s_add_i32 s22, s76, s57
	v_lshl_add_u64 v[196:197], s[6:7], 0, v[142:143]
	s_mov_b32 m0, s22
	ds_read_b128 v[184:187], v205 offset:16384
	ds_read_b128 v[188:191], v205 offset:17408
	ds_read_b128 v[192:195], v205 offset:18432
	ds_read_b128 v[212:215], v205 offset:19456
	ds_read_b128 v[216:219], v205 offset:20480
	ds_read_b128 v[220:223], v205 offset:21504
	ds_read_b128 v[224:227], v205 offset:22528
	ds_read_b128 v[228:231], v205 offset:23552
	global_load_lds_dwordx4 v[196:197], off
	s_add_i32 m0, s22, 0x2000
	s_add_u32 s22, s6, 0x40000
	v_lshl_add_u64 v[232:233], s[6:7], 0, v[146:147]
	s_addc_u32 s23, s7, 0
	s_add_i32 s24, s77, s57
	global_load_lds_dwordx4 v[232:233], off
	v_lshl_add_u64 v[234:235], s[22:23], 0, v[142:143]
	s_mov_b32 m0, s24
	global_load_lds_dwordx4 v[234:235], off
	s_add_i32 m0, s24, 0x2000
	v_lshl_add_u64 v[234:235], s[22:23], 0, v[146:147]
	global_load_lds_dwordx4 v[234:235], off
	s_mov_b32 m0, s58
	v_lshl_add_u64 v[234:235], vcc, 0, v[140:141]
	global_load_lds_dwordx4 v[234:235], off
	s_mov_b32 m0, s59
	v_lshl_add_u64 v[236:237], vcc, 0, v[144:145]
	global_load_lds_dwordx4 v[236:237], off
	s_cmp_eq_u32 s21, -2
	s_waitcnt vmcnt(8) lgkmcnt(0)
	s_barrier
	s_cbranch_scc1 .Lzv_2_1
	v_mfma_f32_16x16x32_bf16 v[60:63], v[128:131], v[184:187], v[60:63]
	v_mfma_f32_16x16x32_bf16 v[60:63], v[132:135], v[188:191], v[60:63]
	v_mfma_f32_16x16x32_bf16 v[52:55], v[136:139], v[184:187], v[52:55]
	v_mfma_f32_16x16x32_bf16 v[52:55], v[164:167], v[188:191], v[52:55]
	v_mfma_f32_16x16x32_bf16 v[44:47], v[128:131], v[192:195], v[44:47]
	v_mfma_f32_16x16x32_bf16 v[44:47], v[132:135], v[212:215], v[44:47]
	v_mfma_f32_16x16x32_bf16 v[36:39], v[136:139], v[192:195], v[36:39]
	v_mfma_f32_16x16x32_bf16 v[36:39], v[164:167], v[212:215], v[36:39]
	v_mfma_f32_16x16x32_bf16 v[28:31], v[128:131], v[216:219], v[28:31]
	v_mfma_f32_16x16x32_bf16 v[28:31], v[132:135], v[220:223], v[28:31]
	v_mfma_f32_16x16x32_bf16 v[20:23], v[136:139], v[216:219], v[20:23]
	v_mfma_f32_16x16x32_bf16 v[20:23], v[164:167], v[220:223], v[20:23]
	v_mfma_f32_16x16x32_bf16 v[12:15], v[128:131], v[224:227], v[12:15]
	v_mfma_f32_16x16x32_bf16 v[12:15], v[132:135], v[228:231], v[12:15]
	v_mfma_f32_16x16x32_bf16 v[4:7], v[136:139], v[224:227], v[4:7]
	v_mfma_f32_16x16x32_bf16 v[4:7], v[164:167], v[228:231], v[4:7]
	v_mfma_f32_16x16x32_bf16 v[56:59], v[168:171], v[184:187], v[56:59]
	v_mfma_f32_16x16x32_bf16 v[56:59], v[172:175], v[188:191], v[56:59]
	v_mfma_f32_16x16x32_bf16 v[48:51], v[176:179], v[184:187], v[48:51]
	v_mfma_f32_16x16x32_bf16 v[48:51], v[180:183], v[188:191], v[48:51]
	v_mfma_f32_16x16x32_bf16 v[40:43], v[168:171], v[192:195], v[40:43]
	v_mfma_f32_16x16x32_bf16 v[40:43], v[172:175], v[212:215], v[40:43]
	v_mfma_f32_16x16x32_bf16 v[32:35], v[176:179], v[192:195], v[32:35]
	v_mfma_f32_16x16x32_bf16 v[32:35], v[180:183], v[212:215], v[32:35]
	v_mfma_f32_16x16x32_bf16 v[24:27], v[168:171], v[216:219], v[24:27]
	v_mfma_f32_16x16x32_bf16 v[24:27], v[172:175], v[220:223], v[24:27]
	v_mfma_f32_16x16x32_bf16 v[16:19], v[176:179], v[216:219], v[16:19]
	v_mfma_f32_16x16x32_bf16 v[16:19], v[180:183], v[220:223], v[16:19]
	v_mfma_f32_16x16x32_bf16 v[8:11], v[168:171], v[224:227], v[8:11]
	v_mfma_f32_16x16x32_bf16 v[8:11], v[172:175], v[228:231], v[8:11]
	s_setprio 3
	s_barrier
	v_mfma_f32_16x16x32_bf16 v[0:3], v[176:179], v[224:227], v[0:3]
	v_mfma_f32_16x16x32_bf16 v[0:3], v[180:183], v[228:231], v[0:3]
	s_setprio 0
.Lzj_2_1:
	s_add_i32 s24, 0, 0x18000
	v_add_u32_e32 v150, s24, v200
	s_add_i32 s25, 0, 0x1c000
	ds_read_b128 v[128:131], v150
	ds_read_b128 v[132:135], v150 offset:1024
	ds_read_b128 v[136:139], v150 offset:2048
	ds_read_b128 v[164:167], v150 offset:3072
	v_add_u32_e32 v150, s25, v200
	ds_read_b128 v[168:171], v150
	ds_read_b128 v[172:175], v150 offset:1024
	ds_read_b128 v[176:179], v150 offset:2048
	ds_read_b128 v[180:183], v150 offset:3072
	s_add_u32 s22, vcc_lo, 0x40000
	s_addc_u32 s23, vcc_hi, 0
	s_mov_b32 m0, s66
	v_lshl_add_u64 v[238:239], s[22:23], 0, v[140:141]
	ds_read_b128 v[184:187], v205 offset:32768
	ds_read_b128 v[188:191], v205 offset:33792
	ds_read_b128 v[192:195], v205 offset:34816
	ds_read_b128 v[212:215], v205 offset:35840
	ds_read_b128 v[216:219], v205 offset:36864
	ds_read_b128 v[220:223], v205 offset:37888
	ds_read_b128 v[224:227], v205 offset:38912
	ds_read_b128 v[228:231], v205 offset:39936
	global_load_lds_dwordx4 v[238:239], off
	s_mov_b32 m0, s67
	v_lshl_add_u64 v[238:239], s[22:23], 0, v[144:145]
	global_load_lds_dwordx4 v[238:239], off
	s_waitcnt vmcnt(8) lgkmcnt(0)
	s_barrier
	v_mfma_f32_16x16x32_bf16 v[124:127], v[128:131], v[184:187], v[124:127]
	v_mfma_f32_16x16x32_bf16 v[124:127], v[132:135], v[188:191], v[124:127]
	v_mfma_f32_16x16x32_bf16 v[116:119], v[136:139], v[184:187], v[116:119]
	v_mfma_f32_16x16x32_bf16 v[116:119], v[164:167], v[188:191], v[116:119]
	v_mfma_f32_16x16x32_bf16 v[108:111], v[128:131], v[192:195], v[108:111]
	v_mfma_f32_16x16x32_bf16 v[108:111], v[132:135], v[212:215], v[108:111]
	v_mfma_f32_16x16x32_bf16 v[100:103], v[136:139], v[192:195], v[100:103]
	v_mfma_f32_16x16x32_bf16 v[100:103], v[164:167], v[212:215], v[100:103]
	v_mfma_f32_16x16x32_bf16 v[92:95], v[128:131], v[216:219], v[92:95]
	v_mfma_f32_16x16x32_bf16 v[92:95], v[132:135], v[220:223], v[92:95]
	v_mfma_f32_16x16x32_bf16 v[84:87], v[136:139], v[216:219], v[84:87]
	v_mfma_f32_16x16x32_bf16 v[84:87], v[164:167], v[220:223], v[84:87]
	v_mfma_f32_16x16x32_bf16 v[76:79], v[128:131], v[224:227], v[76:79]
	v_mfma_f32_16x16x32_bf16 v[76:79], v[132:135], v[228:231], v[76:79]
	v_mfma_f32_16x16x32_bf16 v[68:71], v[136:139], v[224:227], v[68:71]
	v_mfma_f32_16x16x32_bf16 v[68:71], v[164:167], v[228:231], v[68:71]
	v_mfma_f32_16x16x32_bf16 v[120:123], v[168:171], v[184:187], v[120:123]
	v_mfma_f32_16x16x32_bf16 v[120:123], v[172:175], v[188:191], v[120:123]
	v_mfma_f32_16x16x32_bf16 v[112:115], v[176:179], v[184:187], v[112:115]
	v_mfma_f32_16x16x32_bf16 v[112:115], v[180:183], v[188:191], v[112:115]
	v_mfma_f32_16x16x32_bf16 v[104:107], v[168:171], v[192:195], v[104:107]
	v_mfma_f32_16x16x32_bf16 v[104:107], v[172:175], v[212:215], v[104:107]
	v_mfma_f32_16x16x32_bf16 v[96:99], v[176:179], v[192:195], v[96:99]
	v_mfma_f32_16x16x32_bf16 v[96:99], v[180:183], v[212:215], v[96:99]
	v_mfma_f32_16x16x32_bf16 v[88:91], v[168:171], v[216:219], v[88:91]
	v_mfma_f32_16x16x32_bf16 v[88:91], v[172:175], v[220:223], v[88:91]
	v_mfma_f32_16x16x32_bf16 v[80:83], v[176:179], v[216:219], v[80:83]
	v_mfma_f32_16x16x32_bf16 v[80:83], v[180:183], v[220:223], v[80:83]
	v_mfma_f32_16x16x32_bf16 v[72:75], v[168:171], v[224:227], v[72:75]
	v_mfma_f32_16x16x32_bf16 v[72:75], v[172:175], v[228:231], v[72:75]
	s_setprio 3
	s_barrier
	v_mfma_f32_16x16x32_bf16 v[64:67], v[176:179], v[224:227], v[64:67]
	v_mfma_f32_16x16x32_bf16 v[64:67], v[180:183], v[228:231], v[64:67]
	s_setprio 0
	s_add_i32 s22, s24, s57
	v_lshl_add_u64 v[196:197], v[196:197], 0, s[80:81]
	s_mov_b32 m0, s22
	ds_read_b128 v[184:187], v205 offset:49152
	ds_read_b128 v[188:191], v205 offset:50176
	ds_read_b128 v[192:195], v205 offset:51200
	ds_read_b128 v[212:215], v205 offset:52224
	ds_read_b128 v[216:219], v205 offset:53248
	ds_read_b128 v[220:223], v205 offset:54272
	ds_read_b128 v[224:227], v205 offset:55296
	ds_read_b128 v[228:231], v205 offset:56320
	global_load_lds_dwordx4 v[196:197], off
	s_add_i32 m0, s22, 0x2000
	s_add_u32 s6, s6, 0x40080
	v_lshl_add_u64 v[196:197], v[232:233], 0, s[80:81]
	s_addc_u32 s7, s7, 0
	s_add_i32 s22, s25, s57
	global_load_lds_dwordx4 v[196:197], off
	s_mov_b32 m0, s22
	v_lshl_add_u64 v[196:197], s[6:7], 0, v[142:143]
	global_load_lds_dwordx4 v[196:197], off
	s_add_i32 m0, s22, 0x2000
	v_lshl_add_u64 v[196:197], s[6:7], 0, v[146:147]
	global_load_lds_dwordx4 v[196:197], off
	s_mov_b32 m0, s93
	v_lshl_add_u64 v[196:197], v[234:235], 0, s[80:81]
	global_load_lds_dwordx4 v[196:197], off
	s_mov_b32 m0, s69
	v_lshl_add_u64 v[196:197], v[236:237], 0, s[80:81]
	global_load_lds_dwordx4 v[196:197], off
	s_waitcnt vmcnt(8) lgkmcnt(0)
	s_barrier
	v_mfma_f32_16x16x32_bf16 v[60:63], v[128:131], v[184:187], v[60:63]
	v_mfma_f32_16x16x32_bf16 v[60:63], v[132:135], v[188:191], v[60:63]
	v_mfma_f32_16x16x32_bf16 v[52:55], v[136:139], v[184:187], v[52:55]
	v_mfma_f32_16x16x32_bf16 v[52:55], v[164:167], v[188:191], v[52:55]
	v_mfma_f32_16x16x32_bf16 v[44:47], v[128:131], v[192:195], v[44:47]
	v_mfma_f32_16x16x32_bf16 v[44:47], v[132:135], v[212:215], v[44:47]
	v_mfma_f32_16x16x32_bf16 v[36:39], v[136:139], v[192:195], v[36:39]
	v_mfma_f32_16x16x32_bf16 v[36:39], v[164:167], v[212:215], v[36:39]
	v_mfma_f32_16x16x32_bf16 v[28:31], v[128:131], v[216:219], v[28:31]
	v_mfma_f32_16x16x32_bf16 v[28:31], v[132:135], v[220:223], v[28:31]
	v_mfma_f32_16x16x32_bf16 v[20:23], v[136:139], v[216:219], v[20:23]
	v_mfma_f32_16x16x32_bf16 v[20:23], v[164:167], v[220:223], v[20:23]
	v_mfma_f32_16x16x32_bf16 v[12:15], v[128:131], v[224:227], v[12:15]
	v_mfma_f32_16x16x32_bf16 v[12:15], v[132:135], v[228:231], v[12:15]
	v_mfma_f32_16x16x32_bf16 v[4:7], v[136:139], v[224:227], v[4:7]
	v_mfma_f32_16x16x32_bf16 v[4:7], v[164:167], v[228:231], v[4:7]
	v_mfma_f32_16x16x32_bf16 v[56:59], v[168:171], v[184:187], v[56:59]
	v_mfma_f32_16x16x32_bf16 v[56:59], v[172:175], v[188:191], v[56:59]
	v_mfma_f32_16x16x32_bf16 v[48:51], v[176:179], v[184:187], v[48:51]
	v_mfma_f32_16x16x32_bf16 v[48:51], v[180:183], v[188:191], v[48:51]
	v_mfma_f32_16x16x32_bf16 v[40:43], v[168:171], v[192:195], v[40:43]
	v_mfma_f32_16x16x32_bf16 v[40:43], v[172:175], v[212:215], v[40:43]
	v_mfma_f32_16x16x32_bf16 v[32:35], v[176:179], v[192:195], v[32:35]
	v_mfma_f32_16x16x32_bf16 v[32:35], v[180:183], v[212:215], v[32:35]
	v_mfma_f32_16x16x32_bf16 v[24:27], v[168:171], v[216:219], v[24:27]
	v_mfma_f32_16x16x32_bf16 v[24:27], v[172:175], v[220:223], v[24:27]
	v_mfma_f32_16x16x32_bf16 v[16:19], v[176:179], v[216:219], v[16:19]
	v_mfma_f32_16x16x32_bf16 v[16:19], v[180:183], v[220:223], v[16:19]
	v_mfma_f32_16x16x32_bf16 v[8:11], v[168:171], v[224:227], v[8:11]
	v_mfma_f32_16x16x32_bf16 v[8:11], v[172:175], v[228:231], v[8:11]
	s_setprio 3
	s_barrier
	v_mfma_f32_16x16x32_bf16 v[0:3], v[176:179], v[224:227], v[0:3]
	v_mfma_f32_16x16x32_bf16 v[0:3], v[180:183], v[228:231], v[0:3]
	s_setprio 0
	s_add_i32 s21, s21, 2
	s_add_u32 s88, s88, 0x100
	s_addc_u32 s89, s89, 0
	s_add_u32 s19, s19, 0x100
	s_addc_u32 s20, s20, 0
	s_cmp_gt_u32 s21, 13
	s_cbranch_scc0 .LBB0_429
	s_branch .Lzskip_2

.LBB0_993:
	ds_read_b128 v[120:123], v245
	ds_read_b128 v[124:127], v245 offset:1024
	ds_read_b128 v[128:131], v245 offset:2048
	ds_read_b128 v[132:135], v245 offset:3072
	ds_read_b128 v[144:147], v246
	ds_read_b128 v[148:151], v246 offset:1024
	ds_read_b128 v[152:155], v246 offset:2048
	ds_read_b128 v[156:159], v246 offset:3072
	s_add_u32 s59, s82, 0xfffc0080
	s_addc_u32 s66, s83, -1
	s_cmp_eq_u32 s58, 12
	s_cselect_b32 s87, s53, s66
	s_cselect_b32 s86, s54, s59
	s_cselect_b32 s85, s51, s57
	s_cselect_b32 s84, s55, s56
	v_lshl_add_u64 v[204:205], s[82:83], 0, v[200:201]
	s_add_i32 m0, s16, 0xc000
	ds_read_b128 v[160:163], v247
	ds_read_b128 v[164:167], v247 offset:1024
	ds_read_b128 v[168:171], v247 offset:2048
	ds_read_b128 v[172:175], v247 offset:3072
	ds_read_b128 v[176:179], v247 offset:4096
	ds_read_b128 v[180:183], v247 offset:5120
	ds_read_b128 v[184:187], v247 offset:6144
	ds_read_b128 v[188:191], v247 offset:7168
	global_load_lds_dwordx4 v[204:205], off
	s_add_i32 m0, s16, 0xe000
	v_lshl_add_u64 v[204:205], s[82:83], 0, v[202:203]
	global_load_lds_dwordx4 v[204:205], off
	s_cmp_eq_u32 s58, -2
	s_waitcnt vmcnt(8) lgkmcnt(0)
	s_barrier
	s_cbranch_scc1 .Lzv_3_0
	v_mfma_f32_16x16x32_bf16 v[140:143], v[120:123], v[160:163], v[140:143]
	v_mfma_f32_16x16x32_bf16 v[140:143], v[124:127], v[164:167], v[140:143]
	v_mfma_f32_16x16x32_bf16 v[136:139], v[128:131], v[160:163], v[136:139]
	v_mfma_f32_16x16x32_bf16 v[136:139], v[132:135], v[164:167], v[136:139]
	v_mfma_f32_16x16x32_bf16 v[108:111], v[120:123], v[168:171], v[108:111]
	v_mfma_f32_16x16x32_bf16 v[108:111], v[124:127], v[172:175], v[108:111]
	v_mfma_f32_16x16x32_bf16 v[104:107], v[128:131], v[168:171], v[104:107]
	v_mfma_f32_16x16x32_bf16 v[104:107], v[132:135], v[172:175], v[104:107]
	v_mfma_f32_16x16x32_bf16 v[92:95], v[120:123], v[176:179], v[92:95]
	v_mfma_f32_16x16x32_bf16 v[92:95], v[124:127], v[180:183], v[92:95]
	v_mfma_f32_16x16x32_bf16 v[88:91], v[128:131], v[176:179], v[88:91]
	v_mfma_f32_16x16x32_bf16 v[88:91], v[132:135], v[180:183], v[88:91]
	v_mfma_f32_16x16x32_bf16 v[76:79], v[120:123], v[184:187], v[76:79]
	v_mfma_f32_16x16x32_bf16 v[76:79], v[124:127], v[188:191], v[76:79]
	v_mfma_f32_16x16x32_bf16 v[72:75], v[128:131], v[184:187], v[72:75]
	v_mfma_f32_16x16x32_bf16 v[72:75], v[132:135], v[188:191], v[72:75]
	v_mfma_f32_16x16x32_bf16 v[116:119], v[144:147], v[160:163], v[116:119]
	v_mfma_f32_16x16x32_bf16 v[116:119], v[148:151], v[164:167], v[116:119]
	v_mfma_f32_16x16x32_bf16 v[112:115], v[152:155], v[160:163], v[112:115]
	v_mfma_f32_16x16x32_bf16 v[112:115], v[156:159], v[164:167], v[112:115]
	v_mfma_f32_16x16x32_bf16 v[100:103], v[144:147], v[168:171], v[100:103]
	v_mfma_f32_16x16x32_bf16 v[100:103], v[148:151], v[172:175], v[100:103]
	v_mfma_f32_16x16x32_bf16 v[96:99], v[152:155], v[168:171], v[96:99]
	v_mfma_f32_16x16x32_bf16 v[96:99], v[156:159], v[172:175], v[96:99]
	v_mfma_f32_16x16x32_bf16 v[84:87], v[144:147], v[176:179], v[84:87]
	v_mfma_f32_16x16x32_bf16 v[84:87], v[148:151], v[180:183], v[84:87]
	v_mfma_f32_16x16x32_bf16 v[80:83], v[152:155], v[176:179], v[80:83]
	v_mfma_f32_16x16x32_bf16 v[80:83], v[156:159], v[180:183], v[80:83]
	v_mfma_f32_16x16x32_bf16 v[68:71], v[144:147], v[184:187], v[68:71]
	v_mfma_f32_16x16x32_bf16 v[68:71], v[148:151], v[188:191], v[68:71]
	s_setprio 3
	s_barrier
	v_mfma_f32_16x16x32_bf16 v[64:67], v[152:155], v[184:187], v[64:67]
	v_mfma_f32_16x16x32_bf16 v[64:67], v[156:159], v[188:191], v[64:67]
	s_setprio 0
.Lzj_3_0:
	s_add_i32 s59, s26, s15
	v_lshl_add_u64 v[204:205], s[84:85], 0, v[194:195]
	s_mov_b32 m0, s59
	ds_read_b128 v[160:163], v247 offset:16384
	ds_read_b128 v[164:167], v247 offset:17408
	ds_read_b128 v[168:171], v247 offset:18432
	ds_read_b128 v[172:175], v247 offset:19456
	ds_read_b128 v[176:179], v247 offset:20480
	ds_read_b128 v[180:183], v247 offset:21504
	ds_read_b128 v[184:187], v247 offset:22528
	ds_read_b128 v[188:191], v247 offset:23552
	global_load_lds_dwordx4 v[204:205], off
	s_add_i32 m0, s59, 0x2000
	s_add_u32 s66, s84, 0x40000
	v_lshl_add_u64 v[206:207], s[84:85], 0, v[198:199]
	s_addc_u32 s67, s85, 0
	s_add_i32 s59, s27, s15
	global_load_lds_dwordx4 v[206:207], off
	v_lshl_add_u64 v[208:209], s[66:67], 0, v[194:195]
	s_mov_b32 m0, s59
	global_load_lds_dwordx4 v[208:209], off
	s_add_i32 m0, s59, 0x2000
	v_lshl_add_u64 v[208:209], s[66:67], 0, v[198:199]
	global_load_lds_dwordx4 v[208:209], off
	s_mov_b32 m0, s16
	v_lshl_add_u64 v[208:209], s[86:87], 0, v[192:193]
	global_load_lds_dwordx4 v[208:209], off
	s_mov_b32 m0, s17
	v_lshl_add_u64 v[210:211], s[86:87], 0, v[196:197]
	global_load_lds_dwordx4 v[210:211], off
	s_cmp_eq_u32 s58, -2
	s_waitcnt vmcnt(8) lgkmcnt(0)
	s_barrier
	s_cbranch_scc1 .Lzv_3_1
	v_mfma_f32_16x16x32_bf16 v[60:63], v[120:123], v[160:163], v[60:63]
	v_mfma_f32_16x16x32_bf16 v[60:63], v[124:127], v[164:167], v[60:63]
	v_mfma_f32_16x16x32_bf16 v[56:59], v[128:131], v[160:163], v[56:59]
	v_mfma_f32_16x16x32_bf16 v[56:59], v[132:135], v[164:167], v[56:59]
	v_mfma_f32_16x16x32_bf16 v[44:47], v[120:123], v[168:171], v[44:47]
	v_mfma_f32_16x16x32_bf16 v[44:47], v[124:127], v[172:175], v[44:47]
	v_mfma_f32_16x16x32_bf16 v[40:43], v[128:131], v[168:171], v[40:43]
	v_mfma_f32_16x16x32_bf16 v[40:43], v[132:135], v[172:175], v[40:43]
	v_mfma_f32_16x16x32_bf16 v[28:31], v[120:123], v[176:179], v[28:31]
	v_mfma_f32_16x16x32_bf16 v[28:31], v[124:127], v[180:183], v[28:31]
	v_mfma_f32_16x16x32_bf16 v[24:27], v[128:131], v[176:179], v[24:27]
	v_mfma_f32_16x16x32_bf16 v[24:27], v[132:135], v[180:183], v[24:27]
	v_mfma_f32_16x16x32_bf16 v[12:15], v[120:123], v[184:187], v[12:15]
	v_mfma_f32_16x16x32_bf16 v[12:15], v[124:127], v[188:191], v[12:15]
	v_mfma_f32_16x16x32_bf16 v[8:11], v[128:131], v[184:187], v[8:11]
	v_mfma_f32_16x16x32_bf16 v[8:11], v[132:135], v[188:191], v[8:11]
	v_mfma_f32_16x16x32_bf16 v[52:55], v[144:147], v[160:163], v[52:55]
	v_mfma_f32_16x16x32_bf16 v[52:55], v[148:151], v[164:167], v[52:55]
	v_mfma_f32_16x16x32_bf16 v[48:51], v[152:155], v[160:163], v[48:51]
	v_mfma_f32_16x16x32_bf16 v[48:51], v[156:159], v[164:167], v[48:51]
	v_mfma_f32_16x16x32_bf16 v[36:39], v[144:147], v[168:171], v[36:39]
	v_mfma_f32_16x16x32_bf16 v[36:39], v[148:151], v[172:175], v[36:39]
	v_mfma_f32_16x16x32_bf16 v[32:35], v[152:155], v[168:171], v[32:35]
	v_mfma_f32_16x16x32_bf16 v[32:35], v[156:159], v[172:175], v[32:35]
	v_mfma_f32_16x16x32_bf16 v[20:23], v[144:147], v[176:179], v[20:23]
	v_mfma_f32_16x16x32_bf16 v[20:23], v[148:151], v[180:183], v[20:23]
	v_mfma_f32_16x16x32_bf16 v[16:19], v[152:155], v[176:179], v[16:19]
	v_mfma_f32_16x16x32_bf16 v[16:19], v[156:159], v[180:183], v[16:19]
	v_mfma_f32_16x16x32_bf16 v[4:7], v[144:147], v[184:187], v[4:7]
	v_mfma_f32_16x16x32_bf16 v[4:7], v[148:151], v[188:191], v[4:7]
	s_setprio 3
	s_barrier
	v_mfma_f32_16x16x32_bf16 v[0:3], v[152:155], v[184:187], v[0:3]
	v_mfma_f32_16x16x32_bf16 v[0:3], v[156:159], v[188:191], v[0:3]
	s_setprio 0
.Lzj_3_1:
	s_add_i32 s59, 0, 0x18000
	s_add_i32 s68, 0, 0x1c000
	v_add_u32_e32 v132, s59, v243
	v_add_u32_e32 v156, s68, v243
	ds_read_b128 v[120:123], v132
	ds_read_b128 v[124:127], v132 offset:1024
	ds_read_b128 v[128:131], v132 offset:2048
	ds_read_b128 v[132:135], v132 offset:3072
	ds_read_b128 v[144:147], v156
	ds_read_b128 v[148:151], v156 offset:1024
	ds_read_b128 v[152:155], v156 offset:2048
	ds_read_b128 v[156:159], v156 offset:3072
	s_add_u32 s66, s86, 0x40000
	s_addc_u32 s67, s87, 0
	s_mov_b32 m0, s18
	v_lshl_add_u64 v[212:213], s[66:67], 0, v[192:193]
	ds_read_b128 v[160:163], v247 offset:32768
	ds_read_b128 v[164:167], v247 offset:33792
	ds_read_b128 v[168:171], v247 offset:34816
	ds_read_b128 v[172:175], v247 offset:35840
	ds_read_b128 v[176:179], v247 offset:36864
	ds_read_b128 v[180:183], v247 offset:37888
	ds_read_b128 v[184:187], v247 offset:38912
	ds_read_b128 v[188:191], v247 offset:39936
	global_load_lds_dwordx4 v[212:213], off
	s_mov_b32 m0, s19
	v_lshl_add_u64 v[212:213], s[66:67], 0, v[196:197]
	global_load_lds_dwordx4 v[212:213], off
	s_waitcnt vmcnt(8) lgkmcnt(0)
	s_barrier
	v_mfma_f32_16x16x32_bf16 v[140:143], v[120:123], v[160:163], v[140:143]
	v_mfma_f32_16x16x32_bf16 v[140:143], v[124:127], v[164:167], v[140:143]
	v_mfma_f32_16x16x32_bf16 v[136:139], v[128:131], v[160:163], v[136:139]
	v_mfma_f32_16x16x32_bf16 v[136:139], v[132:135], v[164:167], v[136:139]
	v_mfma_f32_16x16x32_bf16 v[108:111], v[120:123], v[168:171], v[108:111]
	v_mfma_f32_16x16x32_bf16 v[108:111], v[124:127], v[172:175], v[108:111]
	v_mfma_f32_16x16x32_bf16 v[104:107], v[128:131], v[168:171], v[104:107]
	v_mfma_f32_16x16x32_bf16 v[104:107], v[132:135], v[172:175], v[104:107]
	v_mfma_f32_16x16x32_bf16 v[92:95], v[120:123], v[176:179], v[92:95]
	v_mfma_f32_16x16x32_bf16 v[92:95], v[124:127], v[180:183], v[92:95]
	v_mfma_f32_16x16x32_bf16 v[88:91], v[128:131], v[176:179], v[88:91]
	v_mfma_f32_16x16x32_bf16 v[88:91], v[132:135], v[180:183], v[88:91]
	v_mfma_f32_16x16x32_bf16 v[76:79], v[120:123], v[184:187], v[76:79]
	v_mfma_f32_16x16x32_bf16 v[76:79], v[124:127], v[188:191], v[76:79]
	v_mfma_f32_16x16x32_bf16 v[72:75], v[128:131], v[184:187], v[72:75]
	v_mfma_f32_16x16x32_bf16 v[72:75], v[132:135], v[188:191], v[72:75]
	v_mfma_f32_16x16x32_bf16 v[116:119], v[144:147], v[160:163], v[116:119]
	v_mfma_f32_16x16x32_bf16 v[116:119], v[148:151], v[164:167], v[116:119]
	v_mfma_f32_16x16x32_bf16 v[112:115], v[152:155], v[160:163], v[112:115]
	v_mfma_f32_16x16x32_bf16 v[112:115], v[156:159], v[164:167], v[112:115]
	v_mfma_f32_16x16x32_bf16 v[100:103], v[144:147], v[168:171], v[100:103]
	v_mfma_f32_16x16x32_bf16 v[100:103], v[148:151], v[172:175], v[100:103]
	v_mfma_f32_16x16x32_bf16 v[96:99], v[152:155], v[168:171], v[96:99]
	v_mfma_f32_16x16x32_bf16 v[96:99], v[156:159], v[172:175], v[96:99]
	v_mfma_f32_16x16x32_bf16 v[84:87], v[144:147], v[176:179], v[84:87]
	v_mfma_f32_16x16x32_bf16 v[84:87], v[148:151], v[180:183], v[84:87]
	v_mfma_f32_16x16x32_bf16 v[80:83], v[152:155], v[176:179], v[80:83]
	v_mfma_f32_16x16x32_bf16 v[80:83], v[156:159], v[180:183], v[80:83]
	v_mfma_f32_16x16x32_bf16 v[68:71], v[144:147], v[184:187], v[68:71]
	v_mfma_f32_16x16x32_bf16 v[68:71], v[148:151], v[188:191], v[68:71]
	s_setprio 3
	s_barrier
	v_mfma_f32_16x16x32_bf16 v[64:67], v[152:155], v[184:187], v[64:67]
	v_mfma_f32_16x16x32_bf16 v[64:67], v[156:159], v[188:191], v[64:67]
	s_setprio 0
	s_add_i32 s59, s59, s15
	v_lshl_add_u64 v[204:205], v[204:205], 0, s[46:47]
	s_mov_b32 m0, s59
	ds_read_b128 v[160:163], v247 offset:49152
	ds_read_b128 v[164:167], v247 offset:50176
	ds_read_b128 v[168:171], v247 offset:51200
	ds_read_b128 v[172:175], v247 offset:52224
	ds_read_b128 v[176:179], v247 offset:53248
	ds_read_b128 v[180:183], v247 offset:54272
	ds_read_b128 v[184:187], v247 offset:55296
	ds_read_b128 v[188:191], v247 offset:56320
	global_load_lds_dwordx4 v[204:205], off
	s_add_i32 m0, s59, 0x2000
	s_add_u32 s66, s84, 0x40080
	v_lshl_add_u64 v[204:205], v[206:207], 0, s[46:47]
	s_addc_u32 s67, s85, 0
	s_add_i32 s59, s68, s15
	global_load_lds_dwordx4 v[204:205], off
	s_mov_b32 m0, s59
	v_lshl_add_u64 v[204:205], s[66:67], 0, v[194:195]
	global_load_lds_dwordx4 v[204:205], off
	s_add_i32 m0, s59, 0x2000
	v_lshl_add_u64 v[204:205], s[66:67], 0, v[198:199]
	global_load_lds_dwordx4 v[204:205], off
	s_mov_b32 m0, s21
	v_lshl_add_u64 v[204:205], v[208:209], 0, s[46:47]
	global_load_lds_dwordx4 v[204:205], off
	s_mov_b32 m0, s22
	v_lshl_add_u64 v[204:205], v[210:211], 0, s[46:47]
	global_load_lds_dwordx4 v[204:205], off
	s_waitcnt vmcnt(8) lgkmcnt(0)
	s_barrier
	v_mfma_f32_16x16x32_bf16 v[60:63], v[120:123], v[160:163], v[60:63]
	v_mfma_f32_16x16x32_bf16 v[60:63], v[124:127], v[164:167], v[60:63]
	v_mfma_f32_16x16x32_bf16 v[56:59], v[128:131], v[160:163], v[56:59]
	v_mfma_f32_16x16x32_bf16 v[56:59], v[132:135], v[164:167], v[56:59]
	v_mfma_f32_16x16x32_bf16 v[44:47], v[120:123], v[168:171], v[44:47]
	v_mfma_f32_16x16x32_bf16 v[44:47], v[124:127], v[172:175], v[44:47]
	v_mfma_f32_16x16x32_bf16 v[40:43], v[128:131], v[168:171], v[40:43]
	v_mfma_f32_16x16x32_bf16 v[40:43], v[132:135], v[172:175], v[40:43]
	v_mfma_f32_16x16x32_bf16 v[28:31], v[120:123], v[176:179], v[28:31]
	v_mfma_f32_16x16x32_bf16 v[28:31], v[124:127], v[180:183], v[28:31]
	v_mfma_f32_16x16x32_bf16 v[24:27], v[128:131], v[176:179], v[24:27]
	v_mfma_f32_16x16x32_bf16 v[24:27], v[132:135], v[180:183], v[24:27]
	v_mfma_f32_16x16x32_bf16 v[12:15], v[120:123], v[184:187], v[12:15]
	v_mfma_f32_16x16x32_bf16 v[12:15], v[124:127], v[188:191], v[12:15]
	v_mfma_f32_16x16x32_bf16 v[8:11], v[128:131], v[184:187], v[8:11]
	v_mfma_f32_16x16x32_bf16 v[8:11], v[132:135], v[188:191], v[8:11]
	v_mfma_f32_16x16x32_bf16 v[52:55], v[144:147], v[160:163], v[52:55]
	v_mfma_f32_16x16x32_bf16 v[52:55], v[148:151], v[164:167], v[52:55]
	v_mfma_f32_16x16x32_bf16 v[48:51], v[152:155], v[160:163], v[48:51]
	v_mfma_f32_16x16x32_bf16 v[48:51], v[156:159], v[164:167], v[48:51]
	v_mfma_f32_16x16x32_bf16 v[36:39], v[144:147], v[168:171], v[36:39]
	v_mfma_f32_16x16x32_bf16 v[36:39], v[148:151], v[172:175], v[36:39]
	v_mfma_f32_16x16x32_bf16 v[32:35], v[152:155], v[168:171], v[32:35]
	v_mfma_f32_16x16x32_bf16 v[32:35], v[156:159], v[172:175], v[32:35]
	v_mfma_f32_16x16x32_bf16 v[20:23], v[144:147], v[176:179], v[20:23]
	v_mfma_f32_16x16x32_bf16 v[20:23], v[148:151], v[180:183], v[20:23]
	v_mfma_f32_16x16x32_bf16 v[16:19], v[152:155], v[176:179], v[16:19]
	v_mfma_f32_16x16x32_bf16 v[16:19], v[156:159], v[180:183], v[16:19]
	v_mfma_f32_16x16x32_bf16 v[4:7], v[144:147], v[184:187], v[4:7]
	v_mfma_f32_16x16x32_bf16 v[4:7], v[148:151], v[188:191], v[4:7]
	s_setprio 3
	s_barrier
	v_mfma_f32_16x16x32_bf16 v[0:3], v[152:155], v[184:187], v[0:3]
	v_mfma_f32_16x16x32_bf16 v[0:3], v[156:159], v[188:191], v[0:3]
	s_setprio 0
	s_add_i32 s58, s58, 2
	s_add_u32 s82, s82, 0x100
	s_addc_u32 s83, s83, 0
	s_add_u32 s56, s56, 0x100
	s_addc_u32 s57, s57, 0
	s_cmp_gt_u32 s58, 13
	s_cbranch_scc0 .LBB0_993
	s_branch .Lzskip_3

.LBB0_1148:
	ds_read_b128 v[146:149], v174
	ds_read_b128 v[150:153], v174 offset:1024
	ds_read_b128 v[154:157], v174 offset:2048
	ds_read_b128 v[158:161], v174 offset:3072
	ds_read_b128 v[162:165], v175
	ds_read_b128 v[178:181], v175 offset:1024
	ds_read_b128 v[182:185], v175 offset:2048
	ds_read_b128 v[186:189], v175 offset:3072
	s_add_u32 s67, s78, 0xfffc0080
	s_addc_u32 s68, s79, -1
	s_cmp_eq_u32 s66, 12
	s_cselect_b32 s83, s49, s68
	s_cselect_b32 s82, s54, s67
	s_cselect_b32 s81, s47, s59
	s_cselect_b32 s80, s55, s58
	v_lshl_add_u64 v[166:167], s[78:79], 0, v[136:137]
	s_add_i32 m0, s17, 0xc000
	ds_read_b128 v[190:193], v176
	ds_read_b128 v[194:197], v176 offset:1024
	ds_read_b128 v[198:201], v176 offset:2048
	ds_read_b128 v[202:205], v176 offset:3072
	ds_read_b128 v[206:209], v176 offset:4096
	ds_read_b128 v[210:213], v176 offset:5120
	ds_read_b128 v[214:217], v176 offset:6144
	ds_read_b128 v[218:221], v176 offset:7168
	global_load_lds_dwordx4 v[166:167], off
	s_add_i32 m0, s17, 0xe000
	v_lshl_add_u64 v[166:167], s[78:79], 0, v[140:141]
	global_load_lds_dwordx4 v[166:167], off
	s_cmp_eq_u32 s66, -2
	s_waitcnt vmcnt(8) lgkmcnt(0)
	s_barrier
	s_cbranch_scc1 .Lzv_4_0
	v_mfma_f32_16x16x32_bf16 v[124:127], v[146:149], v[190:193], v[124:127]
	v_mfma_f32_16x16x32_bf16 v[124:127], v[150:153], v[194:197], v[124:127]
	v_mfma_f32_16x16x32_bf16 v[116:119], v[154:157], v[190:193], v[116:119]
	v_mfma_f32_16x16x32_bf16 v[116:119], v[158:161], v[194:197], v[116:119]
	v_mfma_f32_16x16x32_bf16 v[108:111], v[146:149], v[198:201], v[108:111]
	v_mfma_f32_16x16x32_bf16 v[108:111], v[150:153], v[202:205], v[108:111]
	v_mfma_f32_16x16x32_bf16 v[100:103], v[154:157], v[198:201], v[100:103]
	v_mfma_f32_16x16x32_bf16 v[100:103], v[158:161], v[202:205], v[100:103]
	v_mfma_f32_16x16x32_bf16 v[92:95], v[146:149], v[206:209], v[92:95]
	v_mfma_f32_16x16x32_bf16 v[92:95], v[150:153], v[210:213], v[92:95]
	v_mfma_f32_16x16x32_bf16 v[84:87], v[154:157], v[206:209], v[84:87]
	v_mfma_f32_16x16x32_bf16 v[84:87], v[158:161], v[210:213], v[84:87]
	v_mfma_f32_16x16x32_bf16 v[76:79], v[146:149], v[214:217], v[76:79]
	v_mfma_f32_16x16x32_bf16 v[76:79], v[150:153], v[218:221], v[76:79]
	v_mfma_f32_16x16x32_bf16 v[68:71], v[154:157], v[214:217], v[68:71]
	v_mfma_f32_16x16x32_bf16 v[68:71], v[158:161], v[218:221], v[68:71]
	v_mfma_f32_16x16x32_bf16 v[120:123], v[162:165], v[190:193], v[120:123]
	v_mfma_f32_16x16x32_bf16 v[120:123], v[178:181], v[194:197], v[120:123]
	v_mfma_f32_16x16x32_bf16 v[112:115], v[182:185], v[190:193], v[112:115]
	v_mfma_f32_16x16x32_bf16 v[112:115], v[186:189], v[194:197], v[112:115]
	v_mfma_f32_16x16x32_bf16 v[104:107], v[162:165], v[198:201], v[104:107]
	v_mfma_f32_16x16x32_bf16 v[104:107], v[178:181], v[202:205], v[104:107]
	v_mfma_f32_16x16x32_bf16 v[96:99], v[182:185], v[198:201], v[96:99]
	v_mfma_f32_16x16x32_bf16 v[96:99], v[186:189], v[202:205], v[96:99]
	v_mfma_f32_16x16x32_bf16 v[88:91], v[162:165], v[206:209], v[88:91]
	v_mfma_f32_16x16x32_bf16 v[88:91], v[178:181], v[210:213], v[88:91]
	v_mfma_f32_16x16x32_bf16 v[80:83], v[182:185], v[206:209], v[80:83]
	v_mfma_f32_16x16x32_bf16 v[80:83], v[186:189], v[210:213], v[80:83]
	v_mfma_f32_16x16x32_bf16 v[72:75], v[162:165], v[214:217], v[72:75]
	v_mfma_f32_16x16x32_bf16 v[72:75], v[178:181], v[218:221], v[72:75]
	s_setprio 3
	s_barrier
	v_mfma_f32_16x16x32_bf16 v[64:67], v[182:185], v[214:217], v[64:67]
	v_mfma_f32_16x16x32_bf16 v[64:67], v[186:189], v[218:221], v[64:67]
	s_setprio 0
.Lzj_4_0:
	s_add_i32 s67, s25, s16
	v_lshl_add_u64 v[166:167], s[80:81], 0, v[132:133]
	s_mov_b32 m0, s67
	ds_read_b128 v[190:193], v176 offset:16384
	ds_read_b128 v[194:197], v176 offset:17408
	ds_read_b128 v[198:201], v176 offset:18432
	ds_read_b128 v[202:205], v176 offset:19456
	ds_read_b128 v[206:209], v176 offset:20480
	ds_read_b128 v[210:213], v176 offset:21504
	ds_read_b128 v[214:217], v176 offset:22528
	ds_read_b128 v[218:221], v176 offset:23552
	global_load_lds_dwordx4 v[166:167], off
	s_add_i32 m0, s67, 0x2000
	s_add_u32 s68, s80, 0x40000
	v_lshl_add_u64 v[222:223], s[80:81], 0, v[128:129]
	s_addc_u32 s69, s81, 0
	s_add_i32 s67, s26, s16
	global_load_lds_dwordx4 v[222:223], off
	v_lshl_add_u64 v[224:225], s[68:69], 0, v[132:133]
	s_mov_b32 m0, s67
	global_load_lds_dwordx4 v[224:225], off
	s_add_i32 m0, s67, 0x2000
	v_lshl_add_u64 v[224:225], s[68:69], 0, v[128:129]
	global_load_lds_dwordx4 v[224:225], off
	s_mov_b32 m0, s17
	v_lshl_add_u64 v[224:225], s[82:83], 0, v[134:135]
	global_load_lds_dwordx4 v[224:225], off
	s_mov_b32 m0, s18
	v_lshl_add_u64 v[226:227], s[82:83], 0, v[130:131]
	global_load_lds_dwordx4 v[226:227], off
	s_cmp_eq_u32 s66, -2
	s_waitcnt vmcnt(8) lgkmcnt(0)
	s_barrier
	s_cbranch_scc1 .Lzv_4_1
	v_mfma_f32_16x16x32_bf16 v[60:63], v[146:149], v[190:193], v[60:63]
	v_mfma_f32_16x16x32_bf16 v[60:63], v[150:153], v[194:197], v[60:63]
	v_mfma_f32_16x16x32_bf16 v[52:55], v[154:157], v[190:193], v[52:55]
	v_mfma_f32_16x16x32_bf16 v[52:55], v[158:161], v[194:197], v[52:55]
	v_mfma_f32_16x16x32_bf16 v[44:47], v[146:149], v[198:201], v[44:47]
	v_mfma_f32_16x16x32_bf16 v[44:47], v[150:153], v[202:205], v[44:47]
	v_mfma_f32_16x16x32_bf16 v[36:39], v[154:157], v[198:201], v[36:39]
	v_mfma_f32_16x16x32_bf16 v[36:39], v[158:161], v[202:205], v[36:39]
	v_mfma_f32_16x16x32_bf16 v[28:31], v[146:149], v[206:209], v[28:31]
	v_mfma_f32_16x16x32_bf16 v[28:31], v[150:153], v[210:213], v[28:31]
	v_mfma_f32_16x16x32_bf16 v[20:23], v[154:157], v[206:209], v[20:23]
	v_mfma_f32_16x16x32_bf16 v[20:23], v[158:161], v[210:213], v[20:23]
	v_mfma_f32_16x16x32_bf16 v[12:15], v[146:149], v[214:217], v[12:15]
	v_mfma_f32_16x16x32_bf16 v[12:15], v[150:153], v[218:221], v[12:15]
	v_mfma_f32_16x16x32_bf16 v[4:7], v[154:157], v[214:217], v[4:7]
	v_mfma_f32_16x16x32_bf16 v[4:7], v[158:161], v[218:221], v[4:7]
	v_mfma_f32_16x16x32_bf16 v[56:59], v[162:165], v[190:193], v[56:59]
	v_mfma_f32_16x16x32_bf16 v[56:59], v[178:181], v[194:197], v[56:59]
	v_mfma_f32_16x16x32_bf16 v[48:51], v[182:185], v[190:193], v[48:51]
	v_mfma_f32_16x16x32_bf16 v[48:51], v[186:189], v[194:197], v[48:51]
	v_mfma_f32_16x16x32_bf16 v[40:43], v[162:165], v[198:201], v[40:43]
	v_mfma_f32_16x16x32_bf16 v[40:43], v[178:181], v[202:205], v[40:43]
	v_mfma_f32_16x16x32_bf16 v[32:35], v[182:185], v[198:201], v[32:35]
	v_mfma_f32_16x16x32_bf16 v[32:35], v[186:189], v[202:205], v[32:35]
	v_mfma_f32_16x16x32_bf16 v[24:27], v[162:165], v[206:209], v[24:27]
	v_mfma_f32_16x16x32_bf16 v[24:27], v[178:181], v[210:213], v[24:27]
	v_mfma_f32_16x16x32_bf16 v[16:19], v[182:185], v[206:209], v[16:19]
	v_mfma_f32_16x16x32_bf16 v[16:19], v[186:189], v[210:213], v[16:19]
	v_mfma_f32_16x16x32_bf16 v[8:11], v[162:165], v[214:217], v[8:11]
	v_mfma_f32_16x16x32_bf16 v[8:11], v[178:181], v[218:221], v[8:11]
	s_setprio 3
	s_barrier
	v_mfma_f32_16x16x32_bf16 v[0:3], v[182:185], v[214:217], v[0:3]
	v_mfma_f32_16x16x32_bf16 v[0:3], v[186:189], v[218:221], v[0:3]
	s_setprio 0
.Lzj_4_1:
	s_add_i32 s67, 0, 0x18000
	s_add_i32 s73, 0, 0x1c000
	v_add_u32_e32 v158, s67, v171
	v_add_u32_e32 v186, s73, v171
	ds_read_b128 v[146:149], v158
	ds_read_b128 v[150:153], v158 offset:1024
	ds_read_b128 v[154:157], v158 offset:2048
	ds_read_b128 v[158:161], v158 offset:3072
	ds_read_b128 v[162:165], v186
	ds_read_b128 v[178:181], v186 offset:1024
	ds_read_b128 v[182:185], v186 offset:2048
	ds_read_b128 v[186:189], v186 offset:3072
	s_add_u32 s68, s82, 0x40000
	s_addc_u32 s69, s83, 0
	s_mov_b32 m0, s19
	v_lshl_add_u64 v[228:229], s[68:69], 0, v[134:135]
	ds_read_b128 v[190:193], v176 offset:32768
	ds_read_b128 v[194:197], v176 offset:33792
	ds_read_b128 v[198:201], v176 offset:34816
	ds_read_b128 v[202:205], v176 offset:35840
	ds_read_b128 v[206:209], v176 offset:36864
	ds_read_b128 v[210:213], v176 offset:37888
	ds_read_b128 v[214:217], v176 offset:38912
	ds_read_b128 v[218:221], v176 offset:39936
	global_load_lds_dwordx4 v[228:229], off
	s_mov_b32 m0, s20
	v_lshl_add_u64 v[228:229], s[68:69], 0, v[130:131]
	global_load_lds_dwordx4 v[228:229], off
	s_waitcnt vmcnt(8) lgkmcnt(0)
	s_barrier
	v_mfma_f32_16x16x32_bf16 v[124:127], v[146:149], v[190:193], v[124:127]
	v_mfma_f32_16x16x32_bf16 v[124:127], v[150:153], v[194:197], v[124:127]
	v_mfma_f32_16x16x32_bf16 v[116:119], v[154:157], v[190:193], v[116:119]
	v_mfma_f32_16x16x32_bf16 v[116:119], v[158:161], v[194:197], v[116:119]
	v_mfma_f32_16x16x32_bf16 v[108:111], v[146:149], v[198:201], v[108:111]
	v_mfma_f32_16x16x32_bf16 v[108:111], v[150:153], v[202:205], v[108:111]
	v_mfma_f32_16x16x32_bf16 v[100:103], v[154:157], v[198:201], v[100:103]
	v_mfma_f32_16x16x32_bf16 v[100:103], v[158:161], v[202:205], v[100:103]
	v_mfma_f32_16x16x32_bf16 v[92:95], v[146:149], v[206:209], v[92:95]
	v_mfma_f32_16x16x32_bf16 v[92:95], v[150:153], v[210:213], v[92:95]
	v_mfma_f32_16x16x32_bf16 v[84:87], v[154:157], v[206:209], v[84:87]
	v_mfma_f32_16x16x32_bf16 v[84:87], v[158:161], v[210:213], v[84:87]
	v_mfma_f32_16x16x32_bf16 v[76:79], v[146:149], v[214:217], v[76:79]
	v_mfma_f32_16x16x32_bf16 v[76:79], v[150:153], v[218:221], v[76:79]
	v_mfma_f32_16x16x32_bf16 v[68:71], v[154:157], v[214:217], v[68:71]
	v_mfma_f32_16x16x32_bf16 v[68:71], v[158:161], v[218:221], v[68:71]
	v_mfma_f32_16x16x32_bf16 v[120:123], v[162:165], v[190:193], v[120:123]
	v_mfma_f32_16x16x32_bf16 v[120:123], v[178:181], v[194:197], v[120:123]
	v_mfma_f32_16x16x32_bf16 v[112:115], v[182:185], v[190:193], v[112:115]
	v_mfma_f32_16x16x32_bf16 v[112:115], v[186:189], v[194:197], v[112:115]
	v_mfma_f32_16x16x32_bf16 v[104:107], v[162:165], v[198:201], v[104:107]
	v_mfma_f32_16x16x32_bf16 v[104:107], v[178:181], v[202:205], v[104:107]
	v_mfma_f32_16x16x32_bf16 v[96:99], v[182:185], v[198:201], v[96:99]
	v_mfma_f32_16x16x32_bf16 v[96:99], v[186:189], v[202:205], v[96:99]
	v_mfma_f32_16x16x32_bf16 v[88:91], v[162:165], v[206:209], v[88:91]
	v_mfma_f32_16x16x32_bf16 v[88:91], v[178:181], v[210:213], v[88:91]
	v_mfma_f32_16x16x32_bf16 v[80:83], v[182:185], v[206:209], v[80:83]
	v_mfma_f32_16x16x32_bf16 v[80:83], v[186:189], v[210:213], v[80:83]
	v_mfma_f32_16x16x32_bf16 v[72:75], v[162:165], v[214:217], v[72:75]
	v_mfma_f32_16x16x32_bf16 v[72:75], v[178:181], v[218:221], v[72:75]
	s_setprio 3
	s_barrier
	v_mfma_f32_16x16x32_bf16 v[64:67], v[182:185], v[214:217], v[64:67]
	v_mfma_f32_16x16x32_bf16 v[64:67], v[186:189], v[218:221], v[64:67]
	s_setprio 0
	s_add_i32 s67, s67, s16
	v_lshl_add_u64 v[166:167], v[166:167], 0, s[10:11]
	s_mov_b32 m0, s67
	ds_read_b128 v[190:193], v176 offset:49152
	ds_read_b128 v[194:197], v176 offset:50176
	ds_read_b128 v[198:201], v176 offset:51200
	ds_read_b128 v[202:205], v176 offset:52224
	ds_read_b128 v[206:209], v176 offset:53248
	ds_read_b128 v[210:213], v176 offset:54272
	ds_read_b128 v[214:217], v176 offset:55296
	ds_read_b128 v[218:221], v176 offset:56320
	global_load_lds_dwordx4 v[166:167], off
	s_add_i32 m0, s67, 0x2000
	s_add_u32 s68, s80, 0x40080
	v_lshl_add_u64 v[166:167], v[222:223], 0, s[10:11]
	s_addc_u32 s69, s81, 0
	s_add_i32 s67, s73, s16
	global_load_lds_dwordx4 v[166:167], off
	s_mov_b32 m0, s67
	v_lshl_add_u64 v[166:167], s[68:69], 0, v[132:133]
	global_load_lds_dwordx4 v[166:167], off
	s_add_i32 m0, s67, 0x2000
	v_lshl_add_u64 v[166:167], s[68:69], 0, v[128:129]
	global_load_lds_dwordx4 v[166:167], off
	s_mov_b32 m0, s23
	v_lshl_add_u64 v[166:167], v[224:225], 0, s[10:11]
	global_load_lds_dwordx4 v[166:167], off
	s_mov_b32 m0, s24
	v_lshl_add_u64 v[166:167], v[226:227], 0, s[10:11]
	global_load_lds_dwordx4 v[166:167], off
	s_waitcnt vmcnt(8) lgkmcnt(0)
	s_barrier
	v_mfma_f32_16x16x32_bf16 v[60:63], v[146:149], v[190:193], v[60:63]
	v_mfma_f32_16x16x32_bf16 v[60:63], v[150:153], v[194:197], v[60:63]
	v_mfma_f32_16x16x32_bf16 v[52:55], v[154:157], v[190:193], v[52:55]
	v_mfma_f32_16x16x32_bf16 v[52:55], v[158:161], v[194:197], v[52:55]
	v_mfma_f32_16x16x32_bf16 v[44:47], v[146:149], v[198:201], v[44:47]
	v_mfma_f32_16x16x32_bf16 v[44:47], v[150:153], v[202:205], v[44:47]
	v_mfma_f32_16x16x32_bf16 v[36:39], v[154:157], v[198:201], v[36:39]
	v_mfma_f32_16x16x32_bf16 v[36:39], v[158:161], v[202:205], v[36:39]
	v_mfma_f32_16x16x32_bf16 v[28:31], v[146:149], v[206:209], v[28:31]
	v_mfma_f32_16x16x32_bf16 v[28:31], v[150:153], v[210:213], v[28:31]
	v_mfma_f32_16x16x32_bf16 v[20:23], v[154:157], v[206:209], v[20:23]
	v_mfma_f32_16x16x32_bf16 v[20:23], v[158:161], v[210:213], v[20:23]
	v_mfma_f32_16x16x32_bf16 v[12:15], v[146:149], v[214:217], v[12:15]
	v_mfma_f32_16x16x32_bf16 v[12:15], v[150:153], v[218:221], v[12:15]
	v_mfma_f32_16x16x32_bf16 v[4:7], v[154:157], v[214:217], v[4:7]
	v_mfma_f32_16x16x32_bf16 v[4:7], v[158:161], v[218:221], v[4:7]
	v_mfma_f32_16x16x32_bf16 v[56:59], v[162:165], v[190:193], v[56:59]
	v_mfma_f32_16x16x32_bf16 v[56:59], v[178:181], v[194:197], v[56:59]
	v_mfma_f32_16x16x32_bf16 v[48:51], v[182:185], v[190:193], v[48:51]
	v_mfma_f32_16x16x32_bf16 v[48:51], v[186:189], v[194:197], v[48:51]
	v_mfma_f32_16x16x32_bf16 v[40:43], v[162:165], v[198:201], v[40:43]
	v_mfma_f32_16x16x32_bf16 v[40:43], v[178:181], v[202:205], v[40:43]
	v_mfma_f32_16x16x32_bf16 v[32:35], v[182:185], v[198:201], v[32:35]
	v_mfma_f32_16x16x32_bf16 v[32:35], v[186:189], v[202:205], v[32:35]
	v_mfma_f32_16x16x32_bf16 v[24:27], v[162:165], v[206:209], v[24:27]
	v_mfma_f32_16x16x32_bf16 v[24:27], v[178:181], v[210:213], v[24:27]
	v_mfma_f32_16x16x32_bf16 v[16:19], v[182:185], v[206:209], v[16:19]
	v_mfma_f32_16x16x32_bf16 v[16:19], v[186:189], v[210:213], v[16:19]
	v_mfma_f32_16x16x32_bf16 v[8:11], v[162:165], v[214:217], v[8:11]
	v_mfma_f32_16x16x32_bf16 v[8:11], v[178:181], v[218:221], v[8:11]
	s_setprio 3
	s_barrier
	v_mfma_f32_16x16x32_bf16 v[0:3], v[182:185], v[214:217], v[0:3]
	v_mfma_f32_16x16x32_bf16 v[0:3], v[186:189], v[218:221], v[0:3]
	s_setprio 0
	s_add_i32 s66, s66, 2
	s_add_u32 s78, s78, 0x100
	s_addc_u32 s79, s79, 0
	s_add_u32 s58, s58, 0x100
	s_addc_u32 s59, s59, 0
	s_cmp_gt_u32 s66, 13
	s_cbranch_scc0 .LBB0_1148
	s_branch .Lzskip_4

.LBB0_1299:
	ds_read_b128 v[120:123], v245
	ds_read_b128 v[124:127], v245 offset:1024
	ds_read_b128 v[128:131], v245 offset:2048
	ds_read_b128 v[132:135], v245 offset:3072
	ds_read_b128 v[144:147], v246
	ds_read_b128 v[148:151], v246 offset:1024
	ds_read_b128 v[152:155], v246 offset:2048
	ds_read_b128 v[156:159], v246 offset:3072
	s_add_u32 s66, s76, 0xfff50080
	s_addc_u32 s67, s77, -1
	s_cmp_eq_u32 s59, 40
	s_cselect_b32 s81, s9, s67
	s_cselect_b32 s80, s8, s66
	s_cselect_b32 s79, s53, s58
	s_cselect_b32 s78, s52, s55
	v_lshl_add_u64 v[204:205], s[76:77], 0, v[200:201]
	s_add_i32 m0, s16, 0xc000
	ds_read_b128 v[160:163], v247
	ds_read_b128 v[164:167], v247 offset:1024
	ds_read_b128 v[168:171], v247 offset:2048
	ds_read_b128 v[172:175], v247 offset:3072
	ds_read_b128 v[176:179], v247 offset:4096
	ds_read_b128 v[180:183], v247 offset:5120
	ds_read_b128 v[184:187], v247 offset:6144
	ds_read_b128 v[188:191], v247 offset:7168
	global_load_lds_dwordx4 v[204:205], off
	s_add_i32 m0, s16, 0xe000
	v_lshl_add_u64 v[204:205], s[76:77], 0, v[202:203]
	global_load_lds_dwordx4 v[204:205], off
	s_cmp_eq_u32 s59, -2
	s_waitcnt vmcnt(8) lgkmcnt(0)
	s_barrier
	s_cbranch_scc1 .Lzv_5_0
	v_mfma_f32_16x16x32_bf16 v[140:143], v[120:123], v[160:163], v[140:143]
	v_mfma_f32_16x16x32_bf16 v[140:143], v[124:127], v[164:167], v[140:143]
	v_mfma_f32_16x16x32_bf16 v[136:139], v[128:131], v[160:163], v[136:139]
	v_mfma_f32_16x16x32_bf16 v[136:139], v[132:135], v[164:167], v[136:139]
	v_mfma_f32_16x16x32_bf16 v[108:111], v[120:123], v[168:171], v[108:111]
	v_mfma_f32_16x16x32_bf16 v[108:111], v[124:127], v[172:175], v[108:111]
	v_mfma_f32_16x16x32_bf16 v[104:107], v[128:131], v[168:171], v[104:107]
	v_mfma_f32_16x16x32_bf16 v[104:107], v[132:135], v[172:175], v[104:107]
	v_mfma_f32_16x16x32_bf16 v[92:95], v[120:123], v[176:179], v[92:95]
	v_mfma_f32_16x16x32_bf16 v[92:95], v[124:127], v[180:183], v[92:95]
	v_mfma_f32_16x16x32_bf16 v[88:91], v[128:131], v[176:179], v[88:91]
	v_mfma_f32_16x16x32_bf16 v[88:91], v[132:135], v[180:183], v[88:91]
	v_mfma_f32_16x16x32_bf16 v[76:79], v[120:123], v[184:187], v[76:79]
	v_mfma_f32_16x16x32_bf16 v[76:79], v[124:127], v[188:191], v[76:79]
	v_mfma_f32_16x16x32_bf16 v[72:75], v[128:131], v[184:187], v[72:75]
	v_mfma_f32_16x16x32_bf16 v[72:75], v[132:135], v[188:191], v[72:75]
	v_mfma_f32_16x16x32_bf16 v[116:119], v[144:147], v[160:163], v[116:119]
	v_mfma_f32_16x16x32_bf16 v[116:119], v[148:151], v[164:167], v[116:119]
	v_mfma_f32_16x16x32_bf16 v[112:115], v[152:155], v[160:163], v[112:115]
	v_mfma_f32_16x16x32_bf16 v[112:115], v[156:159], v[164:167], v[112:115]
	v_mfma_f32_16x16x32_bf16 v[100:103], v[144:147], v[168:171], v[100:103]
	v_mfma_f32_16x16x32_bf16 v[100:103], v[148:151], v[172:175], v[100:103]
	v_mfma_f32_16x16x32_bf16 v[96:99], v[152:155], v[168:171], v[96:99]
	v_mfma_f32_16x16x32_bf16 v[96:99], v[156:159], v[172:175], v[96:99]
	v_mfma_f32_16x16x32_bf16 v[84:87], v[144:147], v[176:179], v[84:87]
	v_mfma_f32_16x16x32_bf16 v[84:87], v[148:151], v[180:183], v[84:87]
	v_mfma_f32_16x16x32_bf16 v[80:83], v[152:155], v[176:179], v[80:83]
	v_mfma_f32_16x16x32_bf16 v[80:83], v[156:159], v[180:183], v[80:83]
	v_mfma_f32_16x16x32_bf16 v[68:71], v[144:147], v[184:187], v[68:71]
	v_mfma_f32_16x16x32_bf16 v[68:71], v[148:151], v[188:191], v[68:71]
	s_setprio 3
	s_barrier
	v_mfma_f32_16x16x32_bf16 v[64:67], v[152:155], v[184:187], v[64:67]
	v_mfma_f32_16x16x32_bf16 v[64:67], v[156:159], v[188:191], v[64:67]
	s_setprio 0
.Lzj_5_0:
	s_add_i32 s66, s26, s15
	v_lshl_add_u64 v[204:205], s[78:79], 0, v[194:195]
	s_mov_b32 m0, s66
	ds_read_b128 v[160:163], v247 offset:16384
	ds_read_b128 v[164:167], v247 offset:17408
	ds_read_b128 v[168:171], v247 offset:18432
	ds_read_b128 v[172:175], v247 offset:19456
	ds_read_b128 v[176:179], v247 offset:20480
	ds_read_b128 v[180:183], v247 offset:21504
	ds_read_b128 v[184:187], v247 offset:22528
	ds_read_b128 v[188:191], v247 offset:23552
	global_load_lds_dwordx4 v[204:205], off
	s_add_i32 m0, s66, 0x2000
	s_add_u32 s66, s78, 0xb0000
	v_lshl_add_u64 v[206:207], s[78:79], 0, v[198:199]
	s_addc_u32 s67, s79, 0
	s_add_i32 s68, s27, s15
	global_load_lds_dwordx4 v[206:207], off
	v_lshl_add_u64 v[208:209], s[66:67], 0, v[194:195]
	s_mov_b32 m0, s68
	global_load_lds_dwordx4 v[208:209], off
	s_add_i32 m0, s68, 0x2000
	v_lshl_add_u64 v[208:209], s[66:67], 0, v[198:199]
	global_load_lds_dwordx4 v[208:209], off
	s_mov_b32 m0, s16
	v_lshl_add_u64 v[208:209], s[80:81], 0, v[192:193]
	global_load_lds_dwordx4 v[208:209], off
	s_mov_b32 m0, s17
	v_lshl_add_u64 v[210:211], s[80:81], 0, v[196:197]
	global_load_lds_dwordx4 v[210:211], off
	s_cmp_eq_u32 s59, -2
	s_waitcnt vmcnt(8) lgkmcnt(0)
	s_barrier
	s_cbranch_scc1 .Lzv_5_1
	v_mfma_f32_16x16x32_bf16 v[60:63], v[120:123], v[160:163], v[60:63]
	v_mfma_f32_16x16x32_bf16 v[60:63], v[124:127], v[164:167], v[60:63]
	v_mfma_f32_16x16x32_bf16 v[56:59], v[128:131], v[160:163], v[56:59]
	v_mfma_f32_16x16x32_bf16 v[56:59], v[132:135], v[164:167], v[56:59]
	v_mfma_f32_16x16x32_bf16 v[44:47], v[120:123], v[168:171], v[44:47]
	v_mfma_f32_16x16x32_bf16 v[44:47], v[124:127], v[172:175], v[44:47]
	v_mfma_f32_16x16x32_bf16 v[40:43], v[128:131], v[168:171], v[40:43]
	v_mfma_f32_16x16x32_bf16 v[40:43], v[132:135], v[172:175], v[40:43]
	v_mfma_f32_16x16x32_bf16 v[28:31], v[120:123], v[176:179], v[28:31]
	v_mfma_f32_16x16x32_bf16 v[28:31], v[124:127], v[180:183], v[28:31]
	v_mfma_f32_16x16x32_bf16 v[24:27], v[128:131], v[176:179], v[24:27]
	v_mfma_f32_16x16x32_bf16 v[24:27], v[132:135], v[180:183], v[24:27]
	v_mfma_f32_16x16x32_bf16 v[12:15], v[120:123], v[184:187], v[12:15]
	v_mfma_f32_16x16x32_bf16 v[12:15], v[124:127], v[188:191], v[12:15]
	v_mfma_f32_16x16x32_bf16 v[8:11], v[128:131], v[184:187], v[8:11]
	v_mfma_f32_16x16x32_bf16 v[8:11], v[132:135], v[188:191], v[8:11]
	v_mfma_f32_16x16x32_bf16 v[52:55], v[144:147], v[160:163], v[52:55]
	v_mfma_f32_16x16x32_bf16 v[52:55], v[148:151], v[164:167], v[52:55]
	v_mfma_f32_16x16x32_bf16 v[48:51], v[152:155], v[160:163], v[48:51]
	v_mfma_f32_16x16x32_bf16 v[48:51], v[156:159], v[164:167], v[48:51]
	v_mfma_f32_16x16x32_bf16 v[36:39], v[144:147], v[168:171], v[36:39]
	v_mfma_f32_16x16x32_bf16 v[36:39], v[148:151], v[172:175], v[36:39]
	v_mfma_f32_16x16x32_bf16 v[32:35], v[152:155], v[168:171], v[32:35]
	v_mfma_f32_16x16x32_bf16 v[32:35], v[156:159], v[172:175], v[32:35]
	v_mfma_f32_16x16x32_bf16 v[20:23], v[144:147], v[176:179], v[20:23]
	v_mfma_f32_16x16x32_bf16 v[20:23], v[148:151], v[180:183], v[20:23]
	v_mfma_f32_16x16x32_bf16 v[16:19], v[152:155], v[176:179], v[16:19]
	v_mfma_f32_16x16x32_bf16 v[16:19], v[156:159], v[180:183], v[16:19]
	v_mfma_f32_16x16x32_bf16 v[4:7], v[144:147], v[184:187], v[4:7]
	v_mfma_f32_16x16x32_bf16 v[4:7], v[148:151], v[188:191], v[4:7]
	s_setprio 3
	s_barrier
	v_mfma_f32_16x16x32_bf16 v[0:3], v[152:155], v[184:187], v[0:3]
	v_mfma_f32_16x16x32_bf16 v[0:3], v[156:159], v[188:191], v[0:3]
	s_setprio 0
.Lzj_5_1:
	s_add_i32 s68, 0, 0x18000
	s_add_i32 s69, 0, 0x1c000
	v_add_u32_e32 v132, s68, v243
	v_add_u32_e32 v156, s69, v243
	ds_read_b128 v[120:123], v132
	ds_read_b128 v[124:127], v132 offset:1024
	ds_read_b128 v[128:131], v132 offset:2048
	ds_read_b128 v[132:135], v132 offset:3072
	ds_read_b128 v[144:147], v156
	ds_read_b128 v[148:151], v156 offset:1024
	ds_read_b128 v[152:155], v156 offset:2048
	ds_read_b128 v[156:159], v156 offset:3072
	s_add_u32 s66, s80, 0xb0000
	s_addc_u32 s67, s81, 0
	s_mov_b32 m0, s18
	v_lshl_add_u64 v[212:213], s[66:67], 0, v[192:193]
	ds_read_b128 v[160:163], v247 offset:32768
	ds_read_b128 v[164:167], v247 offset:33792
	ds_read_b128 v[168:171], v247 offset:34816
	ds_read_b128 v[172:175], v247 offset:35840
	ds_read_b128 v[176:179], v247 offset:36864
	ds_read_b128 v[180:183], v247 offset:37888
	ds_read_b128 v[184:187], v247 offset:38912
	ds_read_b128 v[188:191], v247 offset:39936
	global_load_lds_dwordx4 v[212:213], off
	s_mov_b32 m0, s19
	v_lshl_add_u64 v[212:213], s[66:67], 0, v[196:197]
	global_load_lds_dwordx4 v[212:213], off
	s_waitcnt vmcnt(8) lgkmcnt(0)
	s_barrier
	v_mfma_f32_16x16x32_bf16 v[140:143], v[120:123], v[160:163], v[140:143]
	v_mfma_f32_16x16x32_bf16 v[140:143], v[124:127], v[164:167], v[140:143]
	v_mfma_f32_16x16x32_bf16 v[136:139], v[128:131], v[160:163], v[136:139]
	v_mfma_f32_16x16x32_bf16 v[136:139], v[132:135], v[164:167], v[136:139]
	v_mfma_f32_16x16x32_bf16 v[108:111], v[120:123], v[168:171], v[108:111]
	v_mfma_f32_16x16x32_bf16 v[108:111], v[124:127], v[172:175], v[108:111]
	v_mfma_f32_16x16x32_bf16 v[104:107], v[128:131], v[168:171], v[104:107]
	v_mfma_f32_16x16x32_bf16 v[104:107], v[132:135], v[172:175], v[104:107]
	v_mfma_f32_16x16x32_bf16 v[92:95], v[120:123], v[176:179], v[92:95]
	v_mfma_f32_16x16x32_bf16 v[92:95], v[124:127], v[180:183], v[92:95]
	v_mfma_f32_16x16x32_bf16 v[88:91], v[128:131], v[176:179], v[88:91]
	v_mfma_f32_16x16x32_bf16 v[88:91], v[132:135], v[180:183], v[88:91]
	v_mfma_f32_16x16x32_bf16 v[76:79], v[120:123], v[184:187], v[76:79]
	v_mfma_f32_16x16x32_bf16 v[76:79], v[124:127], v[188:191], v[76:79]
	v_mfma_f32_16x16x32_bf16 v[72:75], v[128:131], v[184:187], v[72:75]
	v_mfma_f32_16x16x32_bf16 v[72:75], v[132:135], v[188:191], v[72:75]
	v_mfma_f32_16x16x32_bf16 v[116:119], v[144:147], v[160:163], v[116:119]
	v_mfma_f32_16x16x32_bf16 v[116:119], v[148:151], v[164:167], v[116:119]
	v_mfma_f32_16x16x32_bf16 v[112:115], v[152:155], v[160:163], v[112:115]
	v_mfma_f32_16x16x32_bf16 v[112:115], v[156:159], v[164:167], v[112:115]
	v_mfma_f32_16x16x32_bf16 v[100:103], v[144:147], v[168:171], v[100:103]
	v_mfma_f32_16x16x32_bf16 v[100:103], v[148:151], v[172:175], v[100:103]
	v_mfma_f32_16x16x32_bf16 v[96:99], v[152:155], v[168:171], v[96:99]
	v_mfma_f32_16x16x32_bf16 v[96:99], v[156:159], v[172:175], v[96:99]
	v_mfma_f32_16x16x32_bf16 v[84:87], v[144:147], v[176:179], v[84:87]
	v_mfma_f32_16x16x32_bf16 v[84:87], v[148:151], v[180:183], v[84:87]
	v_mfma_f32_16x16x32_bf16 v[80:83], v[152:155], v[176:179], v[80:83]
	v_mfma_f32_16x16x32_bf16 v[80:83], v[156:159], v[180:183], v[80:83]
	v_mfma_f32_16x16x32_bf16 v[68:71], v[144:147], v[184:187], v[68:71]
	v_mfma_f32_16x16x32_bf16 v[68:71], v[148:151], v[188:191], v[68:71]
	s_setprio 3
	s_barrier
	v_mfma_f32_16x16x32_bf16 v[64:67], v[152:155], v[184:187], v[64:67]
	v_mfma_f32_16x16x32_bf16 v[64:67], v[156:159], v[188:191], v[64:67]
	s_setprio 0
	s_add_i32 s66, s68, s15
	v_lshl_add_u64 v[204:205], v[204:205], 0, s[48:49]
	s_mov_b32 m0, s66
	ds_read_b128 v[160:163], v247 offset:49152
	ds_read_b128 v[164:167], v247 offset:50176
	ds_read_b128 v[168:171], v247 offset:51200
	ds_read_b128 v[172:175], v247 offset:52224
	ds_read_b128 v[176:179], v247 offset:53248
	ds_read_b128 v[180:183], v247 offset:54272
	ds_read_b128 v[184:187], v247 offset:55296
	ds_read_b128 v[188:191], v247 offset:56320
	global_load_lds_dwordx4 v[204:205], off
	s_add_i32 m0, s66, 0x2000
	s_add_u32 s66, s78, 0xb0080
	v_lshl_add_u64 v[204:205], v[206:207], 0, s[48:49]
	s_addc_u32 s67, s79, 0
	s_add_i32 s68, s69, s15
	global_load_lds_dwordx4 v[204:205], off
	s_mov_b32 m0, s68
	v_lshl_add_u64 v[204:205], s[66:67], 0, v[194:195]
	global_load_lds_dwordx4 v[204:205], off
	s_add_i32 m0, s68, 0x2000
	v_lshl_add_u64 v[204:205], s[66:67], 0, v[198:199]
	global_load_lds_dwordx4 v[204:205], off
	s_mov_b32 m0, s21
	v_lshl_add_u64 v[204:205], v[208:209], 0, s[48:49]
	global_load_lds_dwordx4 v[204:205], off
	s_mov_b32 m0, s22
	v_lshl_add_u64 v[204:205], v[210:211], 0, s[48:49]
	global_load_lds_dwordx4 v[204:205], off
	s_waitcnt vmcnt(8) lgkmcnt(0)
	s_barrier
	v_mfma_f32_16x16x32_bf16 v[60:63], v[120:123], v[160:163], v[60:63]
	v_mfma_f32_16x16x32_bf16 v[60:63], v[124:127], v[164:167], v[60:63]
	v_mfma_f32_16x16x32_bf16 v[56:59], v[128:131], v[160:163], v[56:59]
	v_mfma_f32_16x16x32_bf16 v[56:59], v[132:135], v[164:167], v[56:59]
	v_mfma_f32_16x16x32_bf16 v[44:47], v[120:123], v[168:171], v[44:47]
	v_mfma_f32_16x16x32_bf16 v[44:47], v[124:127], v[172:175], v[44:47]
	v_mfma_f32_16x16x32_bf16 v[40:43], v[128:131], v[168:171], v[40:43]
	v_mfma_f32_16x16x32_bf16 v[40:43], v[132:135], v[172:175], v[40:43]
	v_mfma_f32_16x16x32_bf16 v[28:31], v[120:123], v[176:179], v[28:31]
	v_mfma_f32_16x16x32_bf16 v[28:31], v[124:127], v[180:183], v[28:31]
	v_mfma_f32_16x16x32_bf16 v[24:27], v[128:131], v[176:179], v[24:27]
	v_mfma_f32_16x16x32_bf16 v[24:27], v[132:135], v[180:183], v[24:27]
	v_mfma_f32_16x16x32_bf16 v[12:15], v[120:123], v[184:187], v[12:15]
	v_mfma_f32_16x16x32_bf16 v[12:15], v[124:127], v[188:191], v[12:15]
	v_mfma_f32_16x16x32_bf16 v[8:11], v[128:131], v[184:187], v[8:11]
	v_mfma_f32_16x16x32_bf16 v[8:11], v[132:135], v[188:191], v[8:11]
	v_mfma_f32_16x16x32_bf16 v[52:55], v[144:147], v[160:163], v[52:55]
	v_mfma_f32_16x16x32_bf16 v[52:55], v[148:151], v[164:167], v[52:55]
	v_mfma_f32_16x16x32_bf16 v[48:51], v[152:155], v[160:163], v[48:51]
	v_mfma_f32_16x16x32_bf16 v[48:51], v[156:159], v[164:167], v[48:51]
	v_mfma_f32_16x16x32_bf16 v[36:39], v[144:147], v[168:171], v[36:39]
	v_mfma_f32_16x16x32_bf16 v[36:39], v[148:151], v[172:175], v[36:39]
	v_mfma_f32_16x16x32_bf16 v[32:35], v[152:155], v[168:171], v[32:35]
	v_mfma_f32_16x16x32_bf16 v[32:35], v[156:159], v[172:175], v[32:35]
	v_mfma_f32_16x16x32_bf16 v[20:23], v[144:147], v[176:179], v[20:23]
	v_mfma_f32_16x16x32_bf16 v[20:23], v[148:151], v[180:183], v[20:23]
	v_mfma_f32_16x16x32_bf16 v[16:19], v[152:155], v[176:179], v[16:19]
	v_mfma_f32_16x16x32_bf16 v[16:19], v[156:159], v[180:183], v[16:19]
	v_mfma_f32_16x16x32_bf16 v[4:7], v[144:147], v[184:187], v[4:7]
	v_mfma_f32_16x16x32_bf16 v[4:7], v[148:151], v[188:191], v[4:7]
	s_setprio 3
	s_barrier
	v_mfma_f32_16x16x32_bf16 v[0:3], v[152:155], v[184:187], v[0:3]
	v_mfma_f32_16x16x32_bf16 v[0:3], v[156:159], v[188:191], v[0:3]
	s_setprio 0
	s_add_i32 s59, s59, 2
	s_add_u32 s76, s76, 0x100
	s_addc_u32 s77, s77, 0
	s_add_u32 s55, s55, 0x100
	s_addc_u32 s58, s58, 0
	s_cmp_gt_u32 s59, 41
	s_cbranch_scc0 .LBB0_1299
	s_branch .Lzskip_5

.LBB0_1760:
	ds_read_b128 v[128:131], v181
	ds_read_b128 v[132:135], v181 offset:1024
	ds_read_b128 v[136:139], v181 offset:2048
	ds_read_b128 v[160:163], v181 offset:3072
	ds_read_b128 v[164:167], v182
	ds_read_b128 v[168:171], v182 offset:1024
	ds_read_b128 v[186:189], v182 offset:2048
	ds_read_b128 v[190:193], v182 offset:3072
	s_add_u32 s69, s78, 0xfffc0080
	s_addc_u32 s73, s79, -1
	s_cmp_eq_u32 s68, 12
	s_cselect_b32 s83, s49, s73
	s_cselect_b32 s82, s54, s69
	s_cselect_b32 s81, s47, s67
	s_cselect_b32 s80, s55, s66
	v_lshl_add_u64 v[172:173], s[78:79], 0, v[152:153]
	s_add_i32 m0, s18, 0xc000
	ds_read_b128 v[194:197], v183
	ds_read_b128 v[198:201], v183 offset:1024
	ds_read_b128 v[202:205], v183 offset:2048
	ds_read_b128 v[206:209], v183 offset:3072
	ds_read_b128 v[210:213], v183 offset:4096
	ds_read_b128 v[214:217], v183 offset:5120
	ds_read_b128 v[218:221], v183 offset:6144
	ds_read_b128 v[222:225], v183 offset:7168
	global_load_lds_dwordx4 v[172:173], off
	s_add_i32 m0, s18, 0xe000
	v_lshl_add_u64 v[172:173], s[78:79], 0, v[154:155]
	global_load_lds_dwordx4 v[172:173], off
	s_cmp_eq_u32 s68, -2
	s_waitcnt vmcnt(8) lgkmcnt(0)
	s_barrier
	s_cbranch_scc1 .Lzv_8_0
	v_mfma_f32_16x16x32_bf16 v[124:127], v[128:131], v[194:197], v[124:127]
	v_mfma_f32_16x16x32_bf16 v[124:127], v[132:135], v[198:201], v[124:127]
	v_mfma_f32_16x16x32_bf16 v[120:123], v[136:139], v[194:197], v[120:123]
	v_mfma_f32_16x16x32_bf16 v[120:123], v[160:163], v[198:201], v[120:123]
	v_mfma_f32_16x16x32_bf16 v[108:111], v[128:131], v[202:205], v[108:111]
	v_mfma_f32_16x16x32_bf16 v[108:111], v[132:135], v[206:209], v[108:111]
	v_mfma_f32_16x16x32_bf16 v[104:107], v[136:139], v[202:205], v[104:107]
	v_mfma_f32_16x16x32_bf16 v[104:107], v[160:163], v[206:209], v[104:107]
	v_mfma_f32_16x16x32_bf16 v[92:95], v[128:131], v[210:213], v[92:95]
	v_mfma_f32_16x16x32_bf16 v[92:95], v[132:135], v[214:217], v[92:95]
	v_mfma_f32_16x16x32_bf16 v[88:91], v[136:139], v[210:213], v[88:91]
	v_mfma_f32_16x16x32_bf16 v[88:91], v[160:163], v[214:217], v[88:91]
	v_mfma_f32_16x16x32_bf16 v[76:79], v[128:131], v[218:221], v[76:79]
	v_mfma_f32_16x16x32_bf16 v[76:79], v[132:135], v[222:225], v[76:79]
	v_mfma_f32_16x16x32_bf16 v[72:75], v[136:139], v[218:221], v[72:75]
	v_mfma_f32_16x16x32_bf16 v[72:75], v[160:163], v[222:225], v[72:75]
	v_mfma_f32_16x16x32_bf16 v[116:119], v[164:167], v[194:197], v[116:119]
	v_mfma_f32_16x16x32_bf16 v[116:119], v[168:171], v[198:201], v[116:119]
	v_mfma_f32_16x16x32_bf16 v[112:115], v[186:189], v[194:197], v[112:115]
	v_mfma_f32_16x16x32_bf16 v[112:115], v[190:193], v[198:201], v[112:115]
	v_mfma_f32_16x16x32_bf16 v[100:103], v[164:167], v[202:205], v[100:103]
	v_mfma_f32_16x16x32_bf16 v[100:103], v[168:171], v[206:209], v[100:103]
	v_mfma_f32_16x16x32_bf16 v[96:99], v[186:189], v[202:205], v[96:99]
	v_mfma_f32_16x16x32_bf16 v[96:99], v[190:193], v[206:209], v[96:99]
	v_mfma_f32_16x16x32_bf16 v[84:87], v[164:167], v[210:213], v[84:87]
	v_mfma_f32_16x16x32_bf16 v[84:87], v[168:171], v[214:217], v[84:87]
	v_mfma_f32_16x16x32_bf16 v[80:83], v[186:189], v[210:213], v[80:83]
	v_mfma_f32_16x16x32_bf16 v[80:83], v[190:193], v[214:217], v[80:83]
	v_mfma_f32_16x16x32_bf16 v[68:71], v[164:167], v[218:221], v[68:71]
	v_mfma_f32_16x16x32_bf16 v[68:71], v[168:171], v[222:225], v[68:71]
	s_setprio 3
	s_barrier
	v_mfma_f32_16x16x32_bf16 v[64:67], v[186:189], v[218:221], v[64:67]
	v_mfma_f32_16x16x32_bf16 v[64:67], v[190:193], v[222:225], v[64:67]
	s_setprio 0
.Lzj_8_0:
	s_add_i32 s69, s25, s17
	v_lshl_add_u64 v[172:173], s[80:81], 0, v[142:143]
	s_mov_b32 m0, s69
	ds_read_b128 v[194:197], v183 offset:16384
	ds_read_b128 v[198:201], v183 offset:17408
	ds_read_b128 v[202:205], v183 offset:18432
	ds_read_b128 v[206:209], v183 offset:19456
	ds_read_b128 v[210:213], v183 offset:20480
	ds_read_b128 v[214:217], v183 offset:21504
	ds_read_b128 v[218:221], v183 offset:22528
	ds_read_b128 v[222:225], v183 offset:23552
	global_load_lds_dwordx4 v[172:173], off
	s_add_i32 m0, s69, 0x2000
	s_add_u32 s84, s80, 0x40000
	v_lshl_add_u64 v[226:227], s[80:81], 0, v[146:147]
	s_addc_u32 s85, s81, 0
	s_add_i32 s69, s26, s17
	global_load_lds_dwordx4 v[226:227], off
	v_lshl_add_u64 v[228:229], s[84:85], 0, v[142:143]
	s_mov_b32 m0, s69
	global_load_lds_dwordx4 v[228:229], off
	s_add_i32 m0, s69, 0x2000
	v_lshl_add_u64 v[228:229], s[84:85], 0, v[146:147]
	global_load_lds_dwordx4 v[228:229], off
	s_mov_b32 m0, s18
	v_lshl_add_u64 v[228:229], s[82:83], 0, v[140:141]
	global_load_lds_dwordx4 v[228:229], off
	s_mov_b32 m0, s19
	v_lshl_add_u64 v[230:231], s[82:83], 0, v[144:145]
	global_load_lds_dwordx4 v[230:231], off
	s_cmp_eq_u32 s68, -2
	s_waitcnt vmcnt(8) lgkmcnt(0)
	s_barrier
	s_cbranch_scc1 .Lzv_8_1
	v_mfma_f32_16x16x32_bf16 v[60:63], v[128:131], v[194:197], v[60:63]
	v_mfma_f32_16x16x32_bf16 v[60:63], v[132:135], v[198:201], v[60:63]
	v_mfma_f32_16x16x32_bf16 v[56:59], v[136:139], v[194:197], v[56:59]
	v_mfma_f32_16x16x32_bf16 v[56:59], v[160:163], v[198:201], v[56:59]
	v_mfma_f32_16x16x32_bf16 v[44:47], v[128:131], v[202:205], v[44:47]
	v_mfma_f32_16x16x32_bf16 v[44:47], v[132:135], v[206:209], v[44:47]
	v_mfma_f32_16x16x32_bf16 v[40:43], v[136:139], v[202:205], v[40:43]
	v_mfma_f32_16x16x32_bf16 v[40:43], v[160:163], v[206:209], v[40:43]
	v_mfma_f32_16x16x32_bf16 v[28:31], v[128:131], v[210:213], v[28:31]
	v_mfma_f32_16x16x32_bf16 v[28:31], v[132:135], v[214:217], v[28:31]
	v_mfma_f32_16x16x32_bf16 v[24:27], v[136:139], v[210:213], v[24:27]
	v_mfma_f32_16x16x32_bf16 v[24:27], v[160:163], v[214:217], v[24:27]
	v_mfma_f32_16x16x32_bf16 v[12:15], v[128:131], v[218:221], v[12:15]
	v_mfma_f32_16x16x32_bf16 v[12:15], v[132:135], v[222:225], v[12:15]
	v_mfma_f32_16x16x32_bf16 v[8:11], v[136:139], v[218:221], v[8:11]
	v_mfma_f32_16x16x32_bf16 v[8:11], v[160:163], v[222:225], v[8:11]
	v_mfma_f32_16x16x32_bf16 v[52:55], v[164:167], v[194:197], v[52:55]
	v_mfma_f32_16x16x32_bf16 v[52:55], v[168:171], v[198:201], v[52:55]
	v_mfma_f32_16x16x32_bf16 v[48:51], v[186:189], v[194:197], v[48:51]
	v_mfma_f32_16x16x32_bf16 v[48:51], v[190:193], v[198:201], v[48:51]
	v_mfma_f32_16x16x32_bf16 v[36:39], v[164:167], v[202:205], v[36:39]
	v_mfma_f32_16x16x32_bf16 v[36:39], v[168:171], v[206:209], v[36:39]
	v_mfma_f32_16x16x32_bf16 v[32:35], v[186:189], v[202:205], v[32:35]
	v_mfma_f32_16x16x32_bf16 v[32:35], v[190:193], v[206:209], v[32:35]
	v_mfma_f32_16x16x32_bf16 v[20:23], v[164:167], v[210:213], v[20:23]
	v_mfma_f32_16x16x32_bf16 v[20:23], v[168:171], v[214:217], v[20:23]
	v_mfma_f32_16x16x32_bf16 v[16:19], v[186:189], v[210:213], v[16:19]
	v_mfma_f32_16x16x32_bf16 v[16:19], v[190:193], v[214:217], v[16:19]
	v_mfma_f32_16x16x32_bf16 v[4:7], v[164:167], v[218:221], v[4:7]
	v_mfma_f32_16x16x32_bf16 v[4:7], v[168:171], v[222:225], v[4:7]
	s_setprio 3
	s_barrier
	v_mfma_f32_16x16x32_bf16 v[0:3], v[186:189], v[218:221], v[0:3]
	v_mfma_f32_16x16x32_bf16 v[0:3], v[190:193], v[222:225], v[0:3]
	s_setprio 0
.Lzj_8_1:
	s_add_i32 s69, 0, 0x18000
	v_add_u32_e32 v148, s69, v177
	s_add_i32 s73, 0, 0x1c000
	ds_read_b128 v[128:131], v148
	ds_read_b128 v[132:135], v148 offset:1024
	ds_read_b128 v[136:139], v148 offset:2048
	ds_read_b128 v[160:163], v148 offset:3072
	v_add_u32_e32 v148, s73, v177
	ds_read_b128 v[164:167], v148
	ds_read_b128 v[168:171], v148 offset:1024
	ds_read_b128 v[186:189], v148 offset:2048
	ds_read_b128 v[190:193], v148 offset:3072
	s_add_u32 s82, s82, 0x40000
	s_addc_u32 s83, s83, 0
	s_mov_b32 m0, s20
	v_lshl_add_u64 v[232:233], s[82:83], 0, v[140:141]
	ds_read_b128 v[194:197], v183 offset:32768
	ds_read_b128 v[198:201], v183 offset:33792
	ds_read_b128 v[202:205], v183 offset:34816
	ds_read_b128 v[206:209], v183 offset:35840
	ds_read_b128 v[210:213], v183 offset:36864
	ds_read_b128 v[214:217], v183 offset:37888
	ds_read_b128 v[218:221], v183 offset:38912
	ds_read_b128 v[222:225], v183 offset:39936
	global_load_lds_dwordx4 v[232:233], off
	s_mov_b32 m0, s21
	v_lshl_add_u64 v[232:233], s[82:83], 0, v[144:145]
	global_load_lds_dwordx4 v[232:233], off
	s_waitcnt vmcnt(8) lgkmcnt(0)
	s_barrier
	v_mfma_f32_16x16x32_bf16 v[124:127], v[128:131], v[194:197], v[124:127]
	v_mfma_f32_16x16x32_bf16 v[124:127], v[132:135], v[198:201], v[124:127]
	v_mfma_f32_16x16x32_bf16 v[120:123], v[136:139], v[194:197], v[120:123]
	v_mfma_f32_16x16x32_bf16 v[120:123], v[160:163], v[198:201], v[120:123]
	v_mfma_f32_16x16x32_bf16 v[108:111], v[128:131], v[202:205], v[108:111]
	v_mfma_f32_16x16x32_bf16 v[108:111], v[132:135], v[206:209], v[108:111]
	v_mfma_f32_16x16x32_bf16 v[104:107], v[136:139], v[202:205], v[104:107]
	v_mfma_f32_16x16x32_bf16 v[104:107], v[160:163], v[206:209], v[104:107]
	v_mfma_f32_16x16x32_bf16 v[92:95], v[128:131], v[210:213], v[92:95]
	v_mfma_f32_16x16x32_bf16 v[92:95], v[132:135], v[214:217], v[92:95]
	v_mfma_f32_16x16x32_bf16 v[88:91], v[136:139], v[210:213], v[88:91]
	v_mfma_f32_16x16x32_bf16 v[88:91], v[160:163], v[214:217], v[88:91]
	v_mfma_f32_16x16x32_bf16 v[76:79], v[128:131], v[218:221], v[76:79]
	v_mfma_f32_16x16x32_bf16 v[76:79], v[132:135], v[222:225], v[76:79]
	v_mfma_f32_16x16x32_bf16 v[72:75], v[136:139], v[218:221], v[72:75]
	v_mfma_f32_16x16x32_bf16 v[72:75], v[160:163], v[222:225], v[72:75]
	v_mfma_f32_16x16x32_bf16 v[116:119], v[164:167], v[194:197], v[116:119]
	v_mfma_f32_16x16x32_bf16 v[116:119], v[168:171], v[198:201], v[116:119]
	v_mfma_f32_16x16x32_bf16 v[112:115], v[186:189], v[194:197], v[112:115]
	v_mfma_f32_16x16x32_bf16 v[112:115], v[190:193], v[198:201], v[112:115]
	v_mfma_f32_16x16x32_bf16 v[100:103], v[164:167], v[202:205], v[100:103]
	v_mfma_f32_16x16x32_bf16 v[100:103], v[168:171], v[206:209], v[100:103]
	v_mfma_f32_16x16x32_bf16 v[96:99], v[186:189], v[202:205], v[96:99]
	v_mfma_f32_16x16x32_bf16 v[96:99], v[190:193], v[206:209], v[96:99]
	v_mfma_f32_16x16x32_bf16 v[84:87], v[164:167], v[210:213], v[84:87]
	v_mfma_f32_16x16x32_bf16 v[84:87], v[168:171], v[214:217], v[84:87]
	v_mfma_f32_16x16x32_bf16 v[80:83], v[186:189], v[210:213], v[80:83]
	v_mfma_f32_16x16x32_bf16 v[80:83], v[190:193], v[214:217], v[80:83]
	v_mfma_f32_16x16x32_bf16 v[68:71], v[164:167], v[218:221], v[68:71]
	v_mfma_f32_16x16x32_bf16 v[68:71], v[168:171], v[222:225], v[68:71]
	s_setprio 3
	s_barrier
	v_mfma_f32_16x16x32_bf16 v[64:67], v[186:189], v[218:221], v[64:67]
	v_mfma_f32_16x16x32_bf16 v[64:67], v[190:193], v[222:225], v[64:67]
	s_setprio 0
	s_add_i32 s69, s69, s17
	v_lshl_add_u64 v[172:173], v[172:173], 0, s[10:11]
	s_mov_b32 m0, s69
	ds_read_b128 v[194:197], v183 offset:49152
	ds_read_b128 v[198:201], v183 offset:50176
	ds_read_b128 v[202:205], v183 offset:51200
	ds_read_b128 v[206:209], v183 offset:52224
	ds_read_b128 v[210:213], v183 offset:53248
	ds_read_b128 v[214:217], v183 offset:54272
	ds_read_b128 v[218:221], v183 offset:55296
	ds_read_b128 v[222:225], v183 offset:56320
	global_load_lds_dwordx4 v[172:173], off
	s_add_i32 m0, s69, 0x2000
	s_add_u32 s80, s80, 0x40080
	v_lshl_add_u64 v[172:173], v[226:227], 0, s[10:11]
	s_addc_u32 s81, s81, 0
	s_add_i32 s69, s73, s17
	global_load_lds_dwordx4 v[172:173], off
	s_mov_b32 m0, s69
	v_lshl_add_u64 v[172:173], s[80:81], 0, v[142:143]
	global_load_lds_dwordx4 v[172:173], off
	s_add_i32 m0, s69, 0x2000
	v_lshl_add_u64 v[172:173], s[80:81], 0, v[146:147]
	global_load_lds_dwordx4 v[172:173], off
	s_mov_b32 m0, s23
	v_lshl_add_u64 v[172:173], v[228:229], 0, s[10:11]
	global_load_lds_dwordx4 v[172:173], off
	s_mov_b32 m0, s24
	v_lshl_add_u64 v[172:173], v[230:231], 0, s[10:11]
	global_load_lds_dwordx4 v[172:173], off
	s_waitcnt vmcnt(8) lgkmcnt(0)
	s_barrier
	v_mfma_f32_16x16x32_bf16 v[60:63], v[128:131], v[194:197], v[60:63]
	v_mfma_f32_16x16x32_bf16 v[60:63], v[132:135], v[198:201], v[60:63]
	v_mfma_f32_16x16x32_bf16 v[56:59], v[136:139], v[194:197], v[56:59]
	v_mfma_f32_16x16x32_bf16 v[56:59], v[160:163], v[198:201], v[56:59]
	v_mfma_f32_16x16x32_bf16 v[44:47], v[128:131], v[202:205], v[44:47]
	v_mfma_f32_16x16x32_bf16 v[44:47], v[132:135], v[206:209], v[44:47]
	v_mfma_f32_16x16x32_bf16 v[40:43], v[136:139], v[202:205], v[40:43]
	v_mfma_f32_16x16x32_bf16 v[40:43], v[160:163], v[206:209], v[40:43]
	v_mfma_f32_16x16x32_bf16 v[28:31], v[128:131], v[210:213], v[28:31]
	v_mfma_f32_16x16x32_bf16 v[28:31], v[132:135], v[214:217], v[28:31]
	v_mfma_f32_16x16x32_bf16 v[24:27], v[136:139], v[210:213], v[24:27]
	v_mfma_f32_16x16x32_bf16 v[24:27], v[160:163], v[214:217], v[24:27]
	v_mfma_f32_16x16x32_bf16 v[12:15], v[128:131], v[218:221], v[12:15]
	v_mfma_f32_16x16x32_bf16 v[12:15], v[132:135], v[222:225], v[12:15]
	v_mfma_f32_16x16x32_bf16 v[8:11], v[136:139], v[218:221], v[8:11]
	v_mfma_f32_16x16x32_bf16 v[8:11], v[160:163], v[222:225], v[8:11]
	v_mfma_f32_16x16x32_bf16 v[52:55], v[164:167], v[194:197], v[52:55]
	v_mfma_f32_16x16x32_bf16 v[52:55], v[168:171], v[198:201], v[52:55]
	v_mfma_f32_16x16x32_bf16 v[48:51], v[186:189], v[194:197], v[48:51]
	v_mfma_f32_16x16x32_bf16 v[48:51], v[190:193], v[198:201], v[48:51]
	v_mfma_f32_16x16x32_bf16 v[36:39], v[164:167], v[202:205], v[36:39]
	v_mfma_f32_16x16x32_bf16 v[36:39], v[168:171], v[206:209], v[36:39]
	v_mfma_f32_16x16x32_bf16 v[32:35], v[186:189], v[202:205], v[32:35]
	v_mfma_f32_16x16x32_bf16 v[32:35], v[190:193], v[206:209], v[32:35]
	v_mfma_f32_16x16x32_bf16 v[20:23], v[164:167], v[210:213], v[20:23]
	v_mfma_f32_16x16x32_bf16 v[20:23], v[168:171], v[214:217], v[20:23]
	v_mfma_f32_16x16x32_bf16 v[16:19], v[186:189], v[210:213], v[16:19]
	v_mfma_f32_16x16x32_bf16 v[16:19], v[190:193], v[214:217], v[16:19]
	v_mfma_f32_16x16x32_bf16 v[4:7], v[164:167], v[218:221], v[4:7]
	v_mfma_f32_16x16x32_bf16 v[4:7], v[168:171], v[222:225], v[4:7]
	s_setprio 3
	s_barrier
	v_mfma_f32_16x16x32_bf16 v[0:3], v[186:189], v[218:221], v[0:3]
	v_mfma_f32_16x16x32_bf16 v[0:3], v[190:193], v[222:225], v[0:3]
	s_setprio 0
	s_add_i32 s68, s68, 2
	s_add_u32 s78, s78, 0x100
	s_addc_u32 s79, s79, 0
	s_add_u32 s66, s66, 0x100
	s_addc_u32 s67, s67, 0
	s_cmp_gt_u32 s68, 13
	s_cbranch_scc0 .LBB0_1760
	s_branch .Lzskip_8

.LBB0_2037:
	ds_read_b128 v[120:123], v245
	ds_read_b128 v[124:127], v245 offset:1024
	ds_read_b128 v[128:131], v245 offset:2048
	ds_read_b128 v[132:135], v245 offset:3072
	ds_read_b128 v[144:147], v246
	ds_read_b128 v[148:151], v246 offset:1024
	ds_read_b128 v[152:155], v246 offset:2048
	ds_read_b128 v[156:159], v246 offset:3072
	s_add_u32 s67, s76, 0xfffc0080
	s_addc_u32 s68, s77, -1
	s_cmp_eq_u32 s66, 12
	s_cselect_b32 s81, s53, s68
	s_cselect_b32 s80, s54, s67
	s_cselect_b32 s79, s51, s57
	s_cselect_b32 s78, s55, s56
	v_lshl_add_u64 v[204:205], s[76:77], 0, v[200:201]
	s_add_i32 m0, s16, 0xc000
	ds_read_b128 v[160:163], v247
	ds_read_b128 v[164:167], v247 offset:1024
	ds_read_b128 v[168:171], v247 offset:2048
	ds_read_b128 v[172:175], v247 offset:3072
	ds_read_b128 v[176:179], v247 offset:4096
	ds_read_b128 v[180:183], v247 offset:5120
	ds_read_b128 v[184:187], v247 offset:6144
	ds_read_b128 v[188:191], v247 offset:7168
	global_load_lds_dwordx4 v[204:205], off
	s_add_i32 m0, s16, 0xe000
	v_lshl_add_u64 v[204:205], s[76:77], 0, v[202:203]
	global_load_lds_dwordx4 v[204:205], off
	s_cmp_eq_u32 s66, -2
	s_waitcnt vmcnt(8) lgkmcnt(0)
	s_barrier
	s_cbranch_scc1 .Lzv_9_0
	v_mfma_f32_16x16x32_bf16 v[140:143], v[120:123], v[160:163], v[140:143]
	v_mfma_f32_16x16x32_bf16 v[140:143], v[124:127], v[164:167], v[140:143]
	v_mfma_f32_16x16x32_bf16 v[136:139], v[128:131], v[160:163], v[136:139]
	v_mfma_f32_16x16x32_bf16 v[136:139], v[132:135], v[164:167], v[136:139]
	v_mfma_f32_16x16x32_bf16 v[108:111], v[120:123], v[168:171], v[108:111]
	v_mfma_f32_16x16x32_bf16 v[108:111], v[124:127], v[172:175], v[108:111]
	v_mfma_f32_16x16x32_bf16 v[104:107], v[128:131], v[168:171], v[104:107]
	v_mfma_f32_16x16x32_bf16 v[104:107], v[132:135], v[172:175], v[104:107]
	v_mfma_f32_16x16x32_bf16 v[92:95], v[120:123], v[176:179], v[92:95]
	v_mfma_f32_16x16x32_bf16 v[92:95], v[124:127], v[180:183], v[92:95]
	v_mfma_f32_16x16x32_bf16 v[88:91], v[128:131], v[176:179], v[88:91]
	v_mfma_f32_16x16x32_bf16 v[88:91], v[132:135], v[180:183], v[88:91]
	v_mfma_f32_16x16x32_bf16 v[76:79], v[120:123], v[184:187], v[76:79]
	v_mfma_f32_16x16x32_bf16 v[76:79], v[124:127], v[188:191], v[76:79]
	v_mfma_f32_16x16x32_bf16 v[72:75], v[128:131], v[184:187], v[72:75]
	v_mfma_f32_16x16x32_bf16 v[72:75], v[132:135], v[188:191], v[72:75]
	v_mfma_f32_16x16x32_bf16 v[116:119], v[144:147], v[160:163], v[116:119]
	v_mfma_f32_16x16x32_bf16 v[116:119], v[148:151], v[164:167], v[116:119]
	v_mfma_f32_16x16x32_bf16 v[112:115], v[152:155], v[160:163], v[112:115]
	v_mfma_f32_16x16x32_bf16 v[112:115], v[156:159], v[164:167], v[112:115]
	v_mfma_f32_16x16x32_bf16 v[100:103], v[144:147], v[168:171], v[100:103]
	v_mfma_f32_16x16x32_bf16 v[100:103], v[148:151], v[172:175], v[100:103]
	v_mfma_f32_16x16x32_bf16 v[96:99], v[152:155], v[168:171], v[96:99]
	v_mfma_f32_16x16x32_bf16 v[96:99], v[156:159], v[172:175], v[96:99]
	v_mfma_f32_16x16x32_bf16 v[84:87], v[144:147], v[176:179], v[84:87]
	v_mfma_f32_16x16x32_bf16 v[84:87], v[148:151], v[180:183], v[84:87]
	v_mfma_f32_16x16x32_bf16 v[80:83], v[152:155], v[176:179], v[80:83]
	v_mfma_f32_16x16x32_bf16 v[80:83], v[156:159], v[180:183], v[80:83]
	v_mfma_f32_16x16x32_bf16 v[68:71], v[144:147], v[184:187], v[68:71]
	v_mfma_f32_16x16x32_bf16 v[68:71], v[148:151], v[188:191], v[68:71]
	s_setprio 3
	s_barrier
	v_mfma_f32_16x16x32_bf16 v[64:67], v[152:155], v[184:187], v[64:67]
	v_mfma_f32_16x16x32_bf16 v[64:67], v[156:159], v[188:191], v[64:67]
	s_setprio 0
.Lzj_9_0:
	s_add_i32 s67, s26, s15
	v_lshl_add_u64 v[204:205], s[78:79], 0, v[194:195]
	s_mov_b32 m0, s67
	ds_read_b128 v[160:163], v247 offset:16384
	ds_read_b128 v[164:167], v247 offset:17408
	ds_read_b128 v[168:171], v247 offset:18432
	ds_read_b128 v[172:175], v247 offset:19456
	ds_read_b128 v[176:179], v247 offset:20480
	ds_read_b128 v[180:183], v247 offset:21504
	ds_read_b128 v[184:187], v247 offset:22528
	ds_read_b128 v[188:191], v247 offset:23552
	global_load_lds_dwordx4 v[204:205], off
	s_add_i32 m0, s67, 0x2000
	s_add_u32 s68, s78, 0x40000
	v_lshl_add_u64 v[206:207], s[78:79], 0, v[198:199]
	s_addc_u32 s69, s79, 0
	s_add_i32 s67, s27, s15
	global_load_lds_dwordx4 v[206:207], off
	v_lshl_add_u64 v[208:209], s[68:69], 0, v[194:195]
	s_mov_b32 m0, s67
	global_load_lds_dwordx4 v[208:209], off
	s_add_i32 m0, s67, 0x2000
	v_lshl_add_u64 v[208:209], s[68:69], 0, v[198:199]
	global_load_lds_dwordx4 v[208:209], off
	s_mov_b32 m0, s16
	v_lshl_add_u64 v[208:209], s[80:81], 0, v[192:193]
	global_load_lds_dwordx4 v[208:209], off
	s_mov_b32 m0, s17
	v_lshl_add_u64 v[210:211], s[80:81], 0, v[196:197]
	global_load_lds_dwordx4 v[210:211], off
	s_cmp_eq_u32 s66, -2
	s_waitcnt vmcnt(8) lgkmcnt(0)
	s_barrier
	s_cbranch_scc1 .Lzv_9_1
	v_mfma_f32_16x16x32_bf16 v[60:63], v[120:123], v[160:163], v[60:63]
	v_mfma_f32_16x16x32_bf16 v[60:63], v[124:127], v[164:167], v[60:63]
	v_mfma_f32_16x16x32_bf16 v[56:59], v[128:131], v[160:163], v[56:59]
	v_mfma_f32_16x16x32_bf16 v[56:59], v[132:135], v[164:167], v[56:59]
	v_mfma_f32_16x16x32_bf16 v[44:47], v[120:123], v[168:171], v[44:47]
	v_mfma_f32_16x16x32_bf16 v[44:47], v[124:127], v[172:175], v[44:47]
	v_mfma_f32_16x16x32_bf16 v[40:43], v[128:131], v[168:171], v[40:43]
	v_mfma_f32_16x16x32_bf16 v[40:43], v[132:135], v[172:175], v[40:43]
	v_mfma_f32_16x16x32_bf16 v[28:31], v[120:123], v[176:179], v[28:31]
	v_mfma_f32_16x16x32_bf16 v[28:31], v[124:127], v[180:183], v[28:31]
	v_mfma_f32_16x16x32_bf16 v[24:27], v[128:131], v[176:179], v[24:27]
	v_mfma_f32_16x16x32_bf16 v[24:27], v[132:135], v[180:183], v[24:27]
	v_mfma_f32_16x16x32_bf16 v[12:15], v[120:123], v[184:187], v[12:15]
	v_mfma_f32_16x16x32_bf16 v[12:15], v[124:127], v[188:191], v[12:15]
	v_mfma_f32_16x16x32_bf16 v[8:11], v[128:131], v[184:187], v[8:11]
	v_mfma_f32_16x16x32_bf16 v[8:11], v[132:135], v[188:191], v[8:11]
	v_mfma_f32_16x16x32_bf16 v[52:55], v[144:147], v[160:163], v[52:55]
	v_mfma_f32_16x16x32_bf16 v[52:55], v[148:151], v[164:167], v[52:55]
	v_mfma_f32_16x16x32_bf16 v[48:51], v[152:155], v[160:163], v[48:51]
	v_mfma_f32_16x16x32_bf16 v[48:51], v[156:159], v[164:167], v[48:51]
	v_mfma_f32_16x16x32_bf16 v[36:39], v[144:147], v[168:171], v[36:39]
	v_mfma_f32_16x16x32_bf16 v[36:39], v[148:151], v[172:175], v[36:39]
	v_mfma_f32_16x16x32_bf16 v[32:35], v[152:155], v[168:171], v[32:35]
	v_mfma_f32_16x16x32_bf16 v[32:35], v[156:159], v[172:175], v[32:35]
	v_mfma_f32_16x16x32_bf16 v[20:23], v[144:147], v[176:179], v[20:23]
	v_mfma_f32_16x16x32_bf16 v[20:23], v[148:151], v[180:183], v[20:23]
	v_mfma_f32_16x16x32_bf16 v[16:19], v[152:155], v[176:179], v[16:19]
	v_mfma_f32_16x16x32_bf16 v[16:19], v[156:159], v[180:183], v[16:19]
	v_mfma_f32_16x16x32_bf16 v[4:7], v[144:147], v[184:187], v[4:7]
	v_mfma_f32_16x16x32_bf16 v[4:7], v[148:151], v[188:191], v[4:7]
	s_setprio 3
	s_barrier
	v_mfma_f32_16x16x32_bf16 v[0:3], v[152:155], v[184:187], v[0:3]
	v_mfma_f32_16x16x32_bf16 v[0:3], v[156:159], v[188:191], v[0:3]
	s_setprio 0
.Lzj_9_1:
	s_add_i32 s67, 0, 0x18000
	s_add_i32 s75, 0, 0x1c000
	v_add_u32_e32 v132, s67, v243
	v_add_u32_e32 v156, s75, v243
	ds_read_b128 v[120:123], v132
	ds_read_b128 v[124:127], v132 offset:1024
	ds_read_b128 v[128:131], v132 offset:2048
	ds_read_b128 v[132:135], v132 offset:3072
	ds_read_b128 v[144:147], v156
	ds_read_b128 v[148:151], v156 offset:1024
	ds_read_b128 v[152:155], v156 offset:2048
	ds_read_b128 v[156:159], v156 offset:3072
	s_add_u32 s68, s80, 0x40000
	s_addc_u32 s69, s81, 0
	s_mov_b32 m0, s18
	v_lshl_add_u64 v[212:213], s[68:69], 0, v[192:193]
	ds_read_b128 v[160:163], v247 offset:32768
	ds_read_b128 v[164:167], v247 offset:33792
	ds_read_b128 v[168:171], v247 offset:34816
	ds_read_b128 v[172:175], v247 offset:35840
	ds_read_b128 v[176:179], v247 offset:36864
	ds_read_b128 v[180:183], v247 offset:37888
	ds_read_b128 v[184:187], v247 offset:38912
	ds_read_b128 v[188:191], v247 offset:39936
	global_load_lds_dwordx4 v[212:213], off
	s_mov_b32 m0, s19
	v_lshl_add_u64 v[212:213], s[68:69], 0, v[196:197]
	global_load_lds_dwordx4 v[212:213], off
	s_waitcnt vmcnt(8) lgkmcnt(0)
	s_barrier
	v_mfma_f32_16x16x32_bf16 v[140:143], v[120:123], v[160:163], v[140:143]
	v_mfma_f32_16x16x32_bf16 v[140:143], v[124:127], v[164:167], v[140:143]
	v_mfma_f32_16x16x32_bf16 v[136:139], v[128:131], v[160:163], v[136:139]
	v_mfma_f32_16x16x32_bf16 v[136:139], v[132:135], v[164:167], v[136:139]
	v_mfma_f32_16x16x32_bf16 v[108:111], v[120:123], v[168:171], v[108:111]
	v_mfma_f32_16x16x32_bf16 v[108:111], v[124:127], v[172:175], v[108:111]
	v_mfma_f32_16x16x32_bf16 v[104:107], v[128:131], v[168:171], v[104:107]
	v_mfma_f32_16x16x32_bf16 v[104:107], v[132:135], v[172:175], v[104:107]
	v_mfma_f32_16x16x32_bf16 v[92:95], v[120:123], v[176:179], v[92:95]
	v_mfma_f32_16x16x32_bf16 v[92:95], v[124:127], v[180:183], v[92:95]
	v_mfma_f32_16x16x32_bf16 v[88:91], v[128:131], v[176:179], v[88:91]
	v_mfma_f32_16x16x32_bf16 v[88:91], v[132:135], v[180:183], v[88:91]
	v_mfma_f32_16x16x32_bf16 v[76:79], v[120:123], v[184:187], v[76:79]
	v_mfma_f32_16x16x32_bf16 v[76:79], v[124:127], v[188:191], v[76:79]
	v_mfma_f32_16x16x32_bf16 v[72:75], v[128:131], v[184:187], v[72:75]
	v_mfma_f32_16x16x32_bf16 v[72:75], v[132:135], v[188:191], v[72:75]
	v_mfma_f32_16x16x32_bf16 v[116:119], v[144:147], v[160:163], v[116:119]
	v_mfma_f32_16x16x32_bf16 v[116:119], v[148:151], v[164:167], v[116:119]
	v_mfma_f32_16x16x32_bf16 v[112:115], v[152:155], v[160:163], v[112:115]
	v_mfma_f32_16x16x32_bf16 v[112:115], v[156:159], v[164:167], v[112:115]
	v_mfma_f32_16x16x32_bf16 v[100:103], v[144:147], v[168:171], v[100:103]
	v_mfma_f32_16x16x32_bf16 v[100:103], v[148:151], v[172:175], v[100:103]
	v_mfma_f32_16x16x32_bf16 v[96:99], v[152:155], v[168:171], v[96:99]
	v_mfma_f32_16x16x32_bf16 v[96:99], v[156:159], v[172:175], v[96:99]
	v_mfma_f32_16x16x32_bf16 v[84:87], v[144:147], v[176:179], v[84:87]
	v_mfma_f32_16x16x32_bf16 v[84:87], v[148:151], v[180:183], v[84:87]
	v_mfma_f32_16x16x32_bf16 v[80:83], v[152:155], v[176:179], v[80:83]
	v_mfma_f32_16x16x32_bf16 v[80:83], v[156:159], v[180:183], v[80:83]
	v_mfma_f32_16x16x32_bf16 v[68:71], v[144:147], v[184:187], v[68:71]
	v_mfma_f32_16x16x32_bf16 v[68:71], v[148:151], v[188:191], v[68:71]
	s_setprio 3
	s_barrier
	v_mfma_f32_16x16x32_bf16 v[64:67], v[152:155], v[184:187], v[64:67]
	v_mfma_f32_16x16x32_bf16 v[64:67], v[156:159], v[188:191], v[64:67]
	s_setprio 0
	s_add_i32 s67, s67, s15
	v_lshl_add_u64 v[204:205], v[204:205], 0, s[46:47]
	s_mov_b32 m0, s67
	ds_read_b128 v[160:163], v247 offset:49152
	ds_read_b128 v[164:167], v247 offset:50176
	ds_read_b128 v[168:171], v247 offset:51200
	ds_read_b128 v[172:175], v247 offset:52224
	ds_read_b128 v[176:179], v247 offset:53248
	ds_read_b128 v[180:183], v247 offset:54272
	ds_read_b128 v[184:187], v247 offset:55296
	ds_read_b128 v[188:191], v247 offset:56320
	global_load_lds_dwordx4 v[204:205], off
	s_add_i32 m0, s67, 0x2000
	s_add_u32 s68, s78, 0x40080
	v_lshl_add_u64 v[204:205], v[206:207], 0, s[46:47]
	s_addc_u32 s69, s79, 0
	s_add_i32 s67, s75, s15
	global_load_lds_dwordx4 v[204:205], off
	s_mov_b32 m0, s67
	v_lshl_add_u64 v[204:205], s[68:69], 0, v[194:195]
	global_load_lds_dwordx4 v[204:205], off
	s_add_i32 m0, s67, 0x2000
	v_lshl_add_u64 v[204:205], s[68:69], 0, v[198:199]
	global_load_lds_dwordx4 v[204:205], off
	s_mov_b32 m0, s21
	v_lshl_add_u64 v[204:205], v[208:209], 0, s[46:47]
	global_load_lds_dwordx4 v[204:205], off
	s_mov_b32 m0, s22
	v_lshl_add_u64 v[204:205], v[210:211], 0, s[46:47]
	global_load_lds_dwordx4 v[204:205], off
	s_waitcnt vmcnt(8) lgkmcnt(0)
	s_barrier
	v_mfma_f32_16x16x32_bf16 v[60:63], v[120:123], v[160:163], v[60:63]
	v_mfma_f32_16x16x32_bf16 v[60:63], v[124:127], v[164:167], v[60:63]
	v_mfma_f32_16x16x32_bf16 v[56:59], v[128:131], v[160:163], v[56:59]
	v_mfma_f32_16x16x32_bf16 v[56:59], v[132:135], v[164:167], v[56:59]
	v_mfma_f32_16x16x32_bf16 v[44:47], v[120:123], v[168:171], v[44:47]
	v_mfma_f32_16x16x32_bf16 v[44:47], v[124:127], v[172:175], v[44:47]
	v_mfma_f32_16x16x32_bf16 v[40:43], v[128:131], v[168:171], v[40:43]
	v_mfma_f32_16x16x32_bf16 v[40:43], v[132:135], v[172:175], v[40:43]
	v_mfma_f32_16x16x32_bf16 v[28:31], v[120:123], v[176:179], v[28:31]
	v_mfma_f32_16x16x32_bf16 v[28:31], v[124:127], v[180:183], v[28:31]
	v_mfma_f32_16x16x32_bf16 v[24:27], v[128:131], v[176:179], v[24:27]
	v_mfma_f32_16x16x32_bf16 v[24:27], v[132:135], v[180:183], v[24:27]
	v_mfma_f32_16x16x32_bf16 v[12:15], v[120:123], v[184:187], v[12:15]
	v_mfma_f32_16x16x32_bf16 v[12:15], v[124:127], v[188:191], v[12:15]
	v_mfma_f32_16x16x32_bf16 v[8:11], v[128:131], v[184:187], v[8:11]
	v_mfma_f32_16x16x32_bf16 v[8:11], v[132:135], v[188:191], v[8:11]
	v_mfma_f32_16x16x32_bf16 v[52:55], v[144:147], v[160:163], v[52:55]
	v_mfma_f32_16x16x32_bf16 v[52:55], v[148:151], v[164:167], v[52:55]
	v_mfma_f32_16x16x32_bf16 v[48:51], v[152:155], v[160:163], v[48:51]
	v_mfma_f32_16x16x32_bf16 v[48:51], v[156:159], v[164:167], v[48:51]
	v_mfma_f32_16x16x32_bf16 v[36:39], v[144:147], v[168:171], v[36:39]
	v_mfma_f32_16x16x32_bf16 v[36:39], v[148:151], v[172:175], v[36:39]
	v_mfma_f32_16x16x32_bf16 v[32:35], v[152:155], v[168:171], v[32:35]
	v_mfma_f32_16x16x32_bf16 v[32:35], v[156:159], v[172:175], v[32:35]
	v_mfma_f32_16x16x32_bf16 v[20:23], v[144:147], v[176:179], v[20:23]
	v_mfma_f32_16x16x32_bf16 v[20:23], v[148:151], v[180:183], v[20:23]
	v_mfma_f32_16x16x32_bf16 v[16:19], v[152:155], v[176:179], v[16:19]
	v_mfma_f32_16x16x32_bf16 v[16:19], v[156:159], v[180:183], v[16:19]
	v_mfma_f32_16x16x32_bf16 v[4:7], v[144:147], v[184:187], v[4:7]
	v_mfma_f32_16x16x32_bf16 v[4:7], v[148:151], v[188:191], v[4:7]
	s_setprio 3
	s_barrier
	v_mfma_f32_16x16x32_bf16 v[0:3], v[152:155], v[184:187], v[0:3]
	v_mfma_f32_16x16x32_bf16 v[0:3], v[156:159], v[188:191], v[0:3]
	s_setprio 0
	s_add_i32 s66, s66, 2
	s_add_u32 s76, s76, 0x100
	s_addc_u32 s77, s77, 0
	s_add_u32 s56, s56, 0x100
	s_addc_u32 s57, s57, 0
	s_cmp_gt_u32 s66, 13
	s_cbranch_scc0 .LBB0_2037
	s_branch .Lzskip_9

.LBB0_2192:
	ds_read_b128 v[146:149], v174
	ds_read_b128 v[150:153], v174 offset:1024
	ds_read_b128 v[154:157], v174 offset:2048
	ds_read_b128 v[158:161], v174 offset:3072
	ds_read_b128 v[162:165], v175
	ds_read_b128 v[178:181], v175 offset:1024
	ds_read_b128 v[182:185], v175 offset:2048
	ds_read_b128 v[186:189], v175 offset:3072
	s_add_u32 s70, s58, 0xfffc0080
	s_addc_u32 s71, s59, -1
	s_cmp_eq_u32 s69, 12
	s_cselect_b32 s73, s47, s71
	s_cselect_b32 s72, s53, s70
	s_cselect_b32 s71, s45, s68
	s_cselect_b32 s70, s66, s67
	v_lshl_add_u64 v[166:167], s[58:59], 0, v[136:137]
	s_add_i32 m0, s17, 0xc000
	ds_read_b128 v[190:193], v176
	ds_read_b128 v[194:197], v176 offset:1024
	ds_read_b128 v[198:201], v176 offset:2048
	ds_read_b128 v[202:205], v176 offset:3072
	ds_read_b128 v[206:209], v176 offset:4096
	ds_read_b128 v[210:213], v176 offset:5120
	ds_read_b128 v[214:217], v176 offset:6144
	ds_read_b128 v[218:221], v176 offset:7168
	global_load_lds_dwordx4 v[166:167], off
	s_add_i32 m0, s17, 0xe000
	v_lshl_add_u64 v[166:167], s[58:59], 0, v[140:141]
	global_load_lds_dwordx4 v[166:167], off
	s_cmp_eq_u32 s69, -2
	s_waitcnt vmcnt(8) lgkmcnt(0)
	s_barrier
	s_cbranch_scc1 .Lzv_10_0
	v_mfma_f32_16x16x32_bf16 v[124:127], v[146:149], v[190:193], v[124:127]
	v_mfma_f32_16x16x32_bf16 v[124:127], v[150:153], v[194:197], v[124:127]
	v_mfma_f32_16x16x32_bf16 v[116:119], v[154:157], v[190:193], v[116:119]
	v_mfma_f32_16x16x32_bf16 v[116:119], v[158:161], v[194:197], v[116:119]
	v_mfma_f32_16x16x32_bf16 v[108:111], v[146:149], v[198:201], v[108:111]
	v_mfma_f32_16x16x32_bf16 v[108:111], v[150:153], v[202:205], v[108:111]
	v_mfma_f32_16x16x32_bf16 v[100:103], v[154:157], v[198:201], v[100:103]
	v_mfma_f32_16x16x32_bf16 v[100:103], v[158:161], v[202:205], v[100:103]
	v_mfma_f32_16x16x32_bf16 v[92:95], v[146:149], v[206:209], v[92:95]
	v_mfma_f32_16x16x32_bf16 v[92:95], v[150:153], v[210:213], v[92:95]
	v_mfma_f32_16x16x32_bf16 v[84:87], v[154:157], v[206:209], v[84:87]
	v_mfma_f32_16x16x32_bf16 v[84:87], v[158:161], v[210:213], v[84:87]
	v_mfma_f32_16x16x32_bf16 v[76:79], v[146:149], v[214:217], v[76:79]
	v_mfma_f32_16x16x32_bf16 v[76:79], v[150:153], v[218:221], v[76:79]
	v_mfma_f32_16x16x32_bf16 v[68:71], v[154:157], v[214:217], v[68:71]
	v_mfma_f32_16x16x32_bf16 v[68:71], v[158:161], v[218:221], v[68:71]
	v_mfma_f32_16x16x32_bf16 v[120:123], v[162:165], v[190:193], v[120:123]
	v_mfma_f32_16x16x32_bf16 v[120:123], v[178:181], v[194:197], v[120:123]
	v_mfma_f32_16x16x32_bf16 v[112:115], v[182:185], v[190:193], v[112:115]
	v_mfma_f32_16x16x32_bf16 v[112:115], v[186:189], v[194:197], v[112:115]
	v_mfma_f32_16x16x32_bf16 v[104:107], v[162:165], v[198:201], v[104:107]
	v_mfma_f32_16x16x32_bf16 v[104:107], v[178:181], v[202:205], v[104:107]
	v_mfma_f32_16x16x32_bf16 v[96:99], v[182:185], v[198:201], v[96:99]
	v_mfma_f32_16x16x32_bf16 v[96:99], v[186:189], v[202:205], v[96:99]
	v_mfma_f32_16x16x32_bf16 v[88:91], v[162:165], v[206:209], v[88:91]
	v_mfma_f32_16x16x32_bf16 v[88:91], v[178:181], v[210:213], v[88:91]
	v_mfma_f32_16x16x32_bf16 v[80:83], v[182:185], v[206:209], v[80:83]
	v_mfma_f32_16x16x32_bf16 v[80:83], v[186:189], v[210:213], v[80:83]
	v_mfma_f32_16x16x32_bf16 v[72:75], v[162:165], v[214:217], v[72:75]
	v_mfma_f32_16x16x32_bf16 v[72:75], v[178:181], v[218:221], v[72:75]
	s_setprio 3
	s_barrier
	v_mfma_f32_16x16x32_bf16 v[64:67], v[182:185], v[214:217], v[64:67]
	v_mfma_f32_16x16x32_bf16 v[64:67], v[186:189], v[218:221], v[64:67]
	s_setprio 0
.Lzj_10_0:
	s_add_i32 s74, s26, s16
	v_lshl_add_u64 v[166:167], s[70:71], 0, v[132:133]
	s_mov_b32 m0, s74
	ds_read_b128 v[190:193], v176 offset:16384
	ds_read_b128 v[194:197], v176 offset:17408
	ds_read_b128 v[198:201], v176 offset:18432
	ds_read_b128 v[202:205], v176 offset:19456
	ds_read_b128 v[206:209], v176 offset:20480
	ds_read_b128 v[210:213], v176 offset:21504
	ds_read_b128 v[214:217], v176 offset:22528
	ds_read_b128 v[218:221], v176 offset:23552
	global_load_lds_dwordx4 v[166:167], off
	s_add_i32 m0, s74, 0x2000
	s_add_u32 s74, s70, 0x40000
	v_lshl_add_u64 v[222:223], s[70:71], 0, v[128:129]
	s_addc_u32 s75, s71, 0
	s_add_i32 s76, s27, s16
	global_load_lds_dwordx4 v[222:223], off
	v_lshl_add_u64 v[224:225], s[74:75], 0, v[132:133]
	s_mov_b32 m0, s76
	global_load_lds_dwordx4 v[224:225], off
	s_add_i32 m0, s76, 0x2000
	v_lshl_add_u64 v[224:225], s[74:75], 0, v[128:129]
	global_load_lds_dwordx4 v[224:225], off
	s_mov_b32 m0, s17
	v_lshl_add_u64 v[224:225], s[72:73], 0, v[134:135]
	global_load_lds_dwordx4 v[224:225], off
	s_mov_b32 m0, s18
	v_lshl_add_u64 v[226:227], s[72:73], 0, v[130:131]
	global_load_lds_dwordx4 v[226:227], off
	s_cmp_eq_u32 s69, -2
	s_waitcnt vmcnt(8) lgkmcnt(0)
	s_barrier
	s_cbranch_scc1 .Lzv_10_1
	v_mfma_f32_16x16x32_bf16 v[60:63], v[146:149], v[190:193], v[60:63]
	v_mfma_f32_16x16x32_bf16 v[60:63], v[150:153], v[194:197], v[60:63]
	v_mfma_f32_16x16x32_bf16 v[52:55], v[154:157], v[190:193], v[52:55]
	v_mfma_f32_16x16x32_bf16 v[52:55], v[158:161], v[194:197], v[52:55]
	v_mfma_f32_16x16x32_bf16 v[44:47], v[146:149], v[198:201], v[44:47]
	v_mfma_f32_16x16x32_bf16 v[44:47], v[150:153], v[202:205], v[44:47]
	v_mfma_f32_16x16x32_bf16 v[36:39], v[154:157], v[198:201], v[36:39]
	v_mfma_f32_16x16x32_bf16 v[36:39], v[158:161], v[202:205], v[36:39]
	v_mfma_f32_16x16x32_bf16 v[28:31], v[146:149], v[206:209], v[28:31]
	v_mfma_f32_16x16x32_bf16 v[28:31], v[150:153], v[210:213], v[28:31]
	v_mfma_f32_16x16x32_bf16 v[20:23], v[154:157], v[206:209], v[20:23]
	v_mfma_f32_16x16x32_bf16 v[20:23], v[158:161], v[210:213], v[20:23]
	v_mfma_f32_16x16x32_bf16 v[12:15], v[146:149], v[214:217], v[12:15]
	v_mfma_f32_16x16x32_bf16 v[12:15], v[150:153], v[218:221], v[12:15]
	v_mfma_f32_16x16x32_bf16 v[4:7], v[154:157], v[214:217], v[4:7]
	v_mfma_f32_16x16x32_bf16 v[4:7], v[158:161], v[218:221], v[4:7]
	v_mfma_f32_16x16x32_bf16 v[56:59], v[162:165], v[190:193], v[56:59]
	v_mfma_f32_16x16x32_bf16 v[56:59], v[178:181], v[194:197], v[56:59]
	v_mfma_f32_16x16x32_bf16 v[48:51], v[182:185], v[190:193], v[48:51]
	v_mfma_f32_16x16x32_bf16 v[48:51], v[186:189], v[194:197], v[48:51]
	v_mfma_f32_16x16x32_bf16 v[40:43], v[162:165], v[198:201], v[40:43]
	v_mfma_f32_16x16x32_bf16 v[40:43], v[178:181], v[202:205], v[40:43]
	v_mfma_f32_16x16x32_bf16 v[32:35], v[182:185], v[198:201], v[32:35]
	v_mfma_f32_16x16x32_bf16 v[32:35], v[186:189], v[202:205], v[32:35]
	v_mfma_f32_16x16x32_bf16 v[24:27], v[162:165], v[206:209], v[24:27]
	v_mfma_f32_16x16x32_bf16 v[24:27], v[178:181], v[210:213], v[24:27]
	v_mfma_f32_16x16x32_bf16 v[16:19], v[182:185], v[206:209], v[16:19]
	v_mfma_f32_16x16x32_bf16 v[16:19], v[186:189], v[210:213], v[16:19]
	v_mfma_f32_16x16x32_bf16 v[8:11], v[162:165], v[214:217], v[8:11]
	v_mfma_f32_16x16x32_bf16 v[8:11], v[178:181], v[218:221], v[8:11]
	s_setprio 3
	s_barrier
	v_mfma_f32_16x16x32_bf16 v[0:3], v[182:185], v[214:217], v[0:3]
	v_mfma_f32_16x16x32_bf16 v[0:3], v[186:189], v[218:221], v[0:3]
	s_setprio 0
.Lzj_10_1:
	s_add_i32 s74, 0, 0x18000
	s_add_i32 s75, 0, 0x1c000
	v_add_u32_e32 v158, s74, v171
	v_add_u32_e32 v186, s75, v171
	ds_read_b128 v[146:149], v158
	ds_read_b128 v[150:153], v158 offset:1024
	ds_read_b128 v[154:157], v158 offset:2048
	ds_read_b128 v[158:161], v158 offset:3072
	ds_read_b128 v[162:165], v186
	ds_read_b128 v[178:181], v186 offset:1024
	ds_read_b128 v[182:185], v186 offset:2048
	ds_read_b128 v[186:189], v186 offset:3072
	s_add_u32 s72, s72, 0x40000
	s_addc_u32 s73, s73, 0
	s_mov_b32 m0, s19
	v_lshl_add_u64 v[228:229], s[72:73], 0, v[134:135]
	ds_read_b128 v[190:193], v176 offset:32768
	ds_read_b128 v[194:197], v176 offset:33792
	ds_read_b128 v[198:201], v176 offset:34816
	ds_read_b128 v[202:205], v176 offset:35840
	ds_read_b128 v[206:209], v176 offset:36864
	ds_read_b128 v[210:213], v176 offset:37888
	ds_read_b128 v[214:217], v176 offset:38912
	ds_read_b128 v[218:221], v176 offset:39936
	global_load_lds_dwordx4 v[228:229], off
	s_mov_b32 m0, s20
	v_lshl_add_u64 v[228:229], s[72:73], 0, v[130:131]
	global_load_lds_dwordx4 v[228:229], off
	s_waitcnt vmcnt(8) lgkmcnt(0)
	s_barrier
	v_mfma_f32_16x16x32_bf16 v[124:127], v[146:149], v[190:193], v[124:127]
	v_mfma_f32_16x16x32_bf16 v[124:127], v[150:153], v[194:197], v[124:127]
	v_mfma_f32_16x16x32_bf16 v[116:119], v[154:157], v[190:193], v[116:119]
	v_mfma_f32_16x16x32_bf16 v[116:119], v[158:161], v[194:197], v[116:119]
	v_mfma_f32_16x16x32_bf16 v[108:111], v[146:149], v[198:201], v[108:111]
	v_mfma_f32_16x16x32_bf16 v[108:111], v[150:153], v[202:205], v[108:111]
	v_mfma_f32_16x16x32_bf16 v[100:103], v[154:157], v[198:201], v[100:103]
	v_mfma_f32_16x16x32_bf16 v[100:103], v[158:161], v[202:205], v[100:103]
	v_mfma_f32_16x16x32_bf16 v[92:95], v[146:149], v[206:209], v[92:95]
	v_mfma_f32_16x16x32_bf16 v[92:95], v[150:153], v[210:213], v[92:95]
	v_mfma_f32_16x16x32_bf16 v[84:87], v[154:157], v[206:209], v[84:87]
	v_mfma_f32_16x16x32_bf16 v[84:87], v[158:161], v[210:213], v[84:87]
	v_mfma_f32_16x16x32_bf16 v[76:79], v[146:149], v[214:217], v[76:79]
	v_mfma_f32_16x16x32_bf16 v[76:79], v[150:153], v[218:221], v[76:79]
	v_mfma_f32_16x16x32_bf16 v[68:71], v[154:157], v[214:217], v[68:71]
	v_mfma_f32_16x16x32_bf16 v[68:71], v[158:161], v[218:221], v[68:71]
	v_mfma_f32_16x16x32_bf16 v[120:123], v[162:165], v[190:193], v[120:123]
	v_mfma_f32_16x16x32_bf16 v[120:123], v[178:181], v[194:197], v[120:123]
	v_mfma_f32_16x16x32_bf16 v[112:115], v[182:185], v[190:193], v[112:115]
	v_mfma_f32_16x16x32_bf16 v[112:115], v[186:189], v[194:197], v[112:115]
	v_mfma_f32_16x16x32_bf16 v[104:107], v[162:165], v[198:201], v[104:107]
	v_mfma_f32_16x16x32_bf16 v[104:107], v[178:181], v[202:205], v[104:107]
	v_mfma_f32_16x16x32_bf16 v[96:99], v[182:185], v[198:201], v[96:99]
	v_mfma_f32_16x16x32_bf16 v[96:99], v[186:189], v[202:205], v[96:99]
	v_mfma_f32_16x16x32_bf16 v[88:91], v[162:165], v[206:209], v[88:91]
	v_mfma_f32_16x16x32_bf16 v[88:91], v[178:181], v[210:213], v[88:91]
	v_mfma_f32_16x16x32_bf16 v[80:83], v[182:185], v[206:209], v[80:83]
	v_mfma_f32_16x16x32_bf16 v[80:83], v[186:189], v[210:213], v[80:83]
	v_mfma_f32_16x16x32_bf16 v[72:75], v[162:165], v[214:217], v[72:75]
	v_mfma_f32_16x16x32_bf16 v[72:75], v[178:181], v[218:221], v[72:75]
	s_setprio 3
	s_barrier
	v_mfma_f32_16x16x32_bf16 v[64:67], v[182:185], v[214:217], v[64:67]
	v_mfma_f32_16x16x32_bf16 v[64:67], v[186:189], v[218:221], v[64:67]
	s_setprio 0
	s_add_i32 s72, s74, s16
	v_lshl_add_u64 v[166:167], v[166:167], 0, s[10:11]
	s_mov_b32 m0, s72
	ds_read_b128 v[190:193], v176 offset:49152
	ds_read_b128 v[194:197], v176 offset:50176
	ds_read_b128 v[198:201], v176 offset:51200
	ds_read_b128 v[202:205], v176 offset:52224
	ds_read_b128 v[206:209], v176 offset:53248
	ds_read_b128 v[210:213], v176 offset:54272
	ds_read_b128 v[214:217], v176 offset:55296
	ds_read_b128 v[218:221], v176 offset:56320
	global_load_lds_dwordx4 v[166:167], off
	s_add_i32 m0, s72, 0x2000
	s_add_u32 s70, s70, 0x40080
	v_lshl_add_u64 v[166:167], v[222:223], 0, s[10:11]
	s_addc_u32 s71, s71, 0
	s_add_i32 s72, s75, s16
	global_load_lds_dwordx4 v[166:167], off
	s_mov_b32 m0, s72
	v_lshl_add_u64 v[166:167], s[70:71], 0, v[132:133]
	global_load_lds_dwordx4 v[166:167], off
	s_add_i32 m0, s72, 0x2000
	v_lshl_add_u64 v[166:167], s[70:71], 0, v[128:129]
	global_load_lds_dwordx4 v[166:167], off
	s_mov_b32 m0, s23
	v_lshl_add_u64 v[166:167], v[224:225], 0, s[10:11]
	global_load_lds_dwordx4 v[166:167], off
	s_mov_b32 m0, s24
	v_lshl_add_u64 v[166:167], v[226:227], 0, s[10:11]
	global_load_lds_dwordx4 v[166:167], off
	s_waitcnt vmcnt(8) lgkmcnt(0)
	s_barrier
	v_mfma_f32_16x16x32_bf16 v[60:63], v[146:149], v[190:193], v[60:63]
	v_mfma_f32_16x16x32_bf16 v[60:63], v[150:153], v[194:197], v[60:63]
	v_mfma_f32_16x16x32_bf16 v[52:55], v[154:157], v[190:193], v[52:55]
	v_mfma_f32_16x16x32_bf16 v[52:55], v[158:161], v[194:197], v[52:55]
	v_mfma_f32_16x16x32_bf16 v[44:47], v[146:149], v[198:201], v[44:47]
	v_mfma_f32_16x16x32_bf16 v[44:47], v[150:153], v[202:205], v[44:47]
	v_mfma_f32_16x16x32_bf16 v[36:39], v[154:157], v[198:201], v[36:39]
	v_mfma_f32_16x16x32_bf16 v[36:39], v[158:161], v[202:205], v[36:39]
	v_mfma_f32_16x16x32_bf16 v[28:31], v[146:149], v[206:209], v[28:31]
	v_mfma_f32_16x16x32_bf16 v[28:31], v[150:153], v[210:213], v[28:31]
	v_mfma_f32_16x16x32_bf16 v[20:23], v[154:157], v[206:209], v[20:23]
	v_mfma_f32_16x16x32_bf16 v[20:23], v[158:161], v[210:213], v[20:23]
	v_mfma_f32_16x16x32_bf16 v[12:15], v[146:149], v[214:217], v[12:15]
	v_mfma_f32_16x16x32_bf16 v[12:15], v[150:153], v[218:221], v[12:15]
	v_mfma_f32_16x16x32_bf16 v[4:7], v[154:157], v[214:217], v[4:7]
	v_mfma_f32_16x16x32_bf16 v[4:7], v[158:161], v[218:221], v[4:7]
	v_mfma_f32_16x16x32_bf16 v[56:59], v[162:165], v[190:193], v[56:59]
	v_mfma_f32_16x16x32_bf16 v[56:59], v[178:181], v[194:197], v[56:59]
	v_mfma_f32_16x16x32_bf16 v[48:51], v[182:185], v[190:193], v[48:51]
	v_mfma_f32_16x16x32_bf16 v[48:51], v[186:189], v[194:197], v[48:51]
	v_mfma_f32_16x16x32_bf16 v[40:43], v[162:165], v[198:201], v[40:43]
	v_mfma_f32_16x16x32_bf16 v[40:43], v[178:181], v[202:205], v[40:43]
	v_mfma_f32_16x16x32_bf16 v[32:35], v[182:185], v[198:201], v[32:35]
	v_mfma_f32_16x16x32_bf16 v[32:35], v[186:189], v[202:205], v[32:35]
	v_mfma_f32_16x16x32_bf16 v[24:27], v[162:165], v[206:209], v[24:27]
	v_mfma_f32_16x16x32_bf16 v[24:27], v[178:181], v[210:213], v[24:27]
	v_mfma_f32_16x16x32_bf16 v[16:19], v[182:185], v[206:209], v[16:19]
	v_mfma_f32_16x16x32_bf16 v[16:19], v[186:189], v[210:213], v[16:19]
	v_mfma_f32_16x16x32_bf16 v[8:11], v[162:165], v[214:217], v[8:11]
	v_mfma_f32_16x16x32_bf16 v[8:11], v[178:181], v[218:221], v[8:11]
	s_setprio 3
	s_barrier
	v_mfma_f32_16x16x32_bf16 v[0:3], v[182:185], v[214:217], v[0:3]
	v_mfma_f32_16x16x32_bf16 v[0:3], v[186:189], v[218:221], v[0:3]
	s_setprio 0
	s_add_i32 s69, s69, 2
	s_add_u32 s58, s58, 0x100
	s_addc_u32 s59, s59, 0
	s_add_u32 s67, s67, 0x100
	s_addc_u32 s68, s68, 0
	s_cmp_gt_u32 s69, 13
	s_cbranch_scc0 .LBB0_2192
	s_branch .Lzskip_10

.LBB0_2341:
	ds_read_b128 v[128:131], v197
	ds_read_b128 v[132:135], v197 offset:1024
	ds_read_b128 v[136:139], v197 offset:2048
	ds_read_b128 v[140:143], v197 offset:3072
	ds_read_b128 v[144:147], v198
	ds_read_b128 v[148:151], v198 offset:1024
	ds_read_b128 v[152:155], v198 offset:2048
	ds_read_b128 v[156:159], v198 offset:3072
	s_add_u32 s18, s16, 0xfff50080
	s_addc_u32 s19, s17, -1
	s_cmp_eq_u32 s45, 40
	s_cselect_b32 s21, s5, s19
	s_cselect_b32 s20, s4, s18
	s_cselect_b32 s19, s15, s44
	s_cselect_b32 s18, s14, s43
	v_lshl_add_u64 v[192:193], s[16:17], 0, v[172:173]
	s_add_i32 m0, s25, 0xc000
	ds_read_b128 v[160:163], v199
	ds_read_b128 v[180:183], v199 offset:1024
	ds_read_b128 v[184:187], v199 offset:2048
	ds_read_b128 v[188:191], v199 offset:3072
	ds_read_b128 v[200:203], v199 offset:4096
	ds_read_b128 v[204:207], v199 offset:5120
	ds_read_b128 v[208:211], v199 offset:6144
	ds_read_b128 v[212:215], v199 offset:7168
	global_load_lds_dwordx4 v[192:193], off
	s_add_i32 m0, s25, 0xe000
	v_lshl_add_u64 v[192:193], s[16:17], 0, v[174:175]
	global_load_lds_dwordx4 v[192:193], off
	s_cmp_eq_u32 s45, -2
	s_waitcnt vmcnt(8) lgkmcnt(0)
	s_barrier
	s_cbranch_scc1 .Lzv_11_0
	v_mfma_f32_16x16x32_bf16 v[124:127], v[128:131], v[160:163], v[124:127]
	v_mfma_f32_16x16x32_bf16 v[124:127], v[132:135], v[180:183], v[124:127]
	v_mfma_f32_16x16x32_bf16 v[120:123], v[136:139], v[160:163], v[120:123]
	v_mfma_f32_16x16x32_bf16 v[120:123], v[140:143], v[180:183], v[120:123]
	v_mfma_f32_16x16x32_bf16 v[108:111], v[128:131], v[184:187], v[108:111]
	v_mfma_f32_16x16x32_bf16 v[108:111], v[132:135], v[188:191], v[108:111]
	v_mfma_f32_16x16x32_bf16 v[104:107], v[136:139], v[184:187], v[104:107]
	v_mfma_f32_16x16x32_bf16 v[104:107], v[140:143], v[188:191], v[104:107]
	v_mfma_f32_16x16x32_bf16 v[96:99], v[128:131], v[200:203], v[96:99]
	v_mfma_f32_16x16x32_bf16 v[96:99], v[132:135], v[204:207], v[96:99]
	v_mfma_f32_16x16x32_bf16 v[88:91], v[136:139], v[200:203], v[88:91]
	v_mfma_f32_16x16x32_bf16 v[88:91], v[140:143], v[204:207], v[88:91]
	v_mfma_f32_16x16x32_bf16 v[80:83], v[128:131], v[208:211], v[80:83]
	v_mfma_f32_16x16x32_bf16 v[80:83], v[132:135], v[212:215], v[80:83]
	v_mfma_f32_16x16x32_bf16 v[72:75], v[136:139], v[208:211], v[72:75]
	v_mfma_f32_16x16x32_bf16 v[72:75], v[140:143], v[212:215], v[72:75]
	v_mfma_f32_16x16x32_bf16 v[116:119], v[144:147], v[160:163], v[116:119]
	v_mfma_f32_16x16x32_bf16 v[116:119], v[148:151], v[180:183], v[116:119]
	v_mfma_f32_16x16x32_bf16 v[112:115], v[152:155], v[160:163], v[112:115]
	v_mfma_f32_16x16x32_bf16 v[112:115], v[156:159], v[180:183], v[112:115]
	v_mfma_f32_16x16x32_bf16 v[100:103], v[144:147], v[184:187], v[100:103]
	v_mfma_f32_16x16x32_bf16 v[100:103], v[148:151], v[188:191], v[100:103]
	v_mfma_f32_16x16x32_bf16 v[92:95], v[152:155], v[184:187], v[92:95]
	v_mfma_f32_16x16x32_bf16 v[92:95], v[156:159], v[188:191], v[92:95]
	v_mfma_f32_16x16x32_bf16 v[84:87], v[144:147], v[200:203], v[84:87]
	v_mfma_f32_16x16x32_bf16 v[84:87], v[148:151], v[204:207], v[84:87]
	v_mfma_f32_16x16x32_bf16 v[76:79], v[152:155], v[200:203], v[76:79]
	v_mfma_f32_16x16x32_bf16 v[76:79], v[156:159], v[204:207], v[76:79]
	v_mfma_f32_16x16x32_bf16 v[68:71], v[144:147], v[208:211], v[68:71]
	v_mfma_f32_16x16x32_bf16 v[68:71], v[148:151], v[212:215], v[68:71]
	s_setprio 3
	s_barrier
	v_mfma_f32_16x16x32_bf16 v[64:67], v[152:155], v[208:211], v[64:67]
	v_mfma_f32_16x16x32_bf16 v[64:67], v[156:159], v[212:215], v[64:67]
	s_setprio 0
.Lzj_11_0:
	s_add_i32 s46, s37, s24
	v_lshl_add_u64 v[192:193], s[18:19], 0, v[166:167]
	s_mov_b32 m0, s46
	ds_read_b128 v[160:163], v199 offset:16384
	ds_read_b128 v[180:183], v199 offset:17408
	ds_read_b128 v[184:187], v199 offset:18432
	ds_read_b128 v[188:191], v199 offset:19456
	ds_read_b128 v[200:203], v199 offset:20480
	ds_read_b128 v[204:207], v199 offset:21504
	ds_read_b128 v[208:211], v199 offset:22528
	ds_read_b128 v[212:215], v199 offset:23552
	global_load_lds_dwordx4 v[192:193], off
	s_add_i32 m0, s46, 0x2000
	s_add_u32 s46, s18, 0xb0000
	v_lshl_add_u64 v[216:217], s[18:19], 0, v[170:171]
	s_addc_u32 s47, s19, 0
	s_add_i32 s48, s38, s24
	global_load_lds_dwordx4 v[216:217], off
	v_lshl_add_u64 v[218:219], s[46:47], 0, v[166:167]
	s_mov_b32 m0, s48
	global_load_lds_dwordx4 v[218:219], off
	s_add_i32 m0, s48, 0x2000
	v_lshl_add_u64 v[218:219], s[46:47], 0, v[170:171]
	global_load_lds_dwordx4 v[218:219], off
	s_mov_b32 m0, s25
	v_lshl_add_u64 v[218:219], s[20:21], 0, v[164:165]
	global_load_lds_dwordx4 v[218:219], off
	s_mov_b32 m0, s26
	v_lshl_add_u64 v[220:221], s[20:21], 0, v[168:169]
	global_load_lds_dwordx4 v[220:221], off
	s_cmp_eq_u32 s45, -2
	s_waitcnt vmcnt(8) lgkmcnt(0)
	s_barrier
	s_cbranch_scc1 .Lzv_11_1
	v_mfma_f32_16x16x32_bf16 v[60:63], v[128:131], v[160:163], v[60:63]
	v_mfma_f32_16x16x32_bf16 v[60:63], v[132:135], v[180:183], v[60:63]
	v_mfma_f32_16x16x32_bf16 v[56:59], v[136:139], v[160:163], v[56:59]
	v_mfma_f32_16x16x32_bf16 v[56:59], v[140:143], v[180:183], v[56:59]
	v_mfma_f32_16x16x32_bf16 v[48:51], v[128:131], v[184:187], v[48:51]
	v_mfma_f32_16x16x32_bf16 v[48:51], v[132:135], v[188:191], v[48:51]
	v_mfma_f32_16x16x32_bf16 v[40:43], v[136:139], v[184:187], v[40:43]
	v_mfma_f32_16x16x32_bf16 v[40:43], v[140:143], v[188:191], v[40:43]
	v_mfma_f32_16x16x32_bf16 v[32:35], v[128:131], v[200:203], v[32:35]
	v_mfma_f32_16x16x32_bf16 v[32:35], v[132:135], v[204:207], v[32:35]
	v_mfma_f32_16x16x32_bf16 v[24:27], v[136:139], v[200:203], v[24:27]
	v_mfma_f32_16x16x32_bf16 v[24:27], v[140:143], v[204:207], v[24:27]
	v_mfma_f32_16x16x32_bf16 v[16:19], v[128:131], v[208:211], v[16:19]
	v_mfma_f32_16x16x32_bf16 v[16:19], v[132:135], v[212:215], v[16:19]
	v_mfma_f32_16x16x32_bf16 v[8:11], v[136:139], v[208:211], v[8:11]
	v_mfma_f32_16x16x32_bf16 v[8:11], v[140:143], v[212:215], v[8:11]
	v_mfma_f32_16x16x32_bf16 v[52:55], v[144:147], v[160:163], v[52:55]
	v_mfma_f32_16x16x32_bf16 v[52:55], v[148:151], v[180:183], v[52:55]
	v_mfma_f32_16x16x32_bf16 v[44:47], v[152:155], v[160:163], v[44:47]
	v_mfma_f32_16x16x32_bf16 v[44:47], v[156:159], v[180:183], v[44:47]
	v_mfma_f32_16x16x32_bf16 v[36:39], v[144:147], v[184:187], v[36:39]
	v_mfma_f32_16x16x32_bf16 v[36:39], v[148:151], v[188:191], v[36:39]
	v_mfma_f32_16x16x32_bf16 v[28:31], v[152:155], v[184:187], v[28:31]
	v_mfma_f32_16x16x32_bf16 v[28:31], v[156:159], v[188:191], v[28:31]
	v_mfma_f32_16x16x32_bf16 v[20:23], v[144:147], v[200:203], v[20:23]
	v_mfma_f32_16x16x32_bf16 v[20:23], v[148:151], v[204:207], v[20:23]
	v_mfma_f32_16x16x32_bf16 v[12:15], v[152:155], v[200:203], v[12:15]
	v_mfma_f32_16x16x32_bf16 v[12:15], v[156:159], v[204:207], v[12:15]
	v_mfma_f32_16x16x32_bf16 v[4:7], v[144:147], v[208:211], v[4:7]
	v_mfma_f32_16x16x32_bf16 v[4:7], v[148:151], v[212:215], v[4:7]
	s_setprio 3
	s_barrier
	v_mfma_f32_16x16x32_bf16 v[0:3], v[152:155], v[208:211], v[0:3]
	v_mfma_f32_16x16x32_bf16 v[0:3], v[156:159], v[212:215], v[0:3]
	s_setprio 0
.Lzj_11_1:
	s_add_i32 s46, 0, 0x18000
	s_add_i32 s47, 0, 0x1c000
	v_add_u32_e32 v140, s46, v195
	v_add_u32_e32 v156, s47, v195
	ds_read_b128 v[128:131], v140
	ds_read_b128 v[132:135], v140 offset:1024
	ds_read_b128 v[136:139], v140 offset:2048
	ds_read_b128 v[140:143], v140 offset:3072
	ds_read_b128 v[144:147], v156
	ds_read_b128 v[148:151], v156 offset:1024
	ds_read_b128 v[152:155], v156 offset:2048
	ds_read_b128 v[156:159], v156 offset:3072
	s_add_u32 s20, s20, 0xb0000
	s_addc_u32 s21, s21, 0
	s_mov_b32 m0, s27
	v_lshl_add_u64 v[222:223], s[20:21], 0, v[164:165]
	ds_read_b128 v[160:163], v199 offset:32768
	ds_read_b128 v[180:183], v199 offset:33792
	ds_read_b128 v[184:187], v199 offset:34816
	ds_read_b128 v[188:191], v199 offset:35840
	ds_read_b128 v[200:203], v199 offset:36864
	ds_read_b128 v[204:207], v199 offset:37888
	ds_read_b128 v[208:211], v199 offset:38912
	ds_read_b128 v[212:215], v199 offset:39936
	global_load_lds_dwordx4 v[222:223], off
	s_mov_b32 m0, s28
	v_lshl_add_u64 v[222:223], s[20:21], 0, v[168:169]
	global_load_lds_dwordx4 v[222:223], off
	s_waitcnt vmcnt(8) lgkmcnt(0)
	s_barrier
	v_mfma_f32_16x16x32_bf16 v[124:127], v[128:131], v[160:163], v[124:127]
	v_mfma_f32_16x16x32_bf16 v[124:127], v[132:135], v[180:183], v[124:127]
	v_mfma_f32_16x16x32_bf16 v[120:123], v[136:139], v[160:163], v[120:123]
	v_mfma_f32_16x16x32_bf16 v[120:123], v[140:143], v[180:183], v[120:123]
	v_mfma_f32_16x16x32_bf16 v[108:111], v[128:131], v[184:187], v[108:111]
	v_mfma_f32_16x16x32_bf16 v[108:111], v[132:135], v[188:191], v[108:111]
	v_mfma_f32_16x16x32_bf16 v[104:107], v[136:139], v[184:187], v[104:107]
	v_mfma_f32_16x16x32_bf16 v[104:107], v[140:143], v[188:191], v[104:107]
	v_mfma_f32_16x16x32_bf16 v[96:99], v[128:131], v[200:203], v[96:99]
	v_mfma_f32_16x16x32_bf16 v[96:99], v[132:135], v[204:207], v[96:99]
	v_mfma_f32_16x16x32_bf16 v[88:91], v[136:139], v[200:203], v[88:91]
	v_mfma_f32_16x16x32_bf16 v[88:91], v[140:143], v[204:207], v[88:91]
	v_mfma_f32_16x16x32_bf16 v[80:83], v[128:131], v[208:211], v[80:83]
	v_mfma_f32_16x16x32_bf16 v[80:83], v[132:135], v[212:215], v[80:83]
	v_mfma_f32_16x16x32_bf16 v[72:75], v[136:139], v[208:211], v[72:75]
	v_mfma_f32_16x16x32_bf16 v[72:75], v[140:143], v[212:215], v[72:75]
	v_mfma_f32_16x16x32_bf16 v[116:119], v[144:147], v[160:163], v[116:119]
	v_mfma_f32_16x16x32_bf16 v[116:119], v[148:151], v[180:183], v[116:119]
	v_mfma_f32_16x16x32_bf16 v[112:115], v[152:155], v[160:163], v[112:115]
	v_mfma_f32_16x16x32_bf16 v[112:115], v[156:159], v[180:183], v[112:115]
	v_mfma_f32_16x16x32_bf16 v[100:103], v[144:147], v[184:187], v[100:103]
	v_mfma_f32_16x16x32_bf16 v[100:103], v[148:151], v[188:191], v[100:103]
	v_mfma_f32_16x16x32_bf16 v[92:95], v[152:155], v[184:187], v[92:95]
	v_mfma_f32_16x16x32_bf16 v[92:95], v[156:159], v[188:191], v[92:95]
	v_mfma_f32_16x16x32_bf16 v[84:87], v[144:147], v[200:203], v[84:87]
	v_mfma_f32_16x16x32_bf16 v[84:87], v[148:151], v[204:207], v[84:87]
	v_mfma_f32_16x16x32_bf16 v[76:79], v[152:155], v[200:203], v[76:79]
	v_mfma_f32_16x16x32_bf16 v[76:79], v[156:159], v[204:207], v[76:79]
	v_mfma_f32_16x16x32_bf16 v[68:71], v[144:147], v[208:211], v[68:71]
	v_mfma_f32_16x16x32_bf16 v[68:71], v[148:151], v[212:215], v[68:71]
	s_setprio 3
	s_barrier
	v_mfma_f32_16x16x32_bf16 v[64:67], v[152:155], v[208:211], v[64:67]
	v_mfma_f32_16x16x32_bf16 v[64:67], v[156:159], v[212:215], v[64:67]
	s_setprio 0
	s_add_i32 s20, s46, s24
	v_lshl_add_u64 v[192:193], v[192:193], 0, s[8:9]
	s_mov_b32 m0, s20
	ds_read_b128 v[160:163], v199 offset:49152
	ds_read_b128 v[180:183], v199 offset:50176
	ds_read_b128 v[184:187], v199 offset:51200
	ds_read_b128 v[188:191], v199 offset:52224
	ds_read_b128 v[200:203], v199 offset:53248
	ds_read_b128 v[204:207], v199 offset:54272
	ds_read_b128 v[208:211], v199 offset:55296
	ds_read_b128 v[212:215], v199 offset:56320
	global_load_lds_dwordx4 v[192:193], off
	s_add_i32 m0, s20, 0x2000
	s_add_u32 s18, s18, 0xb0080
	v_lshl_add_u64 v[192:193], v[216:217], 0, s[8:9]
	s_addc_u32 s19, s19, 0
	s_add_i32 s20, s47, s24
	global_load_lds_dwordx4 v[192:193], off
	s_mov_b32 m0, s20
	v_lshl_add_u64 v[192:193], s[18:19], 0, v[166:167]
	global_load_lds_dwordx4 v[192:193], off
	s_add_i32 m0, s20, 0x2000
	v_lshl_add_u64 v[192:193], s[18:19], 0, v[170:171]
	global_load_lds_dwordx4 v[192:193], off
	s_mov_b32 m0, s33
	v_lshl_add_u64 v[192:193], v[218:219], 0, s[8:9]
	global_load_lds_dwordx4 v[192:193], off
	s_mov_b32 m0, s35
	v_lshl_add_u64 v[192:193], v[220:221], 0, s[8:9]
	global_load_lds_dwordx4 v[192:193], off
	s_waitcnt vmcnt(8) lgkmcnt(0)
	s_barrier
	v_mfma_f32_16x16x32_bf16 v[60:63], v[128:131], v[160:163], v[60:63]
	v_mfma_f32_16x16x32_bf16 v[60:63], v[132:135], v[180:183], v[60:63]
	v_mfma_f32_16x16x32_bf16 v[56:59], v[136:139], v[160:163], v[56:59]
	v_mfma_f32_16x16x32_bf16 v[56:59], v[140:143], v[180:183], v[56:59]
	v_mfma_f32_16x16x32_bf16 v[48:51], v[128:131], v[184:187], v[48:51]
	v_mfma_f32_16x16x32_bf16 v[48:51], v[132:135], v[188:191], v[48:51]
	v_mfma_f32_16x16x32_bf16 v[40:43], v[136:139], v[184:187], v[40:43]
	v_mfma_f32_16x16x32_bf16 v[40:43], v[140:143], v[188:191], v[40:43]
	v_mfma_f32_16x16x32_bf16 v[32:35], v[128:131], v[200:203], v[32:35]
	v_mfma_f32_16x16x32_bf16 v[32:35], v[132:135], v[204:207], v[32:35]
	v_mfma_f32_16x16x32_bf16 v[24:27], v[136:139], v[200:203], v[24:27]
	v_mfma_f32_16x16x32_bf16 v[24:27], v[140:143], v[204:207], v[24:27]
	v_mfma_f32_16x16x32_bf16 v[16:19], v[128:131], v[208:211], v[16:19]
	v_mfma_f32_16x16x32_bf16 v[16:19], v[132:135], v[212:215], v[16:19]
	v_mfma_f32_16x16x32_bf16 v[8:11], v[136:139], v[208:211], v[8:11]
	v_mfma_f32_16x16x32_bf16 v[8:11], v[140:143], v[212:215], v[8:11]
	v_mfma_f32_16x16x32_bf16 v[52:55], v[144:147], v[160:163], v[52:55]
	v_mfma_f32_16x16x32_bf16 v[52:55], v[148:151], v[180:183], v[52:55]
	v_mfma_f32_16x16x32_bf16 v[44:47], v[152:155], v[160:163], v[44:47]
	v_mfma_f32_16x16x32_bf16 v[44:47], v[156:159], v[180:183], v[44:47]
	v_mfma_f32_16x16x32_bf16 v[36:39], v[144:147], v[184:187], v[36:39]
	v_mfma_f32_16x16x32_bf16 v[36:39], v[148:151], v[188:191], v[36:39]
	v_mfma_f32_16x16x32_bf16 v[28:31], v[152:155], v[184:187], v[28:31]
	v_mfma_f32_16x16x32_bf16 v[28:31], v[156:159], v[188:191], v[28:31]
	v_mfma_f32_16x16x32_bf16 v[20:23], v[144:147], v[200:203], v[20:23]
	v_mfma_f32_16x16x32_bf16 v[20:23], v[148:151], v[204:207], v[20:23]
	v_mfma_f32_16x16x32_bf16 v[12:15], v[152:155], v[200:203], v[12:15]
	v_mfma_f32_16x16x32_bf16 v[12:15], v[156:159], v[204:207], v[12:15]
	v_mfma_f32_16x16x32_bf16 v[4:7], v[144:147], v[208:211], v[4:7]
	v_mfma_f32_16x16x32_bf16 v[4:7], v[148:151], v[212:215], v[4:7]
	s_setprio 3
	s_barrier
	v_mfma_f32_16x16x32_bf16 v[0:3], v[152:155], v[208:211], v[0:3]
	v_mfma_f32_16x16x32_bf16 v[0:3], v[156:159], v[212:215], v[0:3]
	s_setprio 0
	s_add_i32 s45, s45, 2
	s_add_u32 s16, s16, 0x100
	s_addc_u32 s17, s17, 0
	s_add_u32 s43, s43, 0x100
	s_addc_u32 s44, s44, 0
	s_cmp_gt_u32 s45, 41
	s_cbranch_scc0 .LBB0_2341
	s_branch .Lzskip_11
